# redundant s_waitcnt lgkmcnt(0) at the head of each K-loop MFMA segment removed (the same wait already precedes the barrier)
# speedup vs baseline: 1.0048x; 1.0019x over previous
; #define PG8_STAGE(bufoff, gbase, voff) do { _Pragma("unroll") for (int _i = 0; _i < 2; ++_i) \
;         __builtin_amdgcn_global_load_lds((const unsigned*)((const char*)(gbase) + (voff)[_i]), (LAS unsigned*)(lds + (bufoff) + ldsw + _i * 8192), 16, 0, 0); } while (0)
; #define PG8_LDA(dst, b, h) do { _Pragma("unroll") for (int m = 0; m < 4; ++m) _Pragma("unroll") for (int k = 0; k < 2; ++k) dst[m][k] = *(const LAS bf16x8*)(lds + PG8_SA(b, h) + aoff + m * 2048 + k * 1024); } while (0)
; #define PG8_LDB(dst, b, h) do { _Pragma("unroll") for (int n = 0; n < 2; ++n) _Pragma("unroll") for (int k = 0; k < 2; ++k) dst[n][k] = *(const LAS bf16x8*)(lds + PG8_SB(b, h) + boff + n * 2048 + k * 1024); } while (0)
; #define PG8_MMA(ai, bj, At, Bt) do { __builtin_amdgcn_s_setprio(1); _Pragma("unroll") for (int m = 0; m < 4; ++m) _Pragma("unroll") for (int n = 0; n < 2; ++n) _Pragma("unroll") for (int k = 0; k < 2; ++k) \
;         acc[ai][bj][m][n] = __builtin_amdgcn_mfma_f32_16x16x32_bf16(Bt[n][k], At[m][k], acc[ai][bj][m][n], 0, 0, 0); __builtin_amdgcn_s_setprio(0); } while (0)
; #define PG8_WAIT_V(n) asm volatile("s_waitcnt vmcnt(" #n ")" ::: "memory")
; #define PG8_WAIT_L(n) asm volatile("s_waitcnt lgkmcnt(" #n ")" ::: "memory")
; #define PG8_BAR __builtin_amdgcn_s_barrier()
; #define PG8_SCHED __builtin_amdgcn_sched_barrier(0)
; template <class Epi, bool ALIGN_EPI = PG8_ALIGN, bool SP2 = PG8_SP2>
; __device__ __forceinline__ void gemm_phase(LAS unsigned char* lds, const Gemm g, const StaticOrder& S, const Epi& E) {
;     ...
;             const bool last = (t == nt - 2);
;             const char* a1 = cA + (size_t)(t + 1) * kstepA;
;             const char* a2 = last ? nA : cA + (size_t)(t + 2) * kstepA; const char* b2 = last ? nB : cB + (size_t)(t + 2) * kstepB;
;             const char* a3 = a2 + kstepA; const char* b3 = b2 + kstepB;
;             if constexpr (SP2) {
;             PG8_LDB(B0, 0, 0); PG8_LDB(B1, 0, 1); PG8_SCHED; PG8_LDA(At, 0, 0); PG8_STAGE(PG8_SA(1, 1), a1 + hstepA, voffA);
;             PG8_WAIT_V(8); PG8_WAIT_L(0); PG8_BAR; PG8_MMA(0, 0, At, B0); PG8_MMA(0, 1, At, B1); PG8_BAR; PG8_SCHED;
;             PG8_LDA(At, 0, 1); PG8_STAGE(PG8_SB(0, 0), b2, voffB); PG8_STAGE(PG8_SB(0, 1), b2 + hstepB, voffB); PG8_STAGE(PG8_SA(0, 0), a2, voffA);
;             PG8_WAIT_V(8); PG8_WAIT_L(0); PG8_BAR; PG8_MMA(1, 0, At, B0); PG8_MMA(1, 1, At, B1); PG8_BAR; PG8_SCHED;
.LBB0_139:
	s_cmp_eq_u32 s40, -2
	s_cbranch_scc1 .Lfirst_iter_u139
	s_add_u32 s22, s4, 0xfffc0080
	s_addc_u32 s23, s5, -1
	s_add_i32 s41, 0, 0x10000
	s_cmp_eq_u32 s40, 12
	s_cselect_b32 s25, s17, s23
	s_cselect_b32 s24, s36, s22
	v_add_u32_e32 v0, s41, v143
	s_cselect_b32 s23, s15, s39
	s_cselect_b32 s22, s37, s38
	s_add_i32 s44, 0, 0x14000
	ds_read_b128 v[138:141], v0
	ds_read_b128 v[146:149], v0 offset:1024
	ds_read_b128 v[150:153], v0 offset:2048
	ds_read_b128 v[154:157], v0 offset:3072
	v_add_u32_e32 v0, s44, v143
	ds_read_b128 v[158:161], v0
	ds_read_b128 v[164:167], v0 offset:1024
	ds_read_b128 v[170:173], v0 offset:2048
	ds_read_b128 v[174:177], v0 offset:3072
	v_lshl_add_u64 v[190:191], s[4:5], 0, v[134:135]
	s_add_i32 m0, s26, 0xc000
	ds_read_b128 v[178:181], v145
	ds_read_b128 v[182:185], v145 offset:1024
	ds_read_b128 v[186:189], v145 offset:2048
	ds_read_b128 v[194:197], v145 offset:3072
	ds_read_b128 v[206:209], v145 offset:4096
	ds_read_b128 v[210:213], v145 offset:5120
	ds_read_b128 v[214:217], v145 offset:6144
	ds_read_b128 v[218:221], v145 offset:7168
	global_load_lds_dwordx4 v[190:191], off
	v_lshl_add_u64 v[190:191], s[4:5], 0, v[136:137]
	s_add_i32 m0, s26, 0xe000
	s_nop 0
	global_load_lds_dwordx4 v[190:191], off
	s_waitcnt vmcnt(8)
	s_waitcnt lgkmcnt(0)
	s_barrier
	s_setprio 1
	v_mfma_f32_16x16x32_bf16 v[126:129], v[138:141], v[178:181], v[126:129]
	v_mfma_f32_16x16x32_bf16 v[122:125], v[150:153], v[178:181], v[122:125]
	v_mfma_f32_16x16x32_bf16 v[110:113], v[138:141], v[186:189], v[110:113]
	v_mfma_f32_16x16x32_bf16 v[106:109], v[150:153], v[186:189], v[106:109]
	v_mfma_f32_16x16x32_bf16 v[94:97], v[138:141], v[206:209], v[94:97]
	v_mfma_f32_16x16x32_bf16 v[90:93], v[150:153], v[206:209], v[90:93]
	v_mfma_f32_16x16x32_bf16 v[78:81], v[138:141], v[214:217], v[78:81]
	v_mfma_f32_16x16x32_bf16 v[74:77], v[150:153], v[214:217], v[74:77]
	v_mfma_f32_16x16x32_bf16 v[126:129], v[146:149], v[182:185], v[126:129]
	v_mfma_f32_16x16x32_bf16 v[122:125], v[154:157], v[182:185], v[122:125]
	v_mfma_f32_16x16x32_bf16 v[110:113], v[146:149], v[194:197], v[110:113]
	v_mfma_f32_16x16x32_bf16 v[106:109], v[154:157], v[194:197], v[106:109]
	v_mfma_f32_16x16x32_bf16 v[94:97], v[146:149], v[210:213], v[94:97]
	v_mfma_f32_16x16x32_bf16 v[90:93], v[154:157], v[210:213], v[90:93]
	v_mfma_f32_16x16x32_bf16 v[78:81], v[146:149], v[218:221], v[78:81]
	v_mfma_f32_16x16x32_bf16 v[74:77], v[154:157], v[218:221], v[74:77]
	s_setprio 0
	s_setprio 1
	v_mfma_f32_16x16x32_bf16 v[118:121], v[158:161], v[178:181], v[118:121]
	v_mfma_f32_16x16x32_bf16 v[114:117], v[170:173], v[178:181], v[114:117]
	v_mfma_f32_16x16x32_bf16 v[102:105], v[158:161], v[186:189], v[102:105]
	v_mfma_f32_16x16x32_bf16 v[98:101], v[170:173], v[186:189], v[98:101]
	v_mfma_f32_16x16x32_bf16 v[86:89], v[158:161], v[206:209], v[86:89]
	v_mfma_f32_16x16x32_bf16 v[82:85], v[170:173], v[206:209], v[82:85]
	v_mfma_f32_16x16x32_bf16 v[70:73], v[158:161], v[214:217], v[70:73]
	v_mfma_f32_16x16x32_bf16 v[66:69], v[170:173], v[214:217], v[66:69]
	v_mfma_f32_16x16x32_bf16 v[118:121], v[164:167], v[182:185], v[118:121]
	v_mfma_f32_16x16x32_bf16 v[114:117], v[174:177], v[182:185], v[114:117]
	v_mfma_f32_16x16x32_bf16 v[102:105], v[164:167], v[194:197], v[102:105]
	v_mfma_f32_16x16x32_bf16 v[98:101], v[174:177], v[194:197], v[98:101]
	v_mfma_f32_16x16x32_bf16 v[86:89], v[164:167], v[210:213], v[86:89]
	v_mfma_f32_16x16x32_bf16 v[82:85], v[174:177], v[210:213], v[82:85]
	v_mfma_f32_16x16x32_bf16 v[70:73], v[164:167], v[218:221], v[70:73]
	v_mfma_f32_16x16x32_bf16 v[66:69], v[174:177], v[218:221], v[66:69]
	s_setprio 0
	s_barrier
	s_add_i32 s41, s41, s3
	v_lshl_add_u64 v[190:191], s[22:23], 0, v[132:133]
	s_mov_b32 m0, s41
	ds_read_b128 v[178:181], v145 offset:16384
	ds_read_b128 v[182:185], v145 offset:17408
	ds_read_b128 v[186:189], v145 offset:18432
	ds_read_b128 v[194:197], v145 offset:19456
	ds_read_b128 v[206:209], v145 offset:20480
	ds_read_b128 v[210:213], v145 offset:21504
	ds_read_b128 v[214:217], v145 offset:22528
	ds_read_b128 v[218:221], v145 offset:23552
	global_load_lds_dwordx4 v[190:191], off
	s_add_i32 m0, s41, 0x2000
	s_add_u32 s42, s22, 0x40000
	v_lshl_add_u64 v[202:203], s[22:23], 0, v[130:131]
	s_addc_u32 s43, s23, 0
	s_add_i32 s41, s44, s3
	global_load_lds_dwordx4 v[202:203], off
	v_lshl_add_u64 v[204:205], s[42:43], 0, v[132:133]
	s_mov_b32 m0, s41
	v_lshl_add_u64 v[222:223], s[24:25], 0, v[130:131]
	global_load_lds_dwordx4 v[204:205], off
	v_lshl_add_u64 v[204:205], s[42:43], 0, v[130:131]
	s_add_i32 m0, s41, 0x2000
	s_nop 0
	global_load_lds_dwordx4 v[204:205], off
	v_lshl_add_u64 v[204:205], s[24:25], 0, v[132:133]
	s_mov_b32 m0, s26
	s_nop 0
	global_load_lds_dwordx4 v[204:205], off
	s_mov_b32 m0, s27
	s_nop 0
	global_load_lds_dwordx4 v[222:223], off
	s_waitcnt vmcnt(8)
	s_waitcnt lgkmcnt(0)
	s_barrier
; #define PG8_STAGE(bufoff, gbase, voff) do { _Pragma("unroll") for (int _i = 0; _i < 2; ++_i) \
;         __builtin_amdgcn_global_load_lds((const unsigned*)((const char*)(gbase) + (voff)[_i]), (LAS unsigned*)(lds + (bufoff) + ldsw + _i * 8192), 16, 0, 0); } while (0)
; #define PG8_LDA(dst, b, h) do { _Pragma("unroll") for (int m = 0; m < 4; ++m) _Pragma("unroll") for (int k = 0; k < 2; ++k) dst[m][k] = *(const LAS bf16x8*)(lds + PG8_SA(b, h) + aoff + m * 2048 + k * 1024); } while (0)
; #define PG8_LDB(dst, b, h) do { _Pragma("unroll") for (int n = 0; n < 2; ++n) _Pragma("unroll") for (int k = 0; k < 2; ++k) dst[n][k] = *(const LAS bf16x8*)(lds + PG8_SB(b, h) + boff + n * 2048 + k * 1024); } while (0)
; #define PG8_MMA(ai, bj, At, Bt) do { __builtin_amdgcn_s_setprio(1); _Pragma("unroll") for (int m = 0; m < 4; ++m) _Pragma("unroll") for (int n = 0; n < 2; ++n) _Pragma("unroll") for (int k = 0; k < 2; ++k) \
;         acc[ai][bj][m][n] = __builtin_amdgcn_mfma_f32_16x16x32_bf16(Bt[n][k], At[m][k], acc[ai][bj][m][n], 0, 0, 0); __builtin_amdgcn_s_setprio(0); } while (0)
; #define PG8_WAIT_V(n) asm volatile("s_waitcnt vmcnt(" #n ")" ::: "memory")
; #define PG8_WAIT_L(n) asm volatile("s_waitcnt lgkmcnt(" #n ")" ::: "memory")
; #define PG8_BAR __builtin_amdgcn_s_barrier()
; #define PG8_SCHED __builtin_amdgcn_sched_barrier(0)
; template <class Epi, bool ALIGN_EPI = PG8_ALIGN, bool SP2 = PG8_SP2>
; __device__ __forceinline__ void gemm_phase(LAS unsigned char* lds, const Gemm g, const StaticOrder& S, const Epi& E) {
;     ...
;             PG8_WAIT_V(8); PG8_WAIT_L(0); PG8_BAR; PG8_MMA(1, 0, At, B0); PG8_MMA(1, 1, At, B1); PG8_BAR; PG8_SCHED;
;             PG8_LDB(B0, 1, 0); PG8_LDB(B1, 1, 1); PG8_SCHED; PG8_LDA(At, 1, 0); PG8_STAGE(PG8_SA(0, 1), a2 + hstepA, voffA);
;             PG8_WAIT_V(8); PG8_WAIT_L(0); PG8_BAR; PG8_MMA(0, 0, At, B0); PG8_MMA(0, 1, At, B1); PG8_BAR; PG8_SCHED;
	s_setprio 1
	v_mfma_f32_16x16x32_bf16 v[62:65], v[138:141], v[178:181], v[62:65]
	v_mfma_f32_16x16x32_bf16 v[58:61], v[150:153], v[178:181], v[58:61]
	v_mfma_f32_16x16x32_bf16 v[46:49], v[138:141], v[186:189], v[46:49]
	v_mfma_f32_16x16x32_bf16 v[42:45], v[150:153], v[186:189], v[42:45]
	v_mfma_f32_16x16x32_bf16 v[30:33], v[138:141], v[206:209], v[30:33]
	v_mfma_f32_16x16x32_bf16 v[26:29], v[150:153], v[206:209], v[26:29]
	v_mfma_f32_16x16x32_bf16 v[14:17], v[138:141], v[214:217], v[14:17]
	v_mfma_f32_16x16x32_bf16 v[10:13], v[150:153], v[214:217], v[10:13]
	v_mfma_f32_16x16x32_bf16 v[62:65], v[146:149], v[182:185], v[62:65]
	v_mfma_f32_16x16x32_bf16 v[58:61], v[154:157], v[182:185], v[58:61]
	v_mfma_f32_16x16x32_bf16 v[46:49], v[146:149], v[194:197], v[46:49]
	v_mfma_f32_16x16x32_bf16 v[42:45], v[154:157], v[194:197], v[42:45]
	v_mfma_f32_16x16x32_bf16 v[30:33], v[146:149], v[210:213], v[30:33]
	v_mfma_f32_16x16x32_bf16 v[26:29], v[154:157], v[210:213], v[26:29]
	v_mfma_f32_16x16x32_bf16 v[14:17], v[146:149], v[218:221], v[14:17]
	v_mfma_f32_16x16x32_bf16 v[10:13], v[154:157], v[218:221], v[10:13]
	s_setprio 0
	s_setprio 1
	v_mfma_f32_16x16x32_bf16 v[54:57], v[158:161], v[178:181], v[54:57]
	v_mfma_f32_16x16x32_bf16 v[50:53], v[170:173], v[178:181], v[50:53]
	v_mfma_f32_16x16x32_bf16 v[38:41], v[158:161], v[186:189], v[38:41]
	v_mfma_f32_16x16x32_bf16 v[34:37], v[170:173], v[186:189], v[34:37]
	v_mfma_f32_16x16x32_bf16 v[22:25], v[158:161], v[206:209], v[22:25]
	v_mfma_f32_16x16x32_bf16 v[18:21], v[170:173], v[206:209], v[18:21]
	v_mfma_f32_16x16x32_bf16 v[6:9], v[158:161], v[214:217], v[6:9]
	v_mfma_f32_16x16x32_bf16 v[2:5], v[170:173], v[214:217], v[2:5]
	v_mfma_f32_16x16x32_bf16 v[54:57], v[164:167], v[182:185], v[54:57]
	v_mfma_f32_16x16x32_bf16 v[50:53], v[174:177], v[182:185], v[50:53]
	v_mfma_f32_16x16x32_bf16 v[38:41], v[164:167], v[194:197], v[38:41]
	v_mfma_f32_16x16x32_bf16 v[34:37], v[174:177], v[194:197], v[34:37]
	v_mfma_f32_16x16x32_bf16 v[22:25], v[164:167], v[210:213], v[22:25]
	v_mfma_f32_16x16x32_bf16 v[18:21], v[174:177], v[210:213], v[18:21]
	v_mfma_f32_16x16x32_bf16 v[6:9], v[164:167], v[218:221], v[6:9]
	v_mfma_f32_16x16x32_bf16 v[2:5], v[174:177], v[218:221], v[2:5]
	s_setprio 0
	s_barrier
	s_add_i32 s41, 0, 0x18000
	v_add_u32_e32 v0, s41, v143
	s_add_i32 s42, 0, 0x1c000
	ds_read_b128 v[138:141], v0
	ds_read_b128 v[146:149], v0 offset:1024
	ds_read_b128 v[150:153], v0 offset:2048
	ds_read_b128 v[154:157], v0 offset:3072
	v_add_u32_e32 v0, s42, v143
	ds_read_b128 v[158:161], v0
	ds_read_b128 v[164:167], v0 offset:1024
	ds_read_b128 v[170:173], v0 offset:2048
	ds_read_b128 v[174:177], v0 offset:3072
	s_add_u32 s24, s24, 0x40000
	s_addc_u32 s25, s25, 0
	s_mov_b32 m0, s28
	v_lshl_add_u64 v[224:225], s[24:25], 0, v[132:133]
	ds_read_b128 v[178:181], v145 offset:32768
	ds_read_b128 v[182:185], v145 offset:33792
	ds_read_b128 v[186:189], v145 offset:34816
	ds_read_b128 v[194:197], v145 offset:35840
	ds_read_b128 v[206:209], v145 offset:36864
	ds_read_b128 v[210:213], v145 offset:37888
	ds_read_b128 v[214:217], v145 offset:38912
	ds_read_b128 v[218:221], v145 offset:39936
	global_load_lds_dwordx4 v[224:225], off
	v_lshl_add_u64 v[224:225], s[24:25], 0, v[130:131]
	s_mov_b32 m0, s29
	s_nop 0
	global_load_lds_dwordx4 v[224:225], off
	s_waitcnt vmcnt(8)
	s_waitcnt lgkmcnt(0)
	s_barrier
	s_setprio 1
	v_mfma_f32_16x16x32_bf16 v[126:129], v[138:141], v[178:181], v[126:129]
	v_mfma_f32_16x16x32_bf16 v[122:125], v[150:153], v[178:181], v[122:125]
	v_mfma_f32_16x16x32_bf16 v[110:113], v[138:141], v[186:189], v[110:113]
	v_mfma_f32_16x16x32_bf16 v[106:109], v[150:153], v[186:189], v[106:109]
	v_mfma_f32_16x16x32_bf16 v[94:97], v[138:141], v[206:209], v[94:97]
	v_mfma_f32_16x16x32_bf16 v[90:93], v[150:153], v[206:209], v[90:93]
	v_mfma_f32_16x16x32_bf16 v[78:81], v[138:141], v[214:217], v[78:81]
	v_mfma_f32_16x16x32_bf16 v[74:77], v[150:153], v[214:217], v[74:77]
	v_mfma_f32_16x16x32_bf16 v[126:129], v[146:149], v[182:185], v[126:129]
	v_mfma_f32_16x16x32_bf16 v[122:125], v[154:157], v[182:185], v[122:125]
	v_mfma_f32_16x16x32_bf16 v[110:113], v[146:149], v[194:197], v[110:113]
	v_mfma_f32_16x16x32_bf16 v[106:109], v[154:157], v[194:197], v[106:109]
	v_mfma_f32_16x16x32_bf16 v[94:97], v[146:149], v[210:213], v[94:97]
	v_mfma_f32_16x16x32_bf16 v[90:93], v[154:157], v[210:213], v[90:93]
	v_mfma_f32_16x16x32_bf16 v[78:81], v[146:149], v[218:221], v[78:81]
	v_mfma_f32_16x16x32_bf16 v[74:77], v[154:157], v[218:221], v[74:77]
	s_setprio 0
	s_setprio 1
	v_mfma_f32_16x16x32_bf16 v[118:121], v[158:161], v[178:181], v[118:121]
	v_mfma_f32_16x16x32_bf16 v[114:117], v[170:173], v[178:181], v[114:117]
	v_mfma_f32_16x16x32_bf16 v[102:105], v[158:161], v[186:189], v[102:105]
	v_mfma_f32_16x16x32_bf16 v[98:101], v[170:173], v[186:189], v[98:101]
	v_mfma_f32_16x16x32_bf16 v[86:89], v[158:161], v[206:209], v[86:89]
	v_mfma_f32_16x16x32_bf16 v[82:85], v[170:173], v[206:209], v[82:85]
	v_mfma_f32_16x16x32_bf16 v[70:73], v[158:161], v[214:217], v[70:73]
	v_mfma_f32_16x16x32_bf16 v[66:69], v[170:173], v[214:217], v[66:69]
	v_mfma_f32_16x16x32_bf16 v[118:121], v[164:167], v[182:185], v[118:121]
	v_mfma_f32_16x16x32_bf16 v[114:117], v[174:177], v[182:185], v[114:117]
	v_mfma_f32_16x16x32_bf16 v[102:105], v[164:167], v[194:197], v[102:105]
	v_mfma_f32_16x16x32_bf16 v[98:101], v[174:177], v[194:197], v[98:101]
	v_mfma_f32_16x16x32_bf16 v[86:89], v[164:167], v[210:213], v[86:89]
	v_mfma_f32_16x16x32_bf16 v[82:85], v[174:177], v[210:213], v[82:85]
	v_mfma_f32_16x16x32_bf16 v[70:73], v[164:167], v[218:221], v[70:73]
	v_mfma_f32_16x16x32_bf16 v[66:69], v[174:177], v[218:221], v[66:69]
	s_setprio 0
	s_barrier
; #define PG8_STAGE(bufoff, gbase, voff) do { _Pragma("unroll") for (int _i = 0; _i < 2; ++_i) \
;         __builtin_amdgcn_global_load_lds((const unsigned*)((const char*)(gbase) + (voff)[_i]), (LAS unsigned*)(lds + (bufoff) + ldsw + _i * 8192), 16, 0, 0); } while (0)
; #define PG8_LDA(dst, b, h) do { _Pragma("unroll") for (int m = 0; m < 4; ++m) _Pragma("unroll") for (int k = 0; k < 2; ++k) dst[m][k] = *(const LAS bf16x8*)(lds + PG8_SA(b, h) + aoff + m * 2048 + k * 1024); } while (0)
; #define PG8_MMA(ai, bj, At, Bt) do { __builtin_amdgcn_s_setprio(1); _Pragma("unroll") for (int m = 0; m < 4; ++m) _Pragma("unroll") for (int n = 0; n < 2; ++n) _Pragma("unroll") for (int k = 0; k < 2; ++k) \
;         acc[ai][bj][m][n] = __builtin_amdgcn_mfma_f32_16x16x32_bf16(Bt[n][k], At[m][k], acc[ai][bj][m][n], 0, 0, 0); __builtin_amdgcn_s_setprio(0); } while (0)
; #define PG8_WAIT_V(n) asm volatile("s_waitcnt vmcnt(" #n ")" ::: "memory")
; #define PG8_WAIT_L(n) asm volatile("s_waitcnt lgkmcnt(" #n ")" ::: "memory")
; #define PG8_BAR __builtin_amdgcn_s_barrier()
; #define PG8_SCHED __builtin_amdgcn_sched_barrier(0)
; template <class Epi, bool ALIGN_EPI = PG8_ALIGN, bool SP2 = PG8_SP2>
; __device__ __forceinline__ void gemm_phase(LAS unsigned char* lds, const Gemm g, const StaticOrder& S, const Epi& E) {
;     ...
;             PG8_LDA(At, 1, 1); PG8_STAGE(PG8_SB(1, 0), b3, voffB); PG8_STAGE(PG8_SB(1, 1), b3 + hstepB, voffB); PG8_STAGE(PG8_SA(1, 0), a3, voffA);
;             PG8_WAIT_V(8); PG8_WAIT_L(0); PG8_BAR; PG8_MMA(1, 0, At, B0); PG8_MMA(1, 1, At, B1); PG8_BAR; PG8_SCHED;
	s_add_i32 s24, s41, s3
	v_lshl_add_u64 v[190:191], v[190:191], 0, s[50:51]
	s_mov_b32 m0, s24
	ds_read_b128 v[178:181], v145 offset:49152
	ds_read_b128 v[182:185], v145 offset:50176
	ds_read_b128 v[186:189], v145 offset:51200
	ds_read_b128 v[194:197], v145 offset:52224
	ds_read_b128 v[206:209], v145 offset:53248
	ds_read_b128 v[210:213], v145 offset:54272
	ds_read_b128 v[214:217], v145 offset:55296
	ds_read_b128 v[218:221], v145 offset:56320
	global_load_lds_dwordx4 v[190:191], off
	s_add_i32 m0, s24, 0x2000
	s_add_u32 s22, s22, 0x40080
	v_lshl_add_u64 v[190:191], v[202:203], 0, s[50:51]
	s_addc_u32 s23, s23, 0
	s_add_i32 s24, s42, s3
	global_load_lds_dwordx4 v[190:191], off
	v_lshl_add_u64 v[190:191], s[22:23], 0, v[132:133]
	s_mov_b32 m0, s24
	s_nop 0
	global_load_lds_dwordx4 v[190:191], off
	v_lshl_add_u64 v[190:191], s[22:23], 0, v[130:131]
	s_add_i32 m0, s24, 0x2000
	s_nop 0
	global_load_lds_dwordx4 v[190:191], off
	v_lshl_add_u64 v[190:191], v[204:205], 0, s[50:51]
	s_mov_b32 m0, s30
	s_nop 0
	global_load_lds_dwordx4 v[190:191], off
	v_lshl_add_u64 v[190:191], v[222:223], 0, s[50:51]
	s_mov_b32 m0, s31
	s_nop 0
	global_load_lds_dwordx4 v[190:191], off
	s_waitcnt vmcnt(8)
	s_waitcnt lgkmcnt(0)
	s_barrier
	s_setprio 1
	v_mfma_f32_16x16x32_bf16 v[62:65], v[138:141], v[178:181], v[62:65]
	v_mfma_f32_16x16x32_bf16 v[58:61], v[150:153], v[178:181], v[58:61]
	v_mfma_f32_16x16x32_bf16 v[46:49], v[138:141], v[186:189], v[46:49]
	v_mfma_f32_16x16x32_bf16 v[42:45], v[150:153], v[186:189], v[42:45]
	v_mfma_f32_16x16x32_bf16 v[30:33], v[138:141], v[206:209], v[30:33]
	v_mfma_f32_16x16x32_bf16 v[26:29], v[150:153], v[206:209], v[26:29]
	v_mfma_f32_16x16x32_bf16 v[14:17], v[138:141], v[214:217], v[14:17]
	v_mfma_f32_16x16x32_bf16 v[10:13], v[150:153], v[214:217], v[10:13]
	v_mfma_f32_16x16x32_bf16 v[62:65], v[146:149], v[182:185], v[62:65]
	v_mfma_f32_16x16x32_bf16 v[58:61], v[154:157], v[182:185], v[58:61]
	v_mfma_f32_16x16x32_bf16 v[46:49], v[146:149], v[194:197], v[46:49]
	v_mfma_f32_16x16x32_bf16 v[42:45], v[154:157], v[194:197], v[42:45]
	v_mfma_f32_16x16x32_bf16 v[30:33], v[146:149], v[210:213], v[30:33]
	v_mfma_f32_16x16x32_bf16 v[26:29], v[154:157], v[210:213], v[26:29]
	v_mfma_f32_16x16x32_bf16 v[14:17], v[146:149], v[218:221], v[14:17]
	v_mfma_f32_16x16x32_bf16 v[10:13], v[154:157], v[218:221], v[10:13]
	s_setprio 0
	s_setprio 1
	v_mfma_f32_16x16x32_bf16 v[54:57], v[158:161], v[178:181], v[54:57]
	v_mfma_f32_16x16x32_bf16 v[50:53], v[170:173], v[178:181], v[50:53]
	v_mfma_f32_16x16x32_bf16 v[38:41], v[158:161], v[186:189], v[38:41]
	v_mfma_f32_16x16x32_bf16 v[34:37], v[170:173], v[186:189], v[34:37]
	v_mfma_f32_16x16x32_bf16 v[22:25], v[158:161], v[206:209], v[22:25]
	v_mfma_f32_16x16x32_bf16 v[18:21], v[170:173], v[206:209], v[18:21]
	v_mfma_f32_16x16x32_bf16 v[6:9], v[158:161], v[214:217], v[6:9]
	v_mfma_f32_16x16x32_bf16 v[2:5], v[170:173], v[214:217], v[2:5]
	v_mfma_f32_16x16x32_bf16 v[54:57], v[164:167], v[182:185], v[54:57]
	v_mfma_f32_16x16x32_bf16 v[50:53], v[174:177], v[182:185], v[50:53]
	v_mfma_f32_16x16x32_bf16 v[38:41], v[164:167], v[194:197], v[38:41]
	v_mfma_f32_16x16x32_bf16 v[34:37], v[174:177], v[194:197], v[34:37]
	v_mfma_f32_16x16x32_bf16 v[22:25], v[164:167], v[210:213], v[22:25]
	v_mfma_f32_16x16x32_bf16 v[18:21], v[174:177], v[210:213], v[18:21]
	v_mfma_f32_16x16x32_bf16 v[6:9], v[164:167], v[218:221], v[6:9]
	v_mfma_f32_16x16x32_bf16 v[2:5], v[174:177], v[218:221], v[2:5]
	s_setprio 0
	s_barrier
	s_add_i32 s40, s40, 2
	s_add_u32 s4, s4, 0x100
	s_addc_u32 s5, s5, 0
	s_add_u32 s38, s38, 0x100
	s_addc_u32 s39, s39, 0
	s_cmp_gt_u32 s40, 13
	s_cbranch_scc0 .LBB0_139
	s_and_b64 vcc, exec, s[12:13]
	s_cbranch_vccz .LBB0_142
	s_barrier

; #define PG8_STAGE(bufoff, gbase, voff) do { _Pragma("unroll") for (int _i = 0; _i < 2; ++_i) \
;         __builtin_amdgcn_global_load_lds((const unsigned*)((const char*)(gbase) + (voff)[_i]), (LAS unsigned*)(lds + (bufoff) + ldsw + _i * 8192), 16, 0, 0); } while (0)
; #define PG8_LDA(dst, b, h) do { _Pragma("unroll") for (int m = 0; m < 4; ++m) _Pragma("unroll") for (int k = 0; k < 2; ++k) dst[m][k] = *(const LAS bf16x8*)(lds + PG8_SA(b, h) + aoff + m * 2048 + k * 1024); } while (0)
; #define PG8_LDB(dst, b, h) do { _Pragma("unroll") for (int n = 0; n < 2; ++n) _Pragma("unroll") for (int k = 0; k < 2; ++k) dst[n][k] = *(const LAS bf16x8*)(lds + PG8_SB(b, h) + boff + n * 2048 + k * 1024); } while (0)
; #define PG8_MMA(ai, bj, At, Bt) do { __builtin_amdgcn_s_setprio(1); _Pragma("unroll") for (int m = 0; m < 4; ++m) _Pragma("unroll") for (int n = 0; n < 2; ++n) _Pragma("unroll") for (int k = 0; k < 2; ++k) \
;         acc[ai][bj][m][n] = __builtin_amdgcn_mfma_f32_16x16x32_bf16(Bt[n][k], At[m][k], acc[ai][bj][m][n], 0, 0, 0); __builtin_amdgcn_s_setprio(0); } while (0)
; #define PG8_WAIT_V(n) asm volatile("s_waitcnt vmcnt(" #n ")" ::: "memory")
; #define PG8_WAIT_L(n) asm volatile("s_waitcnt lgkmcnt(" #n ")" ::: "memory")
; #define PG8_BAR __builtin_amdgcn_s_barrier()
; #define PG8_SCHED __builtin_amdgcn_sched_barrier(0)
; template <class Epi, bool ALIGN_EPI = PG8_ALIGN, bool SP2 = PG8_SP2>
; __device__ __forceinline__ void gemm_phase(LAS unsigned char* lds, const Gemm g, const StaticOrder& S, const Epi& E) {
;     ...
;             const bool last = (t == nt - 2);
;             const char* a1 = cA + (size_t)(t + 1) * kstepA;
;             const char* a2 = last ? nA : cA + (size_t)(t + 2) * kstepA; const char* b2 = last ? nB : cB + (size_t)(t + 2) * kstepB;
;             const char* a3 = a2 + kstepA; const char* b3 = b2 + kstepB;
;             if constexpr (SP2) {
;             PG8_LDB(B0, 0, 0); PG8_LDB(B1, 0, 1); PG8_SCHED; PG8_LDA(At, 0, 0); PG8_STAGE(PG8_SA(1, 1), a1 + hstepA, voffA);
;             PG8_WAIT_V(8); PG8_WAIT_L(0); PG8_BAR; PG8_MMA(0, 0, At, B0); PG8_MMA(0, 1, At, B1); PG8_BAR; PG8_SCHED;
;             PG8_LDA(At, 0, 1); PG8_STAGE(PG8_SB(0, 0), b2, voffB); PG8_STAGE(PG8_SB(0, 1), b2 + hstepB, voffB); PG8_STAGE(PG8_SA(0, 0), a2, voffA);
;             PG8_WAIT_V(8); PG8_WAIT_L(0); PG8_BAR; PG8_MMA(1, 0, At, B0); PG8_MMA(1, 1, At, B1); PG8_BAR; PG8_SCHED;
.Lfirst_iter_u139:
	s_add_u32 s22, s4, 0xfffc0080
	s_addc_u32 s23, s5, -1
	s_add_i32 s41, 0, 0x10000
	s_cmp_eq_u32 s40, 12
	s_cselect_b32 s25, s17, s23
	s_cselect_b32 s24, s36, s22
	v_add_u32_e32 v0, s41, v143
	s_cselect_b32 s23, s15, s39
	s_cselect_b32 s22, s37, s38
	s_add_i32 s44, 0, 0x14000
	ds_read_b128 v[138:141], v0
	ds_read_b128 v[146:149], v0 offset:1024
	ds_read_b128 v[150:153], v0 offset:2048
	ds_read_b128 v[154:157], v0 offset:3072
	v_add_u32_e32 v0, s44, v143
	ds_read_b128 v[158:161], v0
	ds_read_b128 v[164:167], v0 offset:1024
	ds_read_b128 v[170:173], v0 offset:2048
	ds_read_b128 v[174:177], v0 offset:3072
	v_lshl_add_u64 v[190:191], s[4:5], 0, v[134:135]
	s_add_i32 m0, s26, 0xc000
	ds_read_b128 v[178:181], v145
	ds_read_b128 v[182:185], v145 offset:1024
	ds_read_b128 v[186:189], v145 offset:2048
	ds_read_b128 v[194:197], v145 offset:3072
	ds_read_b128 v[206:209], v145 offset:4096
	ds_read_b128 v[210:213], v145 offset:5120
	ds_read_b128 v[214:217], v145 offset:6144
	ds_read_b128 v[218:221], v145 offset:7168
	global_load_lds_dwordx4 v[190:191], off
	v_lshl_add_u64 v[190:191], s[4:5], 0, v[136:137]
	s_add_i32 m0, s26, 0xe000
	s_nop 0
	global_load_lds_dwordx4 v[190:191], off
	s_waitcnt vmcnt(8)
	s_waitcnt lgkmcnt(0)
	s_barrier
	s_setprio 1
	v_mfma_f32_16x16x32_bf16 v[126:129], v[138:141], v[178:181], 0
	v_mfma_f32_16x16x32_bf16 v[122:125], v[150:153], v[178:181], 0
	v_mfma_f32_16x16x32_bf16 v[110:113], v[138:141], v[186:189], 0
	v_mfma_f32_16x16x32_bf16 v[106:109], v[150:153], v[186:189], 0
	v_mfma_f32_16x16x32_bf16 v[94:97], v[138:141], v[206:209], 0
	v_mfma_f32_16x16x32_bf16 v[90:93], v[150:153], v[206:209], 0
	v_mfma_f32_16x16x32_bf16 v[78:81], v[138:141], v[214:217], 0
	v_mfma_f32_16x16x32_bf16 v[74:77], v[150:153], v[214:217], 0
	v_mfma_f32_16x16x32_bf16 v[126:129], v[146:149], v[182:185], v[126:129]
	v_mfma_f32_16x16x32_bf16 v[122:125], v[154:157], v[182:185], v[122:125]
	v_mfma_f32_16x16x32_bf16 v[110:113], v[146:149], v[194:197], v[110:113]
	v_mfma_f32_16x16x32_bf16 v[106:109], v[154:157], v[194:197], v[106:109]
	v_mfma_f32_16x16x32_bf16 v[94:97], v[146:149], v[210:213], v[94:97]
	v_mfma_f32_16x16x32_bf16 v[90:93], v[154:157], v[210:213], v[90:93]
	v_mfma_f32_16x16x32_bf16 v[78:81], v[146:149], v[218:221], v[78:81]
	v_mfma_f32_16x16x32_bf16 v[74:77], v[154:157], v[218:221], v[74:77]
	s_setprio 0
	s_setprio 1
	v_mfma_f32_16x16x32_bf16 v[118:121], v[158:161], v[178:181], 0
	v_mfma_f32_16x16x32_bf16 v[114:117], v[170:173], v[178:181], 0
	v_mfma_f32_16x16x32_bf16 v[102:105], v[158:161], v[186:189], 0
	v_mfma_f32_16x16x32_bf16 v[98:101], v[170:173], v[186:189], 0
	v_mfma_f32_16x16x32_bf16 v[86:89], v[158:161], v[206:209], 0
	v_mfma_f32_16x16x32_bf16 v[82:85], v[170:173], v[206:209], 0
	v_mfma_f32_16x16x32_bf16 v[70:73], v[158:161], v[214:217], 0
	v_mfma_f32_16x16x32_bf16 v[66:69], v[170:173], v[214:217], 0
	v_mfma_f32_16x16x32_bf16 v[118:121], v[164:167], v[182:185], v[118:121]
	v_mfma_f32_16x16x32_bf16 v[114:117], v[174:177], v[182:185], v[114:117]
	v_mfma_f32_16x16x32_bf16 v[102:105], v[164:167], v[194:197], v[102:105]
	v_mfma_f32_16x16x32_bf16 v[98:101], v[174:177], v[194:197], v[98:101]
	v_mfma_f32_16x16x32_bf16 v[86:89], v[164:167], v[210:213], v[86:89]
	v_mfma_f32_16x16x32_bf16 v[82:85], v[174:177], v[210:213], v[82:85]
	v_mfma_f32_16x16x32_bf16 v[70:73], v[164:167], v[218:221], v[70:73]
	v_mfma_f32_16x16x32_bf16 v[66:69], v[174:177], v[218:221], v[66:69]
	s_setprio 0
	s_barrier
	s_add_i32 s41, s41, s3
	v_lshl_add_u64 v[190:191], s[22:23], 0, v[132:133]
	s_mov_b32 m0, s41
	ds_read_b128 v[178:181], v145 offset:16384
	ds_read_b128 v[182:185], v145 offset:17408
	ds_read_b128 v[186:189], v145 offset:18432
	ds_read_b128 v[194:197], v145 offset:19456
	ds_read_b128 v[206:209], v145 offset:20480
	ds_read_b128 v[210:213], v145 offset:21504
	ds_read_b128 v[214:217], v145 offset:22528
	ds_read_b128 v[218:221], v145 offset:23552
	global_load_lds_dwordx4 v[190:191], off
	s_add_i32 m0, s41, 0x2000
	s_add_u32 s42, s22, 0x40000
	v_lshl_add_u64 v[202:203], s[22:23], 0, v[130:131]
	s_addc_u32 s43, s23, 0
	s_add_i32 s41, s44, s3
	global_load_lds_dwordx4 v[202:203], off
	v_lshl_add_u64 v[204:205], s[42:43], 0, v[132:133]
	s_mov_b32 m0, s41
	v_lshl_add_u64 v[222:223], s[24:25], 0, v[130:131]
	global_load_lds_dwordx4 v[204:205], off
	v_lshl_add_u64 v[204:205], s[42:43], 0, v[130:131]
	s_add_i32 m0, s41, 0x2000
	s_nop 0
	global_load_lds_dwordx4 v[204:205], off
	v_lshl_add_u64 v[204:205], s[24:25], 0, v[132:133]
	s_mov_b32 m0, s26
	s_nop 0
	global_load_lds_dwordx4 v[204:205], off
	s_mov_b32 m0, s27
	s_nop 0
	global_load_lds_dwordx4 v[222:223], off
	s_waitcnt vmcnt(8)
	s_waitcnt lgkmcnt(0)
	s_barrier
; #define PG8_STAGE(bufoff, gbase, voff) do { _Pragma("unroll") for (int _i = 0; _i < 2; ++_i) \
;         __builtin_amdgcn_global_load_lds((const unsigned*)((const char*)(gbase) + (voff)[_i]), (LAS unsigned*)(lds + (bufoff) + ldsw + _i * 8192), 16, 0, 0); } while (0)
; #define PG8_LDA(dst, b, h) do { _Pragma("unroll") for (int m = 0; m < 4; ++m) _Pragma("unroll") for (int k = 0; k < 2; ++k) dst[m][k] = *(const LAS bf16x8*)(lds + PG8_SA(b, h) + aoff + m * 2048 + k * 1024); } while (0)
; #define PG8_LDB(dst, b, h) do { _Pragma("unroll") for (int n = 0; n < 2; ++n) _Pragma("unroll") for (int k = 0; k < 2; ++k) dst[n][k] = *(const LAS bf16x8*)(lds + PG8_SB(b, h) + boff + n * 2048 + k * 1024); } while (0)
; #define PG8_MMA(ai, bj, At, Bt) do { __builtin_amdgcn_s_setprio(1); _Pragma("unroll") for (int m = 0; m < 4; ++m) _Pragma("unroll") for (int n = 0; n < 2; ++n) _Pragma("unroll") for (int k = 0; k < 2; ++k) \
;         acc[ai][bj][m][n] = __builtin_amdgcn_mfma_f32_16x16x32_bf16(Bt[n][k], At[m][k], acc[ai][bj][m][n], 0, 0, 0); __builtin_amdgcn_s_setprio(0); } while (0)
; #define PG8_WAIT_V(n) asm volatile("s_waitcnt vmcnt(" #n ")" ::: "memory")
; #define PG8_WAIT_L(n) asm volatile("s_waitcnt lgkmcnt(" #n ")" ::: "memory")
; #define PG8_BAR __builtin_amdgcn_s_barrier()
; #define PG8_SCHED __builtin_amdgcn_sched_barrier(0)
; template <class Epi, bool ALIGN_EPI = PG8_ALIGN, bool SP2 = PG8_SP2>
; __device__ __forceinline__ void gemm_phase(LAS unsigned char* lds, const Gemm g, const StaticOrder& S, const Epi& E) {
;     ...
;             PG8_WAIT_V(8); PG8_WAIT_L(0); PG8_BAR; PG8_MMA(1, 0, At, B0); PG8_MMA(1, 1, At, B1); PG8_BAR; PG8_SCHED;
;             PG8_LDB(B0, 1, 0); PG8_LDB(B1, 1, 1); PG8_SCHED; PG8_LDA(At, 1, 0); PG8_STAGE(PG8_SA(0, 1), a2 + hstepA, voffA);
;             PG8_WAIT_V(8); PG8_WAIT_L(0); PG8_BAR; PG8_MMA(0, 0, At, B0); PG8_MMA(0, 1, At, B1); PG8_BAR; PG8_SCHED;
	s_setprio 1
	v_mfma_f32_16x16x32_bf16 v[62:65], v[138:141], v[178:181], 0
	v_mfma_f32_16x16x32_bf16 v[58:61], v[150:153], v[178:181], 0
	v_mfma_f32_16x16x32_bf16 v[46:49], v[138:141], v[186:189], 0
	v_mfma_f32_16x16x32_bf16 v[42:45], v[150:153], v[186:189], 0
	v_mfma_f32_16x16x32_bf16 v[30:33], v[138:141], v[206:209], 0
	v_mfma_f32_16x16x32_bf16 v[26:29], v[150:153], v[206:209], 0
	v_mfma_f32_16x16x32_bf16 v[14:17], v[138:141], v[214:217], 0
	v_mfma_f32_16x16x32_bf16 v[10:13], v[150:153], v[214:217], 0
	v_mfma_f32_16x16x32_bf16 v[62:65], v[146:149], v[182:185], v[62:65]
	v_mfma_f32_16x16x32_bf16 v[58:61], v[154:157], v[182:185], v[58:61]
	v_mfma_f32_16x16x32_bf16 v[46:49], v[146:149], v[194:197], v[46:49]
	v_mfma_f32_16x16x32_bf16 v[42:45], v[154:157], v[194:197], v[42:45]
	v_mfma_f32_16x16x32_bf16 v[30:33], v[146:149], v[210:213], v[30:33]
	v_mfma_f32_16x16x32_bf16 v[26:29], v[154:157], v[210:213], v[26:29]
	v_mfma_f32_16x16x32_bf16 v[14:17], v[146:149], v[218:221], v[14:17]
	v_mfma_f32_16x16x32_bf16 v[10:13], v[154:157], v[218:221], v[10:13]
	s_setprio 0
	s_setprio 1
	v_mfma_f32_16x16x32_bf16 v[54:57], v[158:161], v[178:181], 0
	v_mfma_f32_16x16x32_bf16 v[50:53], v[170:173], v[178:181], 0
	v_mfma_f32_16x16x32_bf16 v[38:41], v[158:161], v[186:189], 0
	v_mfma_f32_16x16x32_bf16 v[34:37], v[170:173], v[186:189], 0
	v_mfma_f32_16x16x32_bf16 v[22:25], v[158:161], v[206:209], 0
	v_mfma_f32_16x16x32_bf16 v[18:21], v[170:173], v[206:209], 0
	v_mfma_f32_16x16x32_bf16 v[6:9], v[158:161], v[214:217], 0
	v_mfma_f32_16x16x32_bf16 v[2:5], v[170:173], v[214:217], 0
	v_mfma_f32_16x16x32_bf16 v[54:57], v[164:167], v[182:185], v[54:57]
	v_mfma_f32_16x16x32_bf16 v[50:53], v[174:177], v[182:185], v[50:53]
	v_mfma_f32_16x16x32_bf16 v[38:41], v[164:167], v[194:197], v[38:41]
	v_mfma_f32_16x16x32_bf16 v[34:37], v[174:177], v[194:197], v[34:37]
	v_mfma_f32_16x16x32_bf16 v[22:25], v[164:167], v[210:213], v[22:25]
	v_mfma_f32_16x16x32_bf16 v[18:21], v[174:177], v[210:213], v[18:21]
	v_mfma_f32_16x16x32_bf16 v[6:9], v[164:167], v[218:221], v[6:9]
	v_mfma_f32_16x16x32_bf16 v[2:5], v[174:177], v[218:221], v[2:5]
	s_setprio 0
	s_barrier
	s_add_i32 s41, 0, 0x18000
	v_add_u32_e32 v0, s41, v143
	s_add_i32 s42, 0, 0x1c000
	ds_read_b128 v[138:141], v0
	ds_read_b128 v[146:149], v0 offset:1024
	ds_read_b128 v[150:153], v0 offset:2048
	ds_read_b128 v[154:157], v0 offset:3072
	v_add_u32_e32 v0, s42, v143
	ds_read_b128 v[158:161], v0
	ds_read_b128 v[164:167], v0 offset:1024
	ds_read_b128 v[170:173], v0 offset:2048
	ds_read_b128 v[174:177], v0 offset:3072
	s_add_u32 s24, s24, 0x40000
	s_addc_u32 s25, s25, 0
	s_mov_b32 m0, s28
	v_lshl_add_u64 v[224:225], s[24:25], 0, v[132:133]
	ds_read_b128 v[178:181], v145 offset:32768
	ds_read_b128 v[182:185], v145 offset:33792
	ds_read_b128 v[186:189], v145 offset:34816
	ds_read_b128 v[194:197], v145 offset:35840
	ds_read_b128 v[206:209], v145 offset:36864
	ds_read_b128 v[210:213], v145 offset:37888
	ds_read_b128 v[214:217], v145 offset:38912
	ds_read_b128 v[218:221], v145 offset:39936
	global_load_lds_dwordx4 v[224:225], off
	v_lshl_add_u64 v[224:225], s[24:25], 0, v[130:131]
	s_mov_b32 m0, s29
	s_nop 0
	global_load_lds_dwordx4 v[224:225], off
	s_waitcnt vmcnt(8)
	s_waitcnt lgkmcnt(0)
	s_barrier
	s_setprio 1
	v_mfma_f32_16x16x32_bf16 v[126:129], v[138:141], v[178:181], v[126:129]
	v_mfma_f32_16x16x32_bf16 v[122:125], v[150:153], v[178:181], v[122:125]
	v_mfma_f32_16x16x32_bf16 v[110:113], v[138:141], v[186:189], v[110:113]
	v_mfma_f32_16x16x32_bf16 v[106:109], v[150:153], v[186:189], v[106:109]
	v_mfma_f32_16x16x32_bf16 v[94:97], v[138:141], v[206:209], v[94:97]
	v_mfma_f32_16x16x32_bf16 v[90:93], v[150:153], v[206:209], v[90:93]
	v_mfma_f32_16x16x32_bf16 v[78:81], v[138:141], v[214:217], v[78:81]
	v_mfma_f32_16x16x32_bf16 v[74:77], v[150:153], v[214:217], v[74:77]
	v_mfma_f32_16x16x32_bf16 v[126:129], v[146:149], v[182:185], v[126:129]
	v_mfma_f32_16x16x32_bf16 v[122:125], v[154:157], v[182:185], v[122:125]
	v_mfma_f32_16x16x32_bf16 v[110:113], v[146:149], v[194:197], v[110:113]
	v_mfma_f32_16x16x32_bf16 v[106:109], v[154:157], v[194:197], v[106:109]
	v_mfma_f32_16x16x32_bf16 v[94:97], v[146:149], v[210:213], v[94:97]
	v_mfma_f32_16x16x32_bf16 v[90:93], v[154:157], v[210:213], v[90:93]
	v_mfma_f32_16x16x32_bf16 v[78:81], v[146:149], v[218:221], v[78:81]
	v_mfma_f32_16x16x32_bf16 v[74:77], v[154:157], v[218:221], v[74:77]
	s_setprio 0
	s_setprio 1
	v_mfma_f32_16x16x32_bf16 v[118:121], v[158:161], v[178:181], v[118:121]
	v_mfma_f32_16x16x32_bf16 v[114:117], v[170:173], v[178:181], v[114:117]
	v_mfma_f32_16x16x32_bf16 v[102:105], v[158:161], v[186:189], v[102:105]
	v_mfma_f32_16x16x32_bf16 v[98:101], v[170:173], v[186:189], v[98:101]
	v_mfma_f32_16x16x32_bf16 v[86:89], v[158:161], v[206:209], v[86:89]
	v_mfma_f32_16x16x32_bf16 v[82:85], v[170:173], v[206:209], v[82:85]
	v_mfma_f32_16x16x32_bf16 v[70:73], v[158:161], v[214:217], v[70:73]
	v_mfma_f32_16x16x32_bf16 v[66:69], v[170:173], v[214:217], v[66:69]
	v_mfma_f32_16x16x32_bf16 v[118:121], v[164:167], v[182:185], v[118:121]
	v_mfma_f32_16x16x32_bf16 v[114:117], v[174:177], v[182:185], v[114:117]
	v_mfma_f32_16x16x32_bf16 v[102:105], v[164:167], v[194:197], v[102:105]
	v_mfma_f32_16x16x32_bf16 v[98:101], v[174:177], v[194:197], v[98:101]
	v_mfma_f32_16x16x32_bf16 v[86:89], v[164:167], v[210:213], v[86:89]
	v_mfma_f32_16x16x32_bf16 v[82:85], v[174:177], v[210:213], v[82:85]
	v_mfma_f32_16x16x32_bf16 v[70:73], v[164:167], v[218:221], v[70:73]
	v_mfma_f32_16x16x32_bf16 v[66:69], v[174:177], v[218:221], v[66:69]
	s_setprio 0
	s_barrier
; #define PG8_STAGE(bufoff, gbase, voff) do { _Pragma("unroll") for (int _i = 0; _i < 2; ++_i) \
;         __builtin_amdgcn_global_load_lds((const unsigned*)((const char*)(gbase) + (voff)[_i]), (LAS unsigned*)(lds + (bufoff) + ldsw + _i * 8192), 16, 0, 0); } while (0)
; #define PG8_LDA(dst, b, h) do { _Pragma("unroll") for (int m = 0; m < 4; ++m) _Pragma("unroll") for (int k = 0; k < 2; ++k) dst[m][k] = *(const LAS bf16x8*)(lds + PG8_SA(b, h) + aoff + m * 2048 + k * 1024); } while (0)
; #define PG8_MMA(ai, bj, At, Bt) do { __builtin_amdgcn_s_setprio(1); _Pragma("unroll") for (int m = 0; m < 4; ++m) _Pragma("unroll") for (int n = 0; n < 2; ++n) _Pragma("unroll") for (int k = 0; k < 2; ++k) \
;         acc[ai][bj][m][n] = __builtin_amdgcn_mfma_f32_16x16x32_bf16(Bt[n][k], At[m][k], acc[ai][bj][m][n], 0, 0, 0); __builtin_amdgcn_s_setprio(0); } while (0)
; #define PG8_WAIT_V(n) asm volatile("s_waitcnt vmcnt(" #n ")" ::: "memory")
; #define PG8_WAIT_L(n) asm volatile("s_waitcnt lgkmcnt(" #n ")" ::: "memory")
; #define PG8_BAR __builtin_amdgcn_s_barrier()
; #define PG8_SCHED __builtin_amdgcn_sched_barrier(0)
; template <class Epi, bool ALIGN_EPI = PG8_ALIGN, bool SP2 = PG8_SP2>
; __device__ __forceinline__ void gemm_phase(LAS unsigned char* lds, const Gemm g, const StaticOrder& S, const Epi& E) {
;     ...
;             PG8_LDA(At, 1, 1); PG8_STAGE(PG8_SB(1, 0), b3, voffB); PG8_STAGE(PG8_SB(1, 1), b3 + hstepB, voffB); PG8_STAGE(PG8_SA(1, 0), a3, voffA);
;             PG8_WAIT_V(8); PG8_WAIT_L(0); PG8_BAR; PG8_MMA(1, 0, At, B0); PG8_MMA(1, 1, At, B1); PG8_BAR; PG8_SCHED;
	s_add_i32 s24, s41, s3
	v_lshl_add_u64 v[190:191], v[190:191], 0, s[50:51]
	s_mov_b32 m0, s24
	ds_read_b128 v[178:181], v145 offset:49152
	ds_read_b128 v[182:185], v145 offset:50176
	ds_read_b128 v[186:189], v145 offset:51200
	ds_read_b128 v[194:197], v145 offset:52224
	ds_read_b128 v[206:209], v145 offset:53248
	ds_read_b128 v[210:213], v145 offset:54272
	ds_read_b128 v[214:217], v145 offset:55296
	ds_read_b128 v[218:221], v145 offset:56320
	global_load_lds_dwordx4 v[190:191], off
	s_add_i32 m0, s24, 0x2000
	s_add_u32 s22, s22, 0x40080
	v_lshl_add_u64 v[190:191], v[202:203], 0, s[50:51]
	s_addc_u32 s23, s23, 0
	s_add_i32 s24, s42, s3
	global_load_lds_dwordx4 v[190:191], off
	v_lshl_add_u64 v[190:191], s[22:23], 0, v[132:133]
	s_mov_b32 m0, s24
	s_nop 0
	global_load_lds_dwordx4 v[190:191], off
	v_lshl_add_u64 v[190:191], s[22:23], 0, v[130:131]
	s_add_i32 m0, s24, 0x2000
	s_nop 0
	global_load_lds_dwordx4 v[190:191], off
	v_lshl_add_u64 v[190:191], v[204:205], 0, s[50:51]
	s_mov_b32 m0, s30
	s_nop 0
	global_load_lds_dwordx4 v[190:191], off
	v_lshl_add_u64 v[190:191], v[222:223], 0, s[50:51]
	s_mov_b32 m0, s31
	s_nop 0
	global_load_lds_dwordx4 v[190:191], off
	s_waitcnt vmcnt(8)
	s_waitcnt lgkmcnt(0)
	s_barrier
	s_setprio 1
	v_mfma_f32_16x16x32_bf16 v[62:65], v[138:141], v[178:181], v[62:65]
	v_mfma_f32_16x16x32_bf16 v[58:61], v[150:153], v[178:181], v[58:61]
	v_mfma_f32_16x16x32_bf16 v[46:49], v[138:141], v[186:189], v[46:49]
	v_mfma_f32_16x16x32_bf16 v[42:45], v[150:153], v[186:189], v[42:45]
	v_mfma_f32_16x16x32_bf16 v[30:33], v[138:141], v[206:209], v[30:33]
	v_mfma_f32_16x16x32_bf16 v[26:29], v[150:153], v[206:209], v[26:29]
	v_mfma_f32_16x16x32_bf16 v[14:17], v[138:141], v[214:217], v[14:17]
	v_mfma_f32_16x16x32_bf16 v[10:13], v[150:153], v[214:217], v[10:13]
	v_mfma_f32_16x16x32_bf16 v[62:65], v[146:149], v[182:185], v[62:65]
	v_mfma_f32_16x16x32_bf16 v[58:61], v[154:157], v[182:185], v[58:61]
	v_mfma_f32_16x16x32_bf16 v[46:49], v[146:149], v[194:197], v[46:49]
	v_mfma_f32_16x16x32_bf16 v[42:45], v[154:157], v[194:197], v[42:45]
	v_mfma_f32_16x16x32_bf16 v[30:33], v[146:149], v[210:213], v[30:33]
	v_mfma_f32_16x16x32_bf16 v[26:29], v[154:157], v[210:213], v[26:29]
	v_mfma_f32_16x16x32_bf16 v[14:17], v[146:149], v[218:221], v[14:17]
	v_mfma_f32_16x16x32_bf16 v[10:13], v[154:157], v[218:221], v[10:13]
	s_setprio 0
	s_setprio 1
	v_mfma_f32_16x16x32_bf16 v[54:57], v[158:161], v[178:181], v[54:57]
	v_mfma_f32_16x16x32_bf16 v[50:53], v[170:173], v[178:181], v[50:53]
	v_mfma_f32_16x16x32_bf16 v[38:41], v[158:161], v[186:189], v[38:41]
	v_mfma_f32_16x16x32_bf16 v[34:37], v[170:173], v[186:189], v[34:37]
	v_mfma_f32_16x16x32_bf16 v[22:25], v[158:161], v[206:209], v[22:25]
	v_mfma_f32_16x16x32_bf16 v[18:21], v[170:173], v[206:209], v[18:21]
	v_mfma_f32_16x16x32_bf16 v[6:9], v[158:161], v[214:217], v[6:9]
	v_mfma_f32_16x16x32_bf16 v[2:5], v[170:173], v[214:217], v[2:5]
	v_mfma_f32_16x16x32_bf16 v[54:57], v[164:167], v[182:185], v[54:57]
	v_mfma_f32_16x16x32_bf16 v[50:53], v[174:177], v[182:185], v[50:53]
	v_mfma_f32_16x16x32_bf16 v[38:41], v[164:167], v[194:197], v[38:41]
	v_mfma_f32_16x16x32_bf16 v[34:37], v[174:177], v[194:197], v[34:37]
	v_mfma_f32_16x16x32_bf16 v[22:25], v[164:167], v[210:213], v[22:25]
	v_mfma_f32_16x16x32_bf16 v[18:21], v[174:177], v[210:213], v[18:21]
	v_mfma_f32_16x16x32_bf16 v[6:9], v[164:167], v[218:221], v[6:9]
	v_mfma_f32_16x16x32_bf16 v[2:5], v[174:177], v[218:221], v[2:5]
	s_setprio 0
	s_barrier
	s_add_i32 s40, s40, 2
	s_add_u32 s4, s4, 0x100
	s_addc_u32 s5, s5, 0
	s_add_u32 s38, s38, 0x100
	s_addc_u32 s39, s39, 0
	s_cmp_gt_u32 s40, 13
	s_branch .LBB0_139

; #define PG8_STAGE(bufoff, gbase, voff) do { _Pragma("unroll") for (int _i = 0; _i < 2; ++_i) \
;         __builtin_amdgcn_global_load_lds((const unsigned*)((const char*)(gbase) + (voff)[_i]), (LAS unsigned*)(lds + (bufoff) + ldsw + _i * 8192), 16, 0, 0); } while (0)
; #define PG8_LDA(dst, b, h) do { _Pragma("unroll") for (int m = 0; m < 4; ++m) _Pragma("unroll") for (int k = 0; k < 2; ++k) dst[m][k] = *(const LAS bf16x8*)(lds + PG8_SA(b, h) + aoff + m * 2048 + k * 1024); } while (0)
; #define PG8_LDB(dst, b, h) do { _Pragma("unroll") for (int n = 0; n < 2; ++n) _Pragma("unroll") for (int k = 0; k < 2; ++k) dst[n][k] = *(const LAS bf16x8*)(lds + PG8_SB(b, h) + boff + n * 2048 + k * 1024); } while (0)
; #define PG8_MMA(ai, bj, At, Bt) do { __builtin_amdgcn_s_setprio(1); _Pragma("unroll") for (int m = 0; m < 4; ++m) _Pragma("unroll") for (int n = 0; n < 2; ++n) _Pragma("unroll") for (int k = 0; k < 2; ++k) \
;         acc[ai][bj][m][n] = __builtin_amdgcn_mfma_f32_16x16x32_bf16(Bt[n][k], At[m][k], acc[ai][bj][m][n], 0, 0, 0); __builtin_amdgcn_s_setprio(0); } while (0)
; #define PG8_WAIT_V(n) asm volatile("s_waitcnt vmcnt(" #n ")" ::: "memory")
; #define PG8_WAIT_L(n) asm volatile("s_waitcnt lgkmcnt(" #n ")" ::: "memory")
; #define PG8_BAR __builtin_amdgcn_s_barrier()
; #define PG8_SCHED __builtin_amdgcn_sched_barrier(0)
; template <class Epi, bool ALIGN_EPI = PG8_ALIGN, bool SP2 = PG8_SP2>
; __device__ __forceinline__ void gemm_phase(LAS unsigned char* lds, const Gemm g, const StaticOrder& S, const Epi& E) {
;     ...
;             const bool last = (t == nt - 2);
;             const char* a1 = cA + (size_t)(t + 1) * kstepA;
;             const char* a2 = last ? nA : cA + (size_t)(t + 2) * kstepA; const char* b2 = last ? nB : cB + (size_t)(t + 2) * kstepB;
;             const char* a3 = a2 + kstepA; const char* b3 = b2 + kstepB;
;             if constexpr (SP2) {
;             PG8_LDB(B0, 0, 0); PG8_LDB(B1, 0, 1); PG8_SCHED; PG8_LDA(At, 0, 0); PG8_STAGE(PG8_SA(1, 1), a1 + hstepA, voffA);
;             PG8_WAIT_V(8); PG8_WAIT_L(0); PG8_BAR; PG8_MMA(0, 0, At, B0); PG8_MMA(0, 1, At, B1); PG8_BAR; PG8_SCHED;
;             PG8_LDA(At, 0, 1); PG8_STAGE(PG8_SB(0, 0), b2, voffB); PG8_STAGE(PG8_SB(0, 1), b2 + hstepB, voffB); PG8_STAGE(PG8_SA(0, 0), a2, voffA);
;             PG8_WAIT_V(8); PG8_WAIT_L(0); PG8_BAR; PG8_MMA(1, 0, At, B0); PG8_MMA(1, 1, At, B1); PG8_BAR; PG8_SCHED;
.LBB0_535:
	s_cmp_eq_u32 s39, -2
	s_cbranch_scc1 .Lfirst_iter_u535
	s_add_u32 s4, s0, 0xfffc0080
	s_addc_u32 s5, s1, -1
	s_add_i32 s40, 0, 0x10000
	s_cmp_eq_u32 s39, 12
	s_cselect_b32 s9, s19, s5
	s_cselect_b32 s8, s35, s4
	v_add_u32_e32 v0, s40, v206
	s_cselect_b32 s5, s17, s38
	s_cselect_b32 s4, s36, s37
	s_add_i32 s42, 0, 0x14000
	ds_read_b128 v[114:117], v0
	ds_read_b128 v[122:125], v0 offset:1024
	ds_read_b128 v[130:133], v0 offset:2048
	ds_read_b128 v[134:137], v0 offset:3072
	v_add_u32_e32 v0, s42, v206
	ds_read_b128 v[146:149], v0
	ds_read_b128 v[150:153], v0 offset:1024
	ds_read_b128 v[154:157], v0 offset:2048
	ds_read_b128 v[158:161], v0 offset:3072
	v_lshl_add_u64 v[190:191], s[0:1], 0, v[178:179]
	s_add_i32 m0, s24, 0xc000
	ds_read_b128 v[164:167], v211
	ds_read_b128 v[182:185], v211 offset:1024
	ds_read_b128 v[186:189], v211 offset:2048
	ds_read_b128 v[194:197], v211 offset:3072
	ds_read_b128 v[212:215], v211 offset:4096
	ds_read_b128 v[216:219], v211 offset:5120
	ds_read_b128 v[220:223], v211 offset:6144
	ds_read_b128 v[224:227], v211 offset:7168
	global_load_lds_dwordx4 v[190:191], off
	v_lshl_add_u64 v[190:191], s[0:1], 0, v[180:181]
	s_add_i32 m0, s24, 0xe000
	s_nop 0
	global_load_lds_dwordx4 v[190:191], off
	s_waitcnt vmcnt(8)
	s_waitcnt lgkmcnt(0)
	s_barrier
	s_setprio 1
	v_mfma_f32_16x16x32_bf16 v[70:73], v[114:117], v[164:167], v[70:73]
	v_mfma_f32_16x16x32_bf16 v[30:33], v[130:133], v[164:167], v[30:33]
	v_mfma_f32_16x16x32_bf16 v[58:61], v[114:117], v[186:189], v[58:61]
	v_mfma_f32_16x16x32_bf16 v[26:29], v[130:133], v[186:189], v[26:29]
	v_mfma_f32_16x16x32_bf16 v[54:57], v[114:117], v[212:215], v[54:57]
	v_mfma_f32_16x16x32_bf16 v[22:25], v[130:133], v[212:215], v[22:25]
	v_mfma_f32_16x16x32_bf16 v[50:53], v[114:117], v[220:223], v[50:53]
	v_mfma_f32_16x16x32_bf16 v[18:21], v[130:133], v[220:223], v[18:21]
	v_mfma_f32_16x16x32_bf16 v[70:73], v[122:125], v[182:185], v[70:73]
	v_mfma_f32_16x16x32_bf16 v[30:33], v[134:137], v[182:185], v[30:33]
	v_mfma_f32_16x16x32_bf16 v[58:61], v[122:125], v[194:197], v[58:61]
	v_mfma_f32_16x16x32_bf16 v[26:29], v[134:137], v[194:197], v[26:29]
	v_mfma_f32_16x16x32_bf16 v[54:57], v[122:125], v[216:219], v[54:57]
	v_mfma_f32_16x16x32_bf16 v[22:25], v[134:137], v[216:219], v[22:25]
	v_mfma_f32_16x16x32_bf16 v[50:53], v[122:125], v[224:227], v[50:53]
	v_mfma_f32_16x16x32_bf16 v[18:21], v[134:137], v[224:227], v[18:21]
	s_setprio 0
	s_setprio 1
	v_mfma_f32_16x16x32_bf16 v[142:145], v[146:149], v[164:167], v[142:145]
	v_mfma_f32_16x16x32_bf16 v[138:141], v[154:157], v[164:167], v[138:141]
	v_mfma_f32_16x16x32_bf16 v[126:129], v[146:149], v[186:189], v[126:129]
	v_mfma_f32_16x16x32_bf16 v[118:121], v[154:157], v[186:189], v[118:121]
	v_mfma_f32_16x16x32_bf16 v[110:113], v[146:149], v[212:215], v[110:113]
	v_mfma_f32_16x16x32_bf16 v[106:109], v[154:157], v[212:215], v[106:109]
	v_mfma_f32_16x16x32_bf16 v[102:105], v[146:149], v[220:223], v[102:105]
	v_mfma_f32_16x16x32_bf16 v[98:101], v[154:157], v[220:223], v[98:101]
	v_mfma_f32_16x16x32_bf16 v[142:145], v[150:153], v[182:185], v[142:145]
	v_mfma_f32_16x16x32_bf16 v[138:141], v[158:161], v[182:185], v[138:141]
	v_mfma_f32_16x16x32_bf16 v[126:129], v[150:153], v[194:197], v[126:129]
	v_mfma_f32_16x16x32_bf16 v[118:121], v[158:161], v[194:197], v[118:121]
	v_mfma_f32_16x16x32_bf16 v[110:113], v[150:153], v[216:219], v[110:113]
	v_mfma_f32_16x16x32_bf16 v[106:109], v[158:161], v[216:219], v[106:109]
	v_mfma_f32_16x16x32_bf16 v[102:105], v[150:153], v[224:227], v[102:105]
	v_mfma_f32_16x16x32_bf16 v[98:101], v[158:161], v[224:227], v[98:101]
	s_setprio 0
	s_barrier
	s_add_i32 s40, s40, s3
	v_lshl_add_u64 v[190:191], s[4:5], 0, v[172:173]
	s_mov_b32 m0, s40
	ds_read_b128 v[164:167], v211 offset:16384
	ds_read_b128 v[182:185], v211 offset:17408
	ds_read_b128 v[186:189], v211 offset:18432
	ds_read_b128 v[194:197], v211 offset:19456
	ds_read_b128 v[212:215], v211 offset:20480
	ds_read_b128 v[216:219], v211 offset:21504
	ds_read_b128 v[220:223], v211 offset:22528
	ds_read_b128 v[224:227], v211 offset:23552
	global_load_lds_dwordx4 v[190:191], off
	s_add_i32 m0, s40, 0x2000
	s_add_u32 s40, s4, 0x40000
	v_lshl_add_u64 v[202:203], s[4:5], 0, v[170:171]
	s_addc_u32 s41, s5, 0
	s_add_i32 s42, s42, s3
	global_load_lds_dwordx4 v[202:203], off
	v_lshl_add_u64 v[228:229], s[40:41], 0, v[172:173]
	s_mov_b32 m0, s42
	v_lshl_add_u64 v[230:231], s[8:9], 0, v[170:171]
	global_load_lds_dwordx4 v[228:229], off
	v_lshl_add_u64 v[228:229], s[40:41], 0, v[170:171]
	s_add_i32 m0, s42, 0x2000
	s_nop 0
	global_load_lds_dwordx4 v[228:229], off
	v_lshl_add_u64 v[228:229], s[8:9], 0, v[172:173]
	s_mov_b32 m0, s24
	s_nop 0
	global_load_lds_dwordx4 v[228:229], off
	s_mov_b32 m0, s25
	s_nop 0
	global_load_lds_dwordx4 v[230:231], off
	s_waitcnt vmcnt(8)
	s_waitcnt lgkmcnt(0)
	s_barrier
; #define PG8_STAGE(bufoff, gbase, voff) do { _Pragma("unroll") for (int _i = 0; _i < 2; ++_i) \
;         __builtin_amdgcn_global_load_lds((const unsigned*)((const char*)(gbase) + (voff)[_i]), (LAS unsigned*)(lds + (bufoff) + ldsw + _i * 8192), 16, 0, 0); } while (0)
; #define PG8_LDA(dst, b, h) do { _Pragma("unroll") for (int m = 0; m < 4; ++m) _Pragma("unroll") for (int k = 0; k < 2; ++k) dst[m][k] = *(const LAS bf16x8*)(lds + PG8_SA(b, h) + aoff + m * 2048 + k * 1024); } while (0)
; #define PG8_LDB(dst, b, h) do { _Pragma("unroll") for (int n = 0; n < 2; ++n) _Pragma("unroll") for (int k = 0; k < 2; ++k) dst[n][k] = *(const LAS bf16x8*)(lds + PG8_SB(b, h) + boff + n * 2048 + k * 1024); } while (0)
; #define PG8_MMA(ai, bj, At, Bt) do { __builtin_amdgcn_s_setprio(1); _Pragma("unroll") for (int m = 0; m < 4; ++m) _Pragma("unroll") for (int n = 0; n < 2; ++n) _Pragma("unroll") for (int k = 0; k < 2; ++k) \
;         acc[ai][bj][m][n] = __builtin_amdgcn_mfma_f32_16x16x32_bf16(Bt[n][k], At[m][k], acc[ai][bj][m][n], 0, 0, 0); __builtin_amdgcn_s_setprio(0); } while (0)
; #define PG8_WAIT_V(n) asm volatile("s_waitcnt vmcnt(" #n ")" ::: "memory")
; #define PG8_WAIT_L(n) asm volatile("s_waitcnt lgkmcnt(" #n ")" ::: "memory")
; #define PG8_BAR __builtin_amdgcn_s_barrier()
; #define PG8_SCHED __builtin_amdgcn_sched_barrier(0)
; template <class Epi, bool ALIGN_EPI = PG8_ALIGN, bool SP2 = PG8_SP2>
; __device__ __forceinline__ void gemm_phase(LAS unsigned char* lds, const Gemm g, const StaticOrder& S, const Epi& E) {
;     ...
;             PG8_WAIT_V(8); PG8_WAIT_L(0); PG8_BAR; PG8_MMA(1, 0, At, B0); PG8_MMA(1, 1, At, B1); PG8_BAR; PG8_SCHED;
;             PG8_LDB(B0, 1, 0); PG8_LDB(B1, 1, 1); PG8_SCHED; PG8_LDA(At, 1, 0); PG8_STAGE(PG8_SA(0, 1), a2 + hstepA, voffA);
;             PG8_WAIT_V(8); PG8_WAIT_L(0); PG8_BAR; PG8_MMA(0, 0, At, B0); PG8_MMA(0, 1, At, B1); PG8_BAR; PG8_SCHED;
	s_setprio 1
	v_mfma_f32_16x16x32_bf16 v[46:49], v[114:117], v[164:167], v[46:49]
	v_mfma_f32_16x16x32_bf16 v[14:17], v[130:133], v[164:167], v[14:17]
	v_mfma_f32_16x16x32_bf16 v[42:45], v[114:117], v[186:189], v[42:45]
	v_mfma_f32_16x16x32_bf16 v[10:13], v[130:133], v[186:189], v[10:13]
	v_mfma_f32_16x16x32_bf16 v[38:41], v[114:117], v[212:215], v[38:41]
	v_mfma_f32_16x16x32_bf16 v[6:9], v[130:133], v[212:215], v[6:9]
	v_mfma_f32_16x16x32_bf16 v[34:37], v[114:117], v[220:223], v[34:37]
	v_mfma_f32_16x16x32_bf16 v[2:5], v[130:133], v[220:223], v[2:5]
	v_mfma_f32_16x16x32_bf16 v[46:49], v[122:125], v[182:185], v[46:49]
	v_mfma_f32_16x16x32_bf16 v[14:17], v[134:137], v[182:185], v[14:17]
	v_mfma_f32_16x16x32_bf16 v[42:45], v[122:125], v[194:197], v[42:45]
	v_mfma_f32_16x16x32_bf16 v[10:13], v[134:137], v[194:197], v[10:13]
	v_mfma_f32_16x16x32_bf16 v[38:41], v[122:125], v[216:219], v[38:41]
	v_mfma_f32_16x16x32_bf16 v[6:9], v[134:137], v[216:219], v[6:9]
	v_mfma_f32_16x16x32_bf16 v[34:37], v[122:125], v[224:227], v[34:37]
	v_mfma_f32_16x16x32_bf16 v[2:5], v[134:137], v[224:227], v[2:5]
	s_setprio 0
	s_setprio 1
	v_mfma_f32_16x16x32_bf16 v[94:97], v[146:149], v[164:167], v[94:97]
	v_mfma_f32_16x16x32_bf16 v[90:93], v[154:157], v[164:167], v[90:93]
	v_mfma_f32_16x16x32_bf16 v[86:89], v[146:149], v[186:189], v[86:89]
	v_mfma_f32_16x16x32_bf16 v[82:85], v[154:157], v[186:189], v[82:85]
	v_mfma_f32_16x16x32_bf16 v[78:81], v[146:149], v[212:215], v[78:81]
	v_mfma_f32_16x16x32_bf16 v[74:77], v[154:157], v[212:215], v[74:77]
	v_mfma_f32_16x16x32_bf16 v[66:69], v[146:149], v[220:223], v[66:69]
	v_mfma_f32_16x16x32_bf16 v[62:65], v[154:157], v[220:223], v[62:65]
	v_mfma_f32_16x16x32_bf16 v[94:97], v[150:153], v[182:185], v[94:97]
	v_mfma_f32_16x16x32_bf16 v[90:93], v[158:161], v[182:185], v[90:93]
	v_mfma_f32_16x16x32_bf16 v[86:89], v[150:153], v[194:197], v[86:89]
	v_mfma_f32_16x16x32_bf16 v[82:85], v[158:161], v[194:197], v[82:85]
	v_mfma_f32_16x16x32_bf16 v[78:81], v[150:153], v[216:219], v[78:81]
	v_mfma_f32_16x16x32_bf16 v[74:77], v[158:161], v[216:219], v[74:77]
	v_mfma_f32_16x16x32_bf16 v[66:69], v[150:153], v[224:227], v[66:69]
	v_mfma_f32_16x16x32_bf16 v[62:65], v[158:161], v[224:227], v[62:65]
	s_setprio 0
	s_barrier
	s_add_i32 s40, 0, 0x18000
	v_add_u32_e32 v0, s40, v206
	s_add_i32 s41, 0, 0x1c000
	ds_read_b128 v[114:117], v0
	ds_read_b128 v[122:125], v0 offset:1024
	ds_read_b128 v[130:133], v0 offset:2048
	ds_read_b128 v[134:137], v0 offset:3072
	v_add_u32_e32 v0, s41, v206
	ds_read_b128 v[146:149], v0
	ds_read_b128 v[150:153], v0 offset:1024
	ds_read_b128 v[154:157], v0 offset:2048
	ds_read_b128 v[158:161], v0 offset:3072
	s_add_u32 s8, s8, 0x40000
	s_addc_u32 s9, s9, 0
	s_mov_b32 m0, s26
	v_lshl_add_u64 v[232:233], s[8:9], 0, v[172:173]
	ds_read_b128 v[164:167], v211 offset:32768
	ds_read_b128 v[182:185], v211 offset:33792
	ds_read_b128 v[186:189], v211 offset:34816
	ds_read_b128 v[194:197], v211 offset:35840
	ds_read_b128 v[212:215], v211 offset:36864
	ds_read_b128 v[216:219], v211 offset:37888
	ds_read_b128 v[220:223], v211 offset:38912
	ds_read_b128 v[224:227], v211 offset:39936
	global_load_lds_dwordx4 v[232:233], off
	v_lshl_add_u64 v[232:233], s[8:9], 0, v[170:171]
	s_mov_b32 m0, s27
	s_nop 0
	global_load_lds_dwordx4 v[232:233], off
	s_waitcnt vmcnt(8)
	s_waitcnt lgkmcnt(0)
	s_barrier
	s_setprio 1
	v_mfma_f32_16x16x32_bf16 v[70:73], v[114:117], v[164:167], v[70:73]
	v_mfma_f32_16x16x32_bf16 v[30:33], v[130:133], v[164:167], v[30:33]
	v_mfma_f32_16x16x32_bf16 v[58:61], v[114:117], v[186:189], v[58:61]
	v_mfma_f32_16x16x32_bf16 v[26:29], v[130:133], v[186:189], v[26:29]
	v_mfma_f32_16x16x32_bf16 v[54:57], v[114:117], v[212:215], v[54:57]
	v_mfma_f32_16x16x32_bf16 v[22:25], v[130:133], v[212:215], v[22:25]
	v_mfma_f32_16x16x32_bf16 v[50:53], v[114:117], v[220:223], v[50:53]
	v_mfma_f32_16x16x32_bf16 v[18:21], v[130:133], v[220:223], v[18:21]
	v_mfma_f32_16x16x32_bf16 v[70:73], v[122:125], v[182:185], v[70:73]
	v_mfma_f32_16x16x32_bf16 v[30:33], v[134:137], v[182:185], v[30:33]
	v_mfma_f32_16x16x32_bf16 v[58:61], v[122:125], v[194:197], v[58:61]
	v_mfma_f32_16x16x32_bf16 v[26:29], v[134:137], v[194:197], v[26:29]
	v_mfma_f32_16x16x32_bf16 v[54:57], v[122:125], v[216:219], v[54:57]
	v_mfma_f32_16x16x32_bf16 v[22:25], v[134:137], v[216:219], v[22:25]
	v_mfma_f32_16x16x32_bf16 v[50:53], v[122:125], v[224:227], v[50:53]
	v_mfma_f32_16x16x32_bf16 v[18:21], v[134:137], v[224:227], v[18:21]
	s_setprio 0
	s_setprio 1
	v_mfma_f32_16x16x32_bf16 v[142:145], v[146:149], v[164:167], v[142:145]
	v_mfma_f32_16x16x32_bf16 v[138:141], v[154:157], v[164:167], v[138:141]
	v_mfma_f32_16x16x32_bf16 v[126:129], v[146:149], v[186:189], v[126:129]
	v_mfma_f32_16x16x32_bf16 v[118:121], v[154:157], v[186:189], v[118:121]
	v_mfma_f32_16x16x32_bf16 v[110:113], v[146:149], v[212:215], v[110:113]
	v_mfma_f32_16x16x32_bf16 v[106:109], v[154:157], v[212:215], v[106:109]
	v_mfma_f32_16x16x32_bf16 v[102:105], v[146:149], v[220:223], v[102:105]
	v_mfma_f32_16x16x32_bf16 v[98:101], v[154:157], v[220:223], v[98:101]
	v_mfma_f32_16x16x32_bf16 v[142:145], v[150:153], v[182:185], v[142:145]
	v_mfma_f32_16x16x32_bf16 v[138:141], v[158:161], v[182:185], v[138:141]
	v_mfma_f32_16x16x32_bf16 v[126:129], v[150:153], v[194:197], v[126:129]
	v_mfma_f32_16x16x32_bf16 v[118:121], v[158:161], v[194:197], v[118:121]
	v_mfma_f32_16x16x32_bf16 v[110:113], v[150:153], v[216:219], v[110:113]
	v_mfma_f32_16x16x32_bf16 v[106:109], v[158:161], v[216:219], v[106:109]
	v_mfma_f32_16x16x32_bf16 v[102:105], v[150:153], v[224:227], v[102:105]
	v_mfma_f32_16x16x32_bf16 v[98:101], v[158:161], v[224:227], v[98:101]
	s_setprio 0
	s_barrier
; #define PG8_STAGE(bufoff, gbase, voff) do { _Pragma("unroll") for (int _i = 0; _i < 2; ++_i) \
;         __builtin_amdgcn_global_load_lds((const unsigned*)((const char*)(gbase) + (voff)[_i]), (LAS unsigned*)(lds + (bufoff) + ldsw + _i * 8192), 16, 0, 0); } while (0)
; #define PG8_LDA(dst, b, h) do { _Pragma("unroll") for (int m = 0; m < 4; ++m) _Pragma("unroll") for (int k = 0; k < 2; ++k) dst[m][k] = *(const LAS bf16x8*)(lds + PG8_SA(b, h) + aoff + m * 2048 + k * 1024); } while (0)
; #define PG8_MMA(ai, bj, At, Bt) do { __builtin_amdgcn_s_setprio(1); _Pragma("unroll") for (int m = 0; m < 4; ++m) _Pragma("unroll") for (int n = 0; n < 2; ++n) _Pragma("unroll") for (int k = 0; k < 2; ++k) \
;         acc[ai][bj][m][n] = __builtin_amdgcn_mfma_f32_16x16x32_bf16(Bt[n][k], At[m][k], acc[ai][bj][m][n], 0, 0, 0); __builtin_amdgcn_s_setprio(0); } while (0)
; #define PG8_WAIT_V(n) asm volatile("s_waitcnt vmcnt(" #n ")" ::: "memory")
; #define PG8_WAIT_L(n) asm volatile("s_waitcnt lgkmcnt(" #n ")" ::: "memory")
; #define PG8_BAR __builtin_amdgcn_s_barrier()
; #define PG8_SCHED __builtin_amdgcn_sched_barrier(0)
; template <class Epi, bool ALIGN_EPI = PG8_ALIGN, bool SP2 = PG8_SP2>
; __device__ __forceinline__ void gemm_phase(LAS unsigned char* lds, const Gemm g, const StaticOrder& S, const Epi& E) {
;     ...
;             PG8_LDA(At, 1, 1); PG8_STAGE(PG8_SB(1, 0), b3, voffB); PG8_STAGE(PG8_SB(1, 1), b3 + hstepB, voffB); PG8_STAGE(PG8_SA(1, 0), a3, voffA);
;             PG8_WAIT_V(8); PG8_WAIT_L(0); PG8_BAR; PG8_MMA(1, 0, At, B0); PG8_MMA(1, 1, At, B1); PG8_BAR; PG8_SCHED;
;     ...
;         if constexpr (ALIGN_EPI) { if (wr == 0) PG8_BAR; }
	s_add_i32 s8, s40, s3
	v_lshl_add_u64 v[190:191], v[190:191], 0, s[50:51]
	s_mov_b32 m0, s8
	ds_read_b128 v[164:167], v211 offset:49152
	ds_read_b128 v[182:185], v211 offset:50176
	ds_read_b128 v[186:189], v211 offset:51200
	ds_read_b128 v[194:197], v211 offset:52224
	ds_read_b128 v[212:215], v211 offset:53248
	ds_read_b128 v[216:219], v211 offset:54272
	ds_read_b128 v[220:223], v211 offset:55296
	ds_read_b128 v[224:227], v211 offset:56320
	global_load_lds_dwordx4 v[190:191], off
	s_add_i32 m0, s8, 0x2000
	s_add_u32 s4, s4, 0x40080
	v_lshl_add_u64 v[190:191], v[202:203], 0, s[50:51]
	s_addc_u32 s5, s5, 0
	s_add_i32 s8, s41, s3
	global_load_lds_dwordx4 v[190:191], off
	v_lshl_add_u64 v[190:191], s[4:5], 0, v[172:173]
	s_mov_b32 m0, s8
	s_nop 0
	global_load_lds_dwordx4 v[190:191], off
	v_lshl_add_u64 v[190:191], s[4:5], 0, v[170:171]
	s_add_i32 m0, s8, 0x2000
	s_nop 0
	global_load_lds_dwordx4 v[190:191], off
	v_lshl_add_u64 v[190:191], v[228:229], 0, s[50:51]
	s_mov_b32 m0, s29
	s_nop 0
	global_load_lds_dwordx4 v[190:191], off
	v_lshl_add_u64 v[190:191], v[230:231], 0, s[50:51]
	s_mov_b32 m0, s30
	s_nop 0
	global_load_lds_dwordx4 v[190:191], off
	s_waitcnt vmcnt(8)
	s_waitcnt lgkmcnt(0)
	s_barrier
	s_setprio 1
	v_mfma_f32_16x16x32_bf16 v[46:49], v[114:117], v[164:167], v[46:49]
	v_mfma_f32_16x16x32_bf16 v[14:17], v[130:133], v[164:167], v[14:17]
	v_mfma_f32_16x16x32_bf16 v[42:45], v[114:117], v[186:189], v[42:45]
	v_mfma_f32_16x16x32_bf16 v[10:13], v[130:133], v[186:189], v[10:13]
	v_mfma_f32_16x16x32_bf16 v[38:41], v[114:117], v[212:215], v[38:41]
	v_mfma_f32_16x16x32_bf16 v[6:9], v[130:133], v[212:215], v[6:9]
	v_mfma_f32_16x16x32_bf16 v[34:37], v[114:117], v[220:223], v[34:37]
	v_mfma_f32_16x16x32_bf16 v[2:5], v[130:133], v[220:223], v[2:5]
	v_mfma_f32_16x16x32_bf16 v[46:49], v[122:125], v[182:185], v[46:49]
	v_mfma_f32_16x16x32_bf16 v[14:17], v[134:137], v[182:185], v[14:17]
	v_mfma_f32_16x16x32_bf16 v[42:45], v[122:125], v[194:197], v[42:45]
	v_mfma_f32_16x16x32_bf16 v[10:13], v[134:137], v[194:197], v[10:13]
	v_mfma_f32_16x16x32_bf16 v[38:41], v[122:125], v[216:219], v[38:41]
	v_mfma_f32_16x16x32_bf16 v[6:9], v[134:137], v[216:219], v[6:9]
	v_mfma_f32_16x16x32_bf16 v[34:37], v[122:125], v[224:227], v[34:37]
	v_mfma_f32_16x16x32_bf16 v[2:5], v[134:137], v[224:227], v[2:5]
	s_setprio 0
	s_setprio 1
	v_mfma_f32_16x16x32_bf16 v[94:97], v[146:149], v[164:167], v[94:97]
	v_mfma_f32_16x16x32_bf16 v[90:93], v[154:157], v[164:167], v[90:93]
	v_mfma_f32_16x16x32_bf16 v[86:89], v[146:149], v[186:189], v[86:89]
	v_mfma_f32_16x16x32_bf16 v[82:85], v[154:157], v[186:189], v[82:85]
	v_mfma_f32_16x16x32_bf16 v[78:81], v[146:149], v[212:215], v[78:81]
	v_mfma_f32_16x16x32_bf16 v[74:77], v[154:157], v[212:215], v[74:77]
	v_mfma_f32_16x16x32_bf16 v[66:69], v[146:149], v[220:223], v[66:69]
	v_mfma_f32_16x16x32_bf16 v[62:65], v[154:157], v[220:223], v[62:65]
	v_mfma_f32_16x16x32_bf16 v[94:97], v[150:153], v[182:185], v[94:97]
	v_mfma_f32_16x16x32_bf16 v[90:93], v[158:161], v[182:185], v[90:93]
	v_mfma_f32_16x16x32_bf16 v[86:89], v[150:153], v[194:197], v[86:89]
	v_mfma_f32_16x16x32_bf16 v[82:85], v[158:161], v[194:197], v[82:85]
	v_mfma_f32_16x16x32_bf16 v[78:81], v[150:153], v[216:219], v[78:81]
	v_mfma_f32_16x16x32_bf16 v[74:77], v[158:161], v[216:219], v[74:77]
	v_mfma_f32_16x16x32_bf16 v[66:69], v[150:153], v[224:227], v[66:69]
	v_mfma_f32_16x16x32_bf16 v[62:65], v[158:161], v[224:227], v[62:65]
	s_setprio 0
	s_barrier
	s_add_i32 s39, s39, 2
	s_add_u32 s0, s0, 0x100
	s_addc_u32 s1, s1, 0
	s_add_u32 s37, s37, 0x100
	s_addc_u32 s38, s38, 0
	s_cmp_gt_u32 s39, 13
	s_cbranch_scc0 .LBB0_535
	s_and_b64 vcc, exec, s[12:13]
	s_cbranch_vccz .LBB0_538
	s_barrier

; #define PG8_STAGE(bufoff, gbase, voff) do { _Pragma("unroll") for (int _i = 0; _i < 2; ++_i) \
;         __builtin_amdgcn_global_load_lds((const unsigned*)((const char*)(gbase) + (voff)[_i]), (LAS unsigned*)(lds + (bufoff) + ldsw + _i * 8192), 16, 0, 0); } while (0)
; #define PG8_LDA(dst, b, h) do { _Pragma("unroll") for (int m = 0; m < 4; ++m) _Pragma("unroll") for (int k = 0; k < 2; ++k) dst[m][k] = *(const LAS bf16x8*)(lds + PG8_SA(b, h) + aoff + m * 2048 + k * 1024); } while (0)
; #define PG8_LDB(dst, b, h) do { _Pragma("unroll") for (int n = 0; n < 2; ++n) _Pragma("unroll") for (int k = 0; k < 2; ++k) dst[n][k] = *(const LAS bf16x8*)(lds + PG8_SB(b, h) + boff + n * 2048 + k * 1024); } while (0)
; #define PG8_MMA(ai, bj, At, Bt) do { __builtin_amdgcn_s_setprio(1); _Pragma("unroll") for (int m = 0; m < 4; ++m) _Pragma("unroll") for (int n = 0; n < 2; ++n) _Pragma("unroll") for (int k = 0; k < 2; ++k) \
;         acc[ai][bj][m][n] = __builtin_amdgcn_mfma_f32_16x16x32_bf16(Bt[n][k], At[m][k], acc[ai][bj][m][n], 0, 0, 0); __builtin_amdgcn_s_setprio(0); } while (0)
; #define PG8_WAIT_V(n) asm volatile("s_waitcnt vmcnt(" #n ")" ::: "memory")
; #define PG8_WAIT_L(n) asm volatile("s_waitcnt lgkmcnt(" #n ")" ::: "memory")
; #define PG8_BAR __builtin_amdgcn_s_barrier()
; #define PG8_SCHED __builtin_amdgcn_sched_barrier(0)
; template <class Epi, bool ALIGN_EPI = PG8_ALIGN, bool SP2 = PG8_SP2>
; __device__ __forceinline__ void gemm_phase(LAS unsigned char* lds, const Gemm g, const StaticOrder& S, const Epi& E) {
;     ...
;             const bool last = (t == nt - 2);
;             const char* a1 = cA + (size_t)(t + 1) * kstepA;
;             const char* a2 = last ? nA : cA + (size_t)(t + 2) * kstepA; const char* b2 = last ? nB : cB + (size_t)(t + 2) * kstepB;
;             const char* a3 = a2 + kstepA; const char* b3 = b2 + kstepB;
;             if constexpr (SP2) {
;             PG8_LDB(B0, 0, 0); PG8_LDB(B1, 0, 1); PG8_SCHED; PG8_LDA(At, 0, 0); PG8_STAGE(PG8_SA(1, 1), a1 + hstepA, voffA);
;             PG8_WAIT_V(8); PG8_WAIT_L(0); PG8_BAR; PG8_MMA(0, 0, At, B0); PG8_MMA(0, 1, At, B1); PG8_BAR; PG8_SCHED;
;             PG8_LDA(At, 0, 1); PG8_STAGE(PG8_SB(0, 0), b2, voffB); PG8_STAGE(PG8_SB(0, 1), b2 + hstepB, voffB); PG8_STAGE(PG8_SA(0, 0), a2, voffA);
;             PG8_WAIT_V(8); PG8_WAIT_L(0); PG8_BAR; PG8_MMA(1, 0, At, B0); PG8_MMA(1, 1, At, B1); PG8_BAR; PG8_SCHED;
.Lfirst_iter_u535:
	s_add_u32 s4, s0, 0xfffc0080
	s_addc_u32 s5, s1, -1
	s_add_i32 s40, 0, 0x10000
	s_cmp_eq_u32 s39, 12
	s_cselect_b32 s9, s19, s5
	s_cselect_b32 s8, s35, s4
	v_add_u32_e32 v0, s40, v206
	s_cselect_b32 s5, s17, s38
	s_cselect_b32 s4, s36, s37
	s_add_i32 s42, 0, 0x14000
	ds_read_b128 v[114:117], v0
	ds_read_b128 v[122:125], v0 offset:1024
	ds_read_b128 v[130:133], v0 offset:2048
	ds_read_b128 v[134:137], v0 offset:3072
	v_add_u32_e32 v0, s42, v206
	ds_read_b128 v[146:149], v0
	ds_read_b128 v[150:153], v0 offset:1024
	ds_read_b128 v[154:157], v0 offset:2048
	ds_read_b128 v[158:161], v0 offset:3072
	v_lshl_add_u64 v[190:191], s[0:1], 0, v[178:179]
	s_add_i32 m0, s24, 0xc000
	ds_read_b128 v[164:167], v211
	ds_read_b128 v[182:185], v211 offset:1024
	ds_read_b128 v[186:189], v211 offset:2048
	ds_read_b128 v[194:197], v211 offset:3072
	ds_read_b128 v[212:215], v211 offset:4096
	ds_read_b128 v[216:219], v211 offset:5120
	ds_read_b128 v[220:223], v211 offset:6144
	ds_read_b128 v[224:227], v211 offset:7168
	global_load_lds_dwordx4 v[190:191], off
	v_lshl_add_u64 v[190:191], s[0:1], 0, v[180:181]
	s_add_i32 m0, s24, 0xe000
	s_nop 0
	global_load_lds_dwordx4 v[190:191], off
	s_waitcnt vmcnt(8)
	s_waitcnt lgkmcnt(0)
	s_barrier
	s_setprio 1
	v_mfma_f32_16x16x32_bf16 v[70:73], v[114:117], v[164:167], 0
	v_mfma_f32_16x16x32_bf16 v[30:33], v[130:133], v[164:167], 0
	v_mfma_f32_16x16x32_bf16 v[58:61], v[114:117], v[186:189], 0
	v_mfma_f32_16x16x32_bf16 v[26:29], v[130:133], v[186:189], 0
	v_mfma_f32_16x16x32_bf16 v[54:57], v[114:117], v[212:215], 0
	v_mfma_f32_16x16x32_bf16 v[22:25], v[130:133], v[212:215], 0
	v_mfma_f32_16x16x32_bf16 v[50:53], v[114:117], v[220:223], 0
	v_mfma_f32_16x16x32_bf16 v[18:21], v[130:133], v[220:223], 0
	v_mfma_f32_16x16x32_bf16 v[70:73], v[122:125], v[182:185], v[70:73]
	v_mfma_f32_16x16x32_bf16 v[30:33], v[134:137], v[182:185], v[30:33]
	v_mfma_f32_16x16x32_bf16 v[58:61], v[122:125], v[194:197], v[58:61]
	v_mfma_f32_16x16x32_bf16 v[26:29], v[134:137], v[194:197], v[26:29]
	v_mfma_f32_16x16x32_bf16 v[54:57], v[122:125], v[216:219], v[54:57]
	v_mfma_f32_16x16x32_bf16 v[22:25], v[134:137], v[216:219], v[22:25]
	v_mfma_f32_16x16x32_bf16 v[50:53], v[122:125], v[224:227], v[50:53]
	v_mfma_f32_16x16x32_bf16 v[18:21], v[134:137], v[224:227], v[18:21]
	s_setprio 0
	s_setprio 1
	v_mfma_f32_16x16x32_bf16 v[142:145], v[146:149], v[164:167], 0
	v_mfma_f32_16x16x32_bf16 v[138:141], v[154:157], v[164:167], 0
	v_mfma_f32_16x16x32_bf16 v[126:129], v[146:149], v[186:189], 0
	v_mfma_f32_16x16x32_bf16 v[118:121], v[154:157], v[186:189], 0
	v_mfma_f32_16x16x32_bf16 v[110:113], v[146:149], v[212:215], 0
	v_mfma_f32_16x16x32_bf16 v[106:109], v[154:157], v[212:215], 0
	v_mfma_f32_16x16x32_bf16 v[102:105], v[146:149], v[220:223], 0
	v_mfma_f32_16x16x32_bf16 v[98:101], v[154:157], v[220:223], 0
	v_mfma_f32_16x16x32_bf16 v[142:145], v[150:153], v[182:185], v[142:145]
	v_mfma_f32_16x16x32_bf16 v[138:141], v[158:161], v[182:185], v[138:141]
	v_mfma_f32_16x16x32_bf16 v[126:129], v[150:153], v[194:197], v[126:129]
	v_mfma_f32_16x16x32_bf16 v[118:121], v[158:161], v[194:197], v[118:121]
	v_mfma_f32_16x16x32_bf16 v[110:113], v[150:153], v[216:219], v[110:113]
	v_mfma_f32_16x16x32_bf16 v[106:109], v[158:161], v[216:219], v[106:109]
	v_mfma_f32_16x16x32_bf16 v[102:105], v[150:153], v[224:227], v[102:105]
	v_mfma_f32_16x16x32_bf16 v[98:101], v[158:161], v[224:227], v[98:101]
	s_setprio 0
	s_barrier
	s_add_i32 s40, s40, s3
	v_lshl_add_u64 v[190:191], s[4:5], 0, v[172:173]
	s_mov_b32 m0, s40
	ds_read_b128 v[164:167], v211 offset:16384
	ds_read_b128 v[182:185], v211 offset:17408
	ds_read_b128 v[186:189], v211 offset:18432
	ds_read_b128 v[194:197], v211 offset:19456
	ds_read_b128 v[212:215], v211 offset:20480
	ds_read_b128 v[216:219], v211 offset:21504
	ds_read_b128 v[220:223], v211 offset:22528
	ds_read_b128 v[224:227], v211 offset:23552
	global_load_lds_dwordx4 v[190:191], off
	s_add_i32 m0, s40, 0x2000
	s_add_u32 s40, s4, 0x40000
	v_lshl_add_u64 v[202:203], s[4:5], 0, v[170:171]
	s_addc_u32 s41, s5, 0
	s_add_i32 s42, s42, s3
	global_load_lds_dwordx4 v[202:203], off
	v_lshl_add_u64 v[228:229], s[40:41], 0, v[172:173]
	s_mov_b32 m0, s42
	v_lshl_add_u64 v[230:231], s[8:9], 0, v[170:171]
	global_load_lds_dwordx4 v[228:229], off
	v_lshl_add_u64 v[228:229], s[40:41], 0, v[170:171]
	s_add_i32 m0, s42, 0x2000
	s_nop 0
	global_load_lds_dwordx4 v[228:229], off
	v_lshl_add_u64 v[228:229], s[8:9], 0, v[172:173]
	s_mov_b32 m0, s24
	s_nop 0
	global_load_lds_dwordx4 v[228:229], off
	s_mov_b32 m0, s25
	s_nop 0
	global_load_lds_dwordx4 v[230:231], off
	s_waitcnt vmcnt(8)
	s_waitcnt lgkmcnt(0)
	s_barrier
; #define PG8_STAGE(bufoff, gbase, voff) do { _Pragma("unroll") for (int _i = 0; _i < 2; ++_i) \
;         __builtin_amdgcn_global_load_lds((const unsigned*)((const char*)(gbase) + (voff)[_i]), (LAS unsigned*)(lds + (bufoff) + ldsw + _i * 8192), 16, 0, 0); } while (0)
; #define PG8_LDA(dst, b, h) do { _Pragma("unroll") for (int m = 0; m < 4; ++m) _Pragma("unroll") for (int k = 0; k < 2; ++k) dst[m][k] = *(const LAS bf16x8*)(lds + PG8_SA(b, h) + aoff + m * 2048 + k * 1024); } while (0)
; #define PG8_LDB(dst, b, h) do { _Pragma("unroll") for (int n = 0; n < 2; ++n) _Pragma("unroll") for (int k = 0; k < 2; ++k) dst[n][k] = *(const LAS bf16x8*)(lds + PG8_SB(b, h) + boff + n * 2048 + k * 1024); } while (0)
; #define PG8_MMA(ai, bj, At, Bt) do { __builtin_amdgcn_s_setprio(1); _Pragma("unroll") for (int m = 0; m < 4; ++m) _Pragma("unroll") for (int n = 0; n < 2; ++n) _Pragma("unroll") for (int k = 0; k < 2; ++k) \
;         acc[ai][bj][m][n] = __builtin_amdgcn_mfma_f32_16x16x32_bf16(Bt[n][k], At[m][k], acc[ai][bj][m][n], 0, 0, 0); __builtin_amdgcn_s_setprio(0); } while (0)
; #define PG8_WAIT_V(n) asm volatile("s_waitcnt vmcnt(" #n ")" ::: "memory")
; #define PG8_WAIT_L(n) asm volatile("s_waitcnt lgkmcnt(" #n ")" ::: "memory")
; #define PG8_BAR __builtin_amdgcn_s_barrier()
; #define PG8_SCHED __builtin_amdgcn_sched_barrier(0)
; template <class Epi, bool ALIGN_EPI = PG8_ALIGN, bool SP2 = PG8_SP2>
; __device__ __forceinline__ void gemm_phase(LAS unsigned char* lds, const Gemm g, const StaticOrder& S, const Epi& E) {
;     ...
;             PG8_WAIT_V(8); PG8_WAIT_L(0); PG8_BAR; PG8_MMA(1, 0, At, B0); PG8_MMA(1, 1, At, B1); PG8_BAR; PG8_SCHED;
;             PG8_LDB(B0, 1, 0); PG8_LDB(B1, 1, 1); PG8_SCHED; PG8_LDA(At, 1, 0); PG8_STAGE(PG8_SA(0, 1), a2 + hstepA, voffA);
;             PG8_WAIT_V(8); PG8_WAIT_L(0); PG8_BAR; PG8_MMA(0, 0, At, B0); PG8_MMA(0, 1, At, B1); PG8_BAR; PG8_SCHED;
	s_setprio 1
	v_mfma_f32_16x16x32_bf16 v[46:49], v[114:117], v[164:167], 0
	v_mfma_f32_16x16x32_bf16 v[14:17], v[130:133], v[164:167], 0
	v_mfma_f32_16x16x32_bf16 v[42:45], v[114:117], v[186:189], 0
	v_mfma_f32_16x16x32_bf16 v[10:13], v[130:133], v[186:189], 0
	v_mfma_f32_16x16x32_bf16 v[38:41], v[114:117], v[212:215], 0
	v_mfma_f32_16x16x32_bf16 v[6:9], v[130:133], v[212:215], 0
	v_mfma_f32_16x16x32_bf16 v[34:37], v[114:117], v[220:223], 0
	v_mfma_f32_16x16x32_bf16 v[2:5], v[130:133], v[220:223], 0
	v_mfma_f32_16x16x32_bf16 v[46:49], v[122:125], v[182:185], v[46:49]
	v_mfma_f32_16x16x32_bf16 v[14:17], v[134:137], v[182:185], v[14:17]
	v_mfma_f32_16x16x32_bf16 v[42:45], v[122:125], v[194:197], v[42:45]
	v_mfma_f32_16x16x32_bf16 v[10:13], v[134:137], v[194:197], v[10:13]
	v_mfma_f32_16x16x32_bf16 v[38:41], v[122:125], v[216:219], v[38:41]
	v_mfma_f32_16x16x32_bf16 v[6:9], v[134:137], v[216:219], v[6:9]
	v_mfma_f32_16x16x32_bf16 v[34:37], v[122:125], v[224:227], v[34:37]
	v_mfma_f32_16x16x32_bf16 v[2:5], v[134:137], v[224:227], v[2:5]
	s_setprio 0
	s_setprio 1
	v_mfma_f32_16x16x32_bf16 v[94:97], v[146:149], v[164:167], 0
	v_mfma_f32_16x16x32_bf16 v[90:93], v[154:157], v[164:167], 0
	v_mfma_f32_16x16x32_bf16 v[86:89], v[146:149], v[186:189], 0
	v_mfma_f32_16x16x32_bf16 v[82:85], v[154:157], v[186:189], 0
	v_mfma_f32_16x16x32_bf16 v[78:81], v[146:149], v[212:215], 0
	v_mfma_f32_16x16x32_bf16 v[74:77], v[154:157], v[212:215], 0
	v_mfma_f32_16x16x32_bf16 v[66:69], v[146:149], v[220:223], 0
	v_mfma_f32_16x16x32_bf16 v[62:65], v[154:157], v[220:223], 0
	v_mfma_f32_16x16x32_bf16 v[94:97], v[150:153], v[182:185], v[94:97]
	v_mfma_f32_16x16x32_bf16 v[90:93], v[158:161], v[182:185], v[90:93]
	v_mfma_f32_16x16x32_bf16 v[86:89], v[150:153], v[194:197], v[86:89]
	v_mfma_f32_16x16x32_bf16 v[82:85], v[158:161], v[194:197], v[82:85]
	v_mfma_f32_16x16x32_bf16 v[78:81], v[150:153], v[216:219], v[78:81]
	v_mfma_f32_16x16x32_bf16 v[74:77], v[158:161], v[216:219], v[74:77]
	v_mfma_f32_16x16x32_bf16 v[66:69], v[150:153], v[224:227], v[66:69]
	v_mfma_f32_16x16x32_bf16 v[62:65], v[158:161], v[224:227], v[62:65]
	s_setprio 0
	s_barrier
	s_add_i32 s40, 0, 0x18000
	v_add_u32_e32 v0, s40, v206
	s_add_i32 s41, 0, 0x1c000
	ds_read_b128 v[114:117], v0
	ds_read_b128 v[122:125], v0 offset:1024
	ds_read_b128 v[130:133], v0 offset:2048
	ds_read_b128 v[134:137], v0 offset:3072
	v_add_u32_e32 v0, s41, v206
	ds_read_b128 v[146:149], v0
	ds_read_b128 v[150:153], v0 offset:1024
	ds_read_b128 v[154:157], v0 offset:2048
	ds_read_b128 v[158:161], v0 offset:3072
	s_add_u32 s8, s8, 0x40000
	s_addc_u32 s9, s9, 0
	s_mov_b32 m0, s26
	v_lshl_add_u64 v[232:233], s[8:9], 0, v[172:173]
	ds_read_b128 v[164:167], v211 offset:32768
	ds_read_b128 v[182:185], v211 offset:33792
	ds_read_b128 v[186:189], v211 offset:34816
	ds_read_b128 v[194:197], v211 offset:35840
	ds_read_b128 v[212:215], v211 offset:36864
	ds_read_b128 v[216:219], v211 offset:37888
	ds_read_b128 v[220:223], v211 offset:38912
	ds_read_b128 v[224:227], v211 offset:39936
	global_load_lds_dwordx4 v[232:233], off
	v_lshl_add_u64 v[232:233], s[8:9], 0, v[170:171]
	s_mov_b32 m0, s27
	s_nop 0
	global_load_lds_dwordx4 v[232:233], off
	s_waitcnt vmcnt(8)
	s_waitcnt lgkmcnt(0)
	s_barrier
	s_setprio 1
	v_mfma_f32_16x16x32_bf16 v[70:73], v[114:117], v[164:167], v[70:73]
	v_mfma_f32_16x16x32_bf16 v[30:33], v[130:133], v[164:167], v[30:33]
	v_mfma_f32_16x16x32_bf16 v[58:61], v[114:117], v[186:189], v[58:61]
	v_mfma_f32_16x16x32_bf16 v[26:29], v[130:133], v[186:189], v[26:29]
	v_mfma_f32_16x16x32_bf16 v[54:57], v[114:117], v[212:215], v[54:57]
	v_mfma_f32_16x16x32_bf16 v[22:25], v[130:133], v[212:215], v[22:25]
	v_mfma_f32_16x16x32_bf16 v[50:53], v[114:117], v[220:223], v[50:53]
	v_mfma_f32_16x16x32_bf16 v[18:21], v[130:133], v[220:223], v[18:21]
	v_mfma_f32_16x16x32_bf16 v[70:73], v[122:125], v[182:185], v[70:73]
	v_mfma_f32_16x16x32_bf16 v[30:33], v[134:137], v[182:185], v[30:33]
	v_mfma_f32_16x16x32_bf16 v[58:61], v[122:125], v[194:197], v[58:61]
	v_mfma_f32_16x16x32_bf16 v[26:29], v[134:137], v[194:197], v[26:29]
	v_mfma_f32_16x16x32_bf16 v[54:57], v[122:125], v[216:219], v[54:57]
	v_mfma_f32_16x16x32_bf16 v[22:25], v[134:137], v[216:219], v[22:25]
	v_mfma_f32_16x16x32_bf16 v[50:53], v[122:125], v[224:227], v[50:53]
	v_mfma_f32_16x16x32_bf16 v[18:21], v[134:137], v[224:227], v[18:21]
	s_setprio 0
	s_setprio 1
	v_mfma_f32_16x16x32_bf16 v[142:145], v[146:149], v[164:167], v[142:145]
	v_mfma_f32_16x16x32_bf16 v[138:141], v[154:157], v[164:167], v[138:141]
	v_mfma_f32_16x16x32_bf16 v[126:129], v[146:149], v[186:189], v[126:129]
	v_mfma_f32_16x16x32_bf16 v[118:121], v[154:157], v[186:189], v[118:121]
	v_mfma_f32_16x16x32_bf16 v[110:113], v[146:149], v[212:215], v[110:113]
	v_mfma_f32_16x16x32_bf16 v[106:109], v[154:157], v[212:215], v[106:109]
	v_mfma_f32_16x16x32_bf16 v[102:105], v[146:149], v[220:223], v[102:105]
	v_mfma_f32_16x16x32_bf16 v[98:101], v[154:157], v[220:223], v[98:101]
	v_mfma_f32_16x16x32_bf16 v[142:145], v[150:153], v[182:185], v[142:145]
	v_mfma_f32_16x16x32_bf16 v[138:141], v[158:161], v[182:185], v[138:141]
	v_mfma_f32_16x16x32_bf16 v[126:129], v[150:153], v[194:197], v[126:129]
	v_mfma_f32_16x16x32_bf16 v[118:121], v[158:161], v[194:197], v[118:121]
	v_mfma_f32_16x16x32_bf16 v[110:113], v[150:153], v[216:219], v[110:113]
	v_mfma_f32_16x16x32_bf16 v[106:109], v[158:161], v[216:219], v[106:109]
	v_mfma_f32_16x16x32_bf16 v[102:105], v[150:153], v[224:227], v[102:105]
	v_mfma_f32_16x16x32_bf16 v[98:101], v[158:161], v[224:227], v[98:101]
	s_setprio 0
	s_barrier
; #define PG8_STAGE(bufoff, gbase, voff) do { _Pragma("unroll") for (int _i = 0; _i < 2; ++_i) \
;         __builtin_amdgcn_global_load_lds((const unsigned*)((const char*)(gbase) + (voff)[_i]), (LAS unsigned*)(lds + (bufoff) + ldsw + _i * 8192), 16, 0, 0); } while (0)
; #define PG8_LDA(dst, b, h) do { _Pragma("unroll") for (int m = 0; m < 4; ++m) _Pragma("unroll") for (int k = 0; k < 2; ++k) dst[m][k] = *(const LAS bf16x8*)(lds + PG8_SA(b, h) + aoff + m * 2048 + k * 1024); } while (0)
; #define PG8_MMA(ai, bj, At, Bt) do { __builtin_amdgcn_s_setprio(1); _Pragma("unroll") for (int m = 0; m < 4; ++m) _Pragma("unroll") for (int n = 0; n < 2; ++n) _Pragma("unroll") for (int k = 0; k < 2; ++k) \
;         acc[ai][bj][m][n] = __builtin_amdgcn_mfma_f32_16x16x32_bf16(Bt[n][k], At[m][k], acc[ai][bj][m][n], 0, 0, 0); __builtin_amdgcn_s_setprio(0); } while (0)
; #define PG8_WAIT_V(n) asm volatile("s_waitcnt vmcnt(" #n ")" ::: "memory")
; #define PG8_WAIT_L(n) asm volatile("s_waitcnt lgkmcnt(" #n ")" ::: "memory")
; #define PG8_BAR __builtin_amdgcn_s_barrier()
; #define PG8_SCHED __builtin_amdgcn_sched_barrier(0)
; template <class Epi, bool ALIGN_EPI = PG8_ALIGN, bool SP2 = PG8_SP2>
; __device__ __forceinline__ void gemm_phase(LAS unsigned char* lds, const Gemm g, const StaticOrder& S, const Epi& E) {
;     ...
;             PG8_LDA(At, 1, 1); PG8_STAGE(PG8_SB(1, 0), b3, voffB); PG8_STAGE(PG8_SB(1, 1), b3 + hstepB, voffB); PG8_STAGE(PG8_SA(1, 0), a3, voffA);
;             PG8_WAIT_V(8); PG8_WAIT_L(0); PG8_BAR; PG8_MMA(1, 0, At, B0); PG8_MMA(1, 1, At, B1); PG8_BAR; PG8_SCHED;
	s_add_i32 s8, s40, s3
	v_lshl_add_u64 v[190:191], v[190:191], 0, s[50:51]
	s_mov_b32 m0, s8
	ds_read_b128 v[164:167], v211 offset:49152
	ds_read_b128 v[182:185], v211 offset:50176
	ds_read_b128 v[186:189], v211 offset:51200
	ds_read_b128 v[194:197], v211 offset:52224
	ds_read_b128 v[212:215], v211 offset:53248
	ds_read_b128 v[216:219], v211 offset:54272
	ds_read_b128 v[220:223], v211 offset:55296
	ds_read_b128 v[224:227], v211 offset:56320
	global_load_lds_dwordx4 v[190:191], off
	s_add_i32 m0, s8, 0x2000
	s_add_u32 s4, s4, 0x40080
	v_lshl_add_u64 v[190:191], v[202:203], 0, s[50:51]
	s_addc_u32 s5, s5, 0
	s_add_i32 s8, s41, s3
	global_load_lds_dwordx4 v[190:191], off
	v_lshl_add_u64 v[190:191], s[4:5], 0, v[172:173]
	s_mov_b32 m0, s8
	s_nop 0
	global_load_lds_dwordx4 v[190:191], off
	v_lshl_add_u64 v[190:191], s[4:5], 0, v[170:171]
	s_add_i32 m0, s8, 0x2000
	s_nop 0
	global_load_lds_dwordx4 v[190:191], off
	v_lshl_add_u64 v[190:191], v[228:229], 0, s[50:51]
	s_mov_b32 m0, s29
	s_nop 0
	global_load_lds_dwordx4 v[190:191], off
	v_lshl_add_u64 v[190:191], v[230:231], 0, s[50:51]
	s_mov_b32 m0, s30
	s_nop 0
	global_load_lds_dwordx4 v[190:191], off
	s_waitcnt vmcnt(8)
	s_waitcnt lgkmcnt(0)
	s_barrier
	s_setprio 1
	v_mfma_f32_16x16x32_bf16 v[46:49], v[114:117], v[164:167], v[46:49]
	v_mfma_f32_16x16x32_bf16 v[14:17], v[130:133], v[164:167], v[14:17]
	v_mfma_f32_16x16x32_bf16 v[42:45], v[114:117], v[186:189], v[42:45]
	v_mfma_f32_16x16x32_bf16 v[10:13], v[130:133], v[186:189], v[10:13]
	v_mfma_f32_16x16x32_bf16 v[38:41], v[114:117], v[212:215], v[38:41]
	v_mfma_f32_16x16x32_bf16 v[6:9], v[130:133], v[212:215], v[6:9]
	v_mfma_f32_16x16x32_bf16 v[34:37], v[114:117], v[220:223], v[34:37]
	v_mfma_f32_16x16x32_bf16 v[2:5], v[130:133], v[220:223], v[2:5]
	v_mfma_f32_16x16x32_bf16 v[46:49], v[122:125], v[182:185], v[46:49]
	v_mfma_f32_16x16x32_bf16 v[14:17], v[134:137], v[182:185], v[14:17]
	v_mfma_f32_16x16x32_bf16 v[42:45], v[122:125], v[194:197], v[42:45]
	v_mfma_f32_16x16x32_bf16 v[10:13], v[134:137], v[194:197], v[10:13]
	v_mfma_f32_16x16x32_bf16 v[38:41], v[122:125], v[216:219], v[38:41]
	v_mfma_f32_16x16x32_bf16 v[6:9], v[134:137], v[216:219], v[6:9]
	v_mfma_f32_16x16x32_bf16 v[34:37], v[122:125], v[224:227], v[34:37]
	v_mfma_f32_16x16x32_bf16 v[2:5], v[134:137], v[224:227], v[2:5]
	s_setprio 0
	s_setprio 1
	v_mfma_f32_16x16x32_bf16 v[94:97], v[146:149], v[164:167], v[94:97]
	v_mfma_f32_16x16x32_bf16 v[90:93], v[154:157], v[164:167], v[90:93]
	v_mfma_f32_16x16x32_bf16 v[86:89], v[146:149], v[186:189], v[86:89]
	v_mfma_f32_16x16x32_bf16 v[82:85], v[154:157], v[186:189], v[82:85]
	v_mfma_f32_16x16x32_bf16 v[78:81], v[146:149], v[212:215], v[78:81]
	v_mfma_f32_16x16x32_bf16 v[74:77], v[154:157], v[212:215], v[74:77]
	v_mfma_f32_16x16x32_bf16 v[66:69], v[146:149], v[220:223], v[66:69]
	v_mfma_f32_16x16x32_bf16 v[62:65], v[154:157], v[220:223], v[62:65]
	v_mfma_f32_16x16x32_bf16 v[94:97], v[150:153], v[182:185], v[94:97]
	v_mfma_f32_16x16x32_bf16 v[90:93], v[158:161], v[182:185], v[90:93]
	v_mfma_f32_16x16x32_bf16 v[86:89], v[150:153], v[194:197], v[86:89]
	v_mfma_f32_16x16x32_bf16 v[82:85], v[158:161], v[194:197], v[82:85]
	v_mfma_f32_16x16x32_bf16 v[78:81], v[150:153], v[216:219], v[78:81]
	v_mfma_f32_16x16x32_bf16 v[74:77], v[158:161], v[216:219], v[74:77]
	v_mfma_f32_16x16x32_bf16 v[66:69], v[150:153], v[224:227], v[66:69]
	v_mfma_f32_16x16x32_bf16 v[62:65], v[158:161], v[224:227], v[62:65]
	s_setprio 0
	s_barrier
	s_add_i32 s39, s39, 2
	s_add_u32 s0, s0, 0x100
	s_addc_u32 s1, s1, 0
	s_add_u32 s37, s37, 0x100
	s_addc_u32 s38, s38, 0
	s_cmp_gt_u32 s39, 13
	s_branch .LBB0_535

; #define PG8_STAGE(bufoff, gbase, voff) do { _Pragma("unroll") for (int _i = 0; _i < 2; ++_i) \
;         __builtin_amdgcn_global_load_lds((const unsigned*)((const char*)(gbase) + (voff)[_i]), (LAS unsigned*)(lds + (bufoff) + ldsw + _i * 8192), 16, 0, 0); } while (0)
; #define PG8_LDA(dst, b, h) do { _Pragma("unroll") for (int m = 0; m < 4; ++m) _Pragma("unroll") for (int k = 0; k < 2; ++k) dst[m][k] = *(const LAS bf16x8*)(lds + PG8_SA(b, h) + aoff + m * 2048 + k * 1024); } while (0)
; #define PG8_LDB(dst, b, h) do { _Pragma("unroll") for (int n = 0; n < 2; ++n) _Pragma("unroll") for (int k = 0; k < 2; ++k) dst[n][k] = *(const LAS bf16x8*)(lds + PG8_SB(b, h) + boff + n * 2048 + k * 1024); } while (0)
; #define PG8_MMA(ai, bj, At, Bt) do { __builtin_amdgcn_s_setprio(1); _Pragma("unroll") for (int m = 0; m < 4; ++m) _Pragma("unroll") for (int n = 0; n < 2; ++n) _Pragma("unroll") for (int k = 0; k < 2; ++k) \
;         acc[ai][bj][m][n] = __builtin_amdgcn_mfma_f32_16x16x32_bf16(Bt[n][k], At[m][k], acc[ai][bj][m][n], 0, 0, 0); __builtin_amdgcn_s_setprio(0); } while (0)
; #define PG8_WAIT_V(n) asm volatile("s_waitcnt vmcnt(" #n ")" ::: "memory")
; #define PG8_WAIT_L(n) asm volatile("s_waitcnt lgkmcnt(" #n ")" ::: "memory")
; #define PG8_BAR __builtin_amdgcn_s_barrier()
; #define PG8_SCHED __builtin_amdgcn_sched_barrier(0)
; template <class Epi, bool ALIGN_EPI = PG8_ALIGN, bool SP2 = PG8_SP2>
; __device__ __forceinline__ void gemm_phase(LAS unsigned char* lds, const Gemm g, const StaticOrder& S, const Epi& E) {
;     ...
;             const bool last = (t == nt - 2);
;             const char* a1 = cA + (size_t)(t + 1) * kstepA;
;             const char* a2 = last ? nA : cA + (size_t)(t + 2) * kstepA; const char* b2 = last ? nB : cB + (size_t)(t + 2) * kstepB;
;             const char* a3 = a2 + kstepA; const char* b3 = b2 + kstepB;
;             if constexpr (SP2) {
;             PG8_LDB(B0, 0, 0); PG8_LDB(B1, 0, 1); PG8_SCHED; PG8_LDA(At, 0, 0); PG8_STAGE(PG8_SA(1, 1), a1 + hstepA, voffA);
;             PG8_WAIT_V(8); PG8_WAIT_L(0); PG8_BAR; PG8_MMA(0, 0, At, B0); PG8_MMA(0, 1, At, B1); PG8_BAR; PG8_SCHED;
;             PG8_LDA(At, 0, 1); PG8_STAGE(PG8_SB(0, 0), b2, voffB); PG8_STAGE(PG8_SB(0, 1), b2 + hstepB, voffB); PG8_STAGE(PG8_SA(0, 0), a2, voffA);
;             PG8_WAIT_V(8); PG8_WAIT_L(0); PG8_BAR; PG8_MMA(1, 0, At, B0); PG8_MMA(1, 1, At, B1); PG8_BAR; PG8_SCHED;
.LBB0_583:
	s_cmp_eq_u32 s28, 0
	s_cbranch_scc1 .Lfirst_iter_u583
	s_add_u32 s74, s28, 1
	s_addc_u32 s75, s29, 0
	s_add_u32 s30, s28, 2
	s_addc_u32 s31, s29, 0
	s_lshl_b64 s[34:35], s[30:31], s56
	s_add_u32 s29, s26, s34
	s_addc_u32 s36, s27, s35
	s_add_u32 s34, s24, s34
	s_addc_u32 s35, s25, s35
	s_cmp_eq_u32 s66, s28
	s_cselect_b32 s37, s21, s36
	s_cselect_b32 s36, s20, s29
	s_cselect_b32 s34, s22, s34
	s_cselect_b32 s35, s23, s35
	s_add_u32 s28, s36, s52
	s_addc_u32 s29, s37, 0
	s_add_i32 s73, 0, 0x10000
	s_add_i32 s76, 0, 0x14000
	v_add_u32_e32 v144, s73, v155
	v_add_u32_e32 v152, s76, v155
	ds_read_b128 v[132:135], v144
	ds_read_b128 v[136:139], v144 offset:1024
	ds_read_b128 v[140:143], v144 offset:2048
	ds_read_b128 v[144:147], v144 offset:3072
	ds_read_b128 v[148:151], v152
	ds_read_b128 v[158:161], v152 offset:1024
	ds_read_b128 v[170:173], v152 offset:2048
	ds_read_b128 v[174:177], v152 offset:3072
	s_lshl_b64 s[74:75], s[74:75], s56
	s_add_u32 s74, s71, s74
	s_addc_u32 s75, s72, s75
	v_lshl_add_u64 v[152:153], s[74:75], 0, v[0:1]
	s_add_i32 m0, s41, 0xc000
	ds_read_b128 v[178:181], v157
	ds_read_b128 v[182:185], v157 offset:1024
	ds_read_b128 v[186:189], v157 offset:2048
	ds_read_b128 v[206:209], v157 offset:3072
	ds_read_b128 v[210:213], v157 offset:4096
	ds_read_b128 v[214:217], v157 offset:5120
	ds_read_b128 v[218:221], v157 offset:6144
	ds_read_b128 v[222:225], v157 offset:7168
	global_load_lds_dwordx4 v[152:153], off
	v_lshl_add_u64 v[152:153], s[74:75], 0, v[130:131]
	s_add_i32 m0, s41, 0xe000
	s_nop 0
	global_load_lds_dwordx4 v[152:153], off
	s_waitcnt vmcnt(8)
	s_waitcnt lgkmcnt(0)
	s_barrier
	s_setprio 1
	v_mfma_f32_16x16x32_bf16 v[126:129], v[132:135], v[178:181], v[126:129]
	v_mfma_f32_16x16x32_bf16 v[122:125], v[140:143], v[178:181], v[122:125]
	v_mfma_f32_16x16x32_bf16 v[118:121], v[132:135], v[186:189], v[118:121]
	v_mfma_f32_16x16x32_bf16 v[114:117], v[140:143], v[186:189], v[114:117]
	v_mfma_f32_16x16x32_bf16 v[110:113], v[132:135], v[210:213], v[110:113]
	v_mfma_f32_16x16x32_bf16 v[90:93], v[140:143], v[210:213], v[90:93]
	v_mfma_f32_16x16x32_bf16 v[86:89], v[132:135], v[218:221], v[86:89]
	v_mfma_f32_16x16x32_bf16 v[78:81], v[140:143], v[218:221], v[78:81]
	v_mfma_f32_16x16x32_bf16 v[126:129], v[136:139], v[182:185], v[126:129]
	v_mfma_f32_16x16x32_bf16 v[122:125], v[144:147], v[182:185], v[122:125]
	v_mfma_f32_16x16x32_bf16 v[118:121], v[136:139], v[206:209], v[118:121]
	v_mfma_f32_16x16x32_bf16 v[114:117], v[144:147], v[206:209], v[114:117]
	v_mfma_f32_16x16x32_bf16 v[110:113], v[136:139], v[214:217], v[110:113]
	v_mfma_f32_16x16x32_bf16 v[90:93], v[144:147], v[214:217], v[90:93]
	v_mfma_f32_16x16x32_bf16 v[86:89], v[136:139], v[222:225], v[86:89]
	v_mfma_f32_16x16x32_bf16 v[78:81], v[144:147], v[222:225], v[78:81]
	s_setprio 0
	s_setprio 1
	v_mfma_f32_16x16x32_bf16 v[106:109], v[148:151], v[178:181], v[106:109]
	v_mfma_f32_16x16x32_bf16 v[102:105], v[170:173], v[178:181], v[102:105]
	v_mfma_f32_16x16x32_bf16 v[98:101], v[148:151], v[186:189], v[98:101]
	v_mfma_f32_16x16x32_bf16 v[94:97], v[170:173], v[186:189], v[94:97]
	v_mfma_f32_16x16x32_bf16 v[82:85], v[148:151], v[210:213], v[82:85]
	v_mfma_f32_16x16x32_bf16 v[74:77], v[170:173], v[210:213], v[74:77]
	v_mfma_f32_16x16x32_bf16 v[70:73], v[148:151], v[218:221], v[70:73]
	v_mfma_f32_16x16x32_bf16 v[66:69], v[170:173], v[218:221], v[66:69]
	v_mfma_f32_16x16x32_bf16 v[106:109], v[158:161], v[182:185], v[106:109]
	v_mfma_f32_16x16x32_bf16 v[102:105], v[174:177], v[182:185], v[102:105]
	v_mfma_f32_16x16x32_bf16 v[98:101], v[158:161], v[206:209], v[98:101]
	v_mfma_f32_16x16x32_bf16 v[94:97], v[174:177], v[206:209], v[94:97]
	v_mfma_f32_16x16x32_bf16 v[82:85], v[158:161], v[214:217], v[82:85]
	v_mfma_f32_16x16x32_bf16 v[74:77], v[174:177], v[214:217], v[74:77]
	v_mfma_f32_16x16x32_bf16 v[70:73], v[158:161], v[222:225], v[70:73]
	v_mfma_f32_16x16x32_bf16 v[66:69], v[174:177], v[222:225], v[66:69]
	s_setprio 0
	s_barrier
	s_add_i32 s73, s73, s40
	v_lshl_add_u64 v[152:153], s[34:35], 0, v[0:1]
	s_mov_b32 m0, s73
	ds_read_b128 v[178:181], v157 offset:16384
	ds_read_b128 v[182:185], v157 offset:17408
	ds_read_b128 v[186:189], v157 offset:18432
	ds_read_b128 v[206:209], v157 offset:19456
	ds_read_b128 v[210:213], v157 offset:20480
	ds_read_b128 v[214:217], v157 offset:21504
	ds_read_b128 v[218:221], v157 offset:22528
	ds_read_b128 v[222:225], v157 offset:23552
	global_load_lds_dwordx4 v[152:153], off
	s_add_i32 m0, s73, 0x2000
	s_add_u32 s74, s34, s38
	v_lshl_add_u64 v[152:153], s[34:35], 0, v[130:131]
	s_addc_u32 s75, s35, s33
	s_add_i32 s73, s76, s40
	global_load_lds_dwordx4 v[152:153], off
	v_lshl_add_u64 v[152:153], s[74:75], 0, v[0:1]
	s_mov_b32 m0, s73
	s_nop 0
	global_load_lds_dwordx4 v[152:153], off
	v_lshl_add_u64 v[152:153], s[74:75], 0, v[130:131]
	s_add_i32 m0, s73, 0x2000
	s_nop 0
	global_load_lds_dwordx4 v[152:153], off
	v_lshl_add_u64 v[152:153], s[36:37], 0, v[0:1]
	s_mov_b32 m0, s41
	s_nop 0
	global_load_lds_dwordx4 v[152:153], off
	v_lshl_add_u64 v[152:153], s[36:37], 0, v[130:131]
	s_mov_b32 m0, s42
	s_nop 0
	global_load_lds_dwordx4 v[152:153], off
	s_waitcnt vmcnt(8)
	s_waitcnt lgkmcnt(0)
	s_barrier
; #define PG8_STAGE(bufoff, gbase, voff) do { _Pragma("unroll") for (int _i = 0; _i < 2; ++_i) \
;         __builtin_amdgcn_global_load_lds((const unsigned*)((const char*)(gbase) + (voff)[_i]), (LAS unsigned*)(lds + (bufoff) + ldsw + _i * 8192), 16, 0, 0); } while (0)
; #define PG8_LDA(dst, b, h) do { _Pragma("unroll") for (int m = 0; m < 4; ++m) _Pragma("unroll") for (int k = 0; k < 2; ++k) dst[m][k] = *(const LAS bf16x8*)(lds + PG8_SA(b, h) + aoff + m * 2048 + k * 1024); } while (0)
; #define PG8_LDB(dst, b, h) do { _Pragma("unroll") for (int n = 0; n < 2; ++n) _Pragma("unroll") for (int k = 0; k < 2; ++k) dst[n][k] = *(const LAS bf16x8*)(lds + PG8_SB(b, h) + boff + n * 2048 + k * 1024); } while (0)
; #define PG8_MMA(ai, bj, At, Bt) do { __builtin_amdgcn_s_setprio(1); _Pragma("unroll") for (int m = 0; m < 4; ++m) _Pragma("unroll") for (int n = 0; n < 2; ++n) _Pragma("unroll") for (int k = 0; k < 2; ++k) \
;         acc[ai][bj][m][n] = __builtin_amdgcn_mfma_f32_16x16x32_bf16(Bt[n][k], At[m][k], acc[ai][bj][m][n], 0, 0, 0); __builtin_amdgcn_s_setprio(0); } while (0)
; #define PG8_WAIT_V(n) asm volatile("s_waitcnt vmcnt(" #n ")" ::: "memory")
; #define PG8_WAIT_L(n) asm volatile("s_waitcnt lgkmcnt(" #n ")" ::: "memory")
; #define PG8_BAR __builtin_amdgcn_s_barrier()
; #define PG8_SCHED __builtin_amdgcn_sched_barrier(0)
; template <class Epi, bool ALIGN_EPI = PG8_ALIGN, bool SP2 = PG8_SP2>
; __device__ __forceinline__ void gemm_phase(LAS unsigned char* lds, const Gemm g, const StaticOrder& S, const Epi& E) {
;     ...
;             PG8_WAIT_V(8); PG8_WAIT_L(0); PG8_BAR; PG8_MMA(1, 0, At, B0); PG8_MMA(1, 1, At, B1); PG8_BAR; PG8_SCHED;
;             PG8_LDB(B0, 1, 0); PG8_LDB(B1, 1, 1); PG8_SCHED; PG8_LDA(At, 1, 0); PG8_STAGE(PG8_SA(0, 1), a2 + hstepA, voffA);
;             PG8_WAIT_V(8); PG8_WAIT_L(0); PG8_BAR; PG8_MMA(0, 0, At, B0); PG8_MMA(0, 1, At, B1); PG8_BAR; PG8_SCHED;
	s_setprio 1
	v_mfma_f32_16x16x32_bf16 v[62:65], v[132:135], v[178:181], v[62:65]
	v_mfma_f32_16x16x32_bf16 v[58:61], v[140:143], v[178:181], v[58:61]
	v_mfma_f32_16x16x32_bf16 v[54:57], v[132:135], v[186:189], v[54:57]
	v_mfma_f32_16x16x32_bf16 v[50:53], v[140:143], v[186:189], v[50:53]
	v_mfma_f32_16x16x32_bf16 v[46:49], v[132:135], v[210:213], v[46:49]
	v_mfma_f32_16x16x32_bf16 v[34:37], v[140:143], v[210:213], v[34:37]
	v_mfma_f32_16x16x32_bf16 v[18:21], v[132:135], v[218:221], v[18:21]
	v_mfma_f32_16x16x32_bf16 v[14:17], v[140:143], v[218:221], v[14:17]
	v_mfma_f32_16x16x32_bf16 v[62:65], v[136:139], v[182:185], v[62:65]
	v_mfma_f32_16x16x32_bf16 v[58:61], v[144:147], v[182:185], v[58:61]
	v_mfma_f32_16x16x32_bf16 v[54:57], v[136:139], v[206:209], v[54:57]
	v_mfma_f32_16x16x32_bf16 v[50:53], v[144:147], v[206:209], v[50:53]
	v_mfma_f32_16x16x32_bf16 v[46:49], v[136:139], v[214:217], v[46:49]
	v_mfma_f32_16x16x32_bf16 v[34:37], v[144:147], v[214:217], v[34:37]
	v_mfma_f32_16x16x32_bf16 v[18:21], v[136:139], v[222:225], v[18:21]
	v_mfma_f32_16x16x32_bf16 v[14:17], v[144:147], v[222:225], v[14:17]
	s_setprio 0
	s_setprio 1
	v_mfma_f32_16x16x32_bf16 v[42:45], v[148:151], v[178:181], v[42:45]
	v_mfma_f32_16x16x32_bf16 v[38:41], v[170:173], v[178:181], v[38:41]
	v_mfma_f32_16x16x32_bf16 v[30:33], v[148:151], v[186:189], v[30:33]
	v_mfma_f32_16x16x32_bf16 v[26:29], v[170:173], v[186:189], v[26:29]
	v_mfma_f32_16x16x32_bf16 v[22:25], v[148:151], v[210:213], v[22:25]
	v_mfma_f32_16x16x32_bf16 v[10:13], v[170:173], v[210:213], v[10:13]
	v_mfma_f32_16x16x32_bf16 v[6:9], v[148:151], v[218:221], v[6:9]
	v_mfma_f32_16x16x32_bf16 v[2:5], v[170:173], v[218:221], v[2:5]
	v_mfma_f32_16x16x32_bf16 v[42:45], v[158:161], v[182:185], v[42:45]
	v_mfma_f32_16x16x32_bf16 v[38:41], v[174:177], v[182:185], v[38:41]
	v_mfma_f32_16x16x32_bf16 v[30:33], v[158:161], v[206:209], v[30:33]
	v_mfma_f32_16x16x32_bf16 v[26:29], v[174:177], v[206:209], v[26:29]
	v_mfma_f32_16x16x32_bf16 v[22:25], v[158:161], v[214:217], v[22:25]
	v_mfma_f32_16x16x32_bf16 v[10:13], v[174:177], v[214:217], v[10:13]
	v_mfma_f32_16x16x32_bf16 v[6:9], v[158:161], v[222:225], v[6:9]
	v_mfma_f32_16x16x32_bf16 v[2:5], v[174:177], v[222:225], v[2:5]
	s_setprio 0
	s_barrier
	s_add_i32 s73, 0, 0x18000
	s_add_i32 s74, 0, 0x1c000
	v_add_u32_e32 v144, s73, v155
	v_add_u32_e32 v152, s74, v155
	ds_read_b128 v[132:135], v144
	ds_read_b128 v[136:139], v144 offset:1024
	ds_read_b128 v[140:143], v144 offset:2048
	ds_read_b128 v[144:147], v144 offset:3072
	ds_read_b128 v[148:151], v152
	ds_read_b128 v[158:161], v152 offset:1024
	ds_read_b128 v[170:173], v152 offset:2048
	ds_read_b128 v[174:177], v152 offset:3072
	s_add_u32 s36, s36, s38
	s_addc_u32 s37, s37, s33
	s_mov_b32 m0, s43
	v_lshl_add_u64 v[152:153], s[36:37], 0, v[0:1]
	ds_read_b128 v[178:181], v157 offset:32768
	ds_read_b128 v[182:185], v157 offset:33792
	ds_read_b128 v[186:189], v157 offset:34816
	ds_read_b128 v[206:209], v157 offset:35840
	ds_read_b128 v[210:213], v157 offset:36864
	ds_read_b128 v[214:217], v157 offset:37888
	ds_read_b128 v[218:221], v157 offset:38912
	ds_read_b128 v[222:225], v157 offset:39936
	global_load_lds_dwordx4 v[152:153], off
	v_lshl_add_u64 v[152:153], s[36:37], 0, v[130:131]
	s_mov_b32 m0, s44
	s_nop 0
	global_load_lds_dwordx4 v[152:153], off
	s_waitcnt vmcnt(8)
	s_waitcnt lgkmcnt(0)
	s_barrier
	s_setprio 1
	v_mfma_f32_16x16x32_bf16 v[126:129], v[132:135], v[178:181], v[126:129]
	v_mfma_f32_16x16x32_bf16 v[122:125], v[140:143], v[178:181], v[122:125]
	v_mfma_f32_16x16x32_bf16 v[118:121], v[132:135], v[186:189], v[118:121]
	v_mfma_f32_16x16x32_bf16 v[114:117], v[140:143], v[186:189], v[114:117]
	v_mfma_f32_16x16x32_bf16 v[110:113], v[132:135], v[210:213], v[110:113]
	v_mfma_f32_16x16x32_bf16 v[90:93], v[140:143], v[210:213], v[90:93]
	v_mfma_f32_16x16x32_bf16 v[86:89], v[132:135], v[218:221], v[86:89]
	v_mfma_f32_16x16x32_bf16 v[78:81], v[140:143], v[218:221], v[78:81]
	v_mfma_f32_16x16x32_bf16 v[126:129], v[136:139], v[182:185], v[126:129]
	v_mfma_f32_16x16x32_bf16 v[122:125], v[144:147], v[182:185], v[122:125]
	v_mfma_f32_16x16x32_bf16 v[118:121], v[136:139], v[206:209], v[118:121]
	v_mfma_f32_16x16x32_bf16 v[114:117], v[144:147], v[206:209], v[114:117]
	v_mfma_f32_16x16x32_bf16 v[110:113], v[136:139], v[214:217], v[110:113]
	v_mfma_f32_16x16x32_bf16 v[90:93], v[144:147], v[214:217], v[90:93]
	v_mfma_f32_16x16x32_bf16 v[86:89], v[136:139], v[222:225], v[86:89]
	v_mfma_f32_16x16x32_bf16 v[78:81], v[144:147], v[222:225], v[78:81]
	s_setprio 0
	s_setprio 1
	v_mfma_f32_16x16x32_bf16 v[106:109], v[148:151], v[178:181], v[106:109]
	v_mfma_f32_16x16x32_bf16 v[102:105], v[170:173], v[178:181], v[102:105]
	v_mfma_f32_16x16x32_bf16 v[98:101], v[148:151], v[186:189], v[98:101]
	v_mfma_f32_16x16x32_bf16 v[94:97], v[170:173], v[186:189], v[94:97]
	v_mfma_f32_16x16x32_bf16 v[82:85], v[148:151], v[210:213], v[82:85]
	v_mfma_f32_16x16x32_bf16 v[74:77], v[170:173], v[210:213], v[74:77]
	v_mfma_f32_16x16x32_bf16 v[70:73], v[148:151], v[218:221], v[70:73]
	v_mfma_f32_16x16x32_bf16 v[66:69], v[170:173], v[218:221], v[66:69]
	v_mfma_f32_16x16x32_bf16 v[106:109], v[158:161], v[182:185], v[106:109]
	v_mfma_f32_16x16x32_bf16 v[102:105], v[174:177], v[182:185], v[102:105]
	v_mfma_f32_16x16x32_bf16 v[98:101], v[158:161], v[206:209], v[98:101]
	v_mfma_f32_16x16x32_bf16 v[94:97], v[174:177], v[206:209], v[94:97]
	v_mfma_f32_16x16x32_bf16 v[82:85], v[158:161], v[214:217], v[82:85]
	v_mfma_f32_16x16x32_bf16 v[74:77], v[174:177], v[214:217], v[74:77]
	v_mfma_f32_16x16x32_bf16 v[70:73], v[158:161], v[222:225], v[70:73]
	v_mfma_f32_16x16x32_bf16 v[66:69], v[174:177], v[222:225], v[66:69]
	s_setprio 0
	s_barrier
; #define PG8_STAGE(bufoff, gbase, voff) do { _Pragma("unroll") for (int _i = 0; _i < 2; ++_i) \
;         __builtin_amdgcn_global_load_lds((const unsigned*)((const char*)(gbase) + (voff)[_i]), (LAS unsigned*)(lds + (bufoff) + ldsw + _i * 8192), 16, 0, 0); } while (0)
; #define PG8_LDA(dst, b, h) do { _Pragma("unroll") for (int m = 0; m < 4; ++m) _Pragma("unroll") for (int k = 0; k < 2; ++k) dst[m][k] = *(const LAS bf16x8*)(lds + PG8_SA(b, h) + aoff + m * 2048 + k * 1024); } while (0)
; #define PG8_MMA(ai, bj, At, Bt) do { __builtin_amdgcn_s_setprio(1); _Pragma("unroll") for (int m = 0; m < 4; ++m) _Pragma("unroll") for (int n = 0; n < 2; ++n) _Pragma("unroll") for (int k = 0; k < 2; ++k) \
;         acc[ai][bj][m][n] = __builtin_amdgcn_mfma_f32_16x16x32_bf16(Bt[n][k], At[m][k], acc[ai][bj][m][n], 0, 0, 0); __builtin_amdgcn_s_setprio(0); } while (0)
; #define PG8_WAIT_V(n) asm volatile("s_waitcnt vmcnt(" #n ")" ::: "memory")
; #define PG8_WAIT_L(n) asm volatile("s_waitcnt lgkmcnt(" #n ")" ::: "memory")
; #define PG8_BAR __builtin_amdgcn_s_barrier()
; #define PG8_SCHED __builtin_amdgcn_sched_barrier(0)
; template <class Epi, bool ALIGN_EPI = PG8_ALIGN, bool SP2 = PG8_SP2>
; __device__ __forceinline__ void gemm_phase(LAS unsigned char* lds, const Gemm g, const StaticOrder& S, const Epi& E) {
;     ...
;             PG8_LDA(At, 1, 1); PG8_STAGE(PG8_SB(1, 0), b3, voffB); PG8_STAGE(PG8_SB(1, 1), b3 + hstepB, voffB); PG8_STAGE(PG8_SA(1, 0), a3, voffA);
;             PG8_WAIT_V(8); PG8_WAIT_L(0); PG8_BAR; PG8_MMA(1, 0, At, B0); PG8_MMA(1, 1, At, B1); PG8_BAR; PG8_SCHED;
;     ...
;         if constexpr (ALIGN_EPI) { if (wr == 0) PG8_BAR; }
	s_add_u32 s34, s34, s52
	s_addc_u32 s35, s35, 0
	s_add_i32 s36, s73, s40
	v_lshl_add_u64 v[152:153], s[34:35], 0, v[0:1]
	s_mov_b32 m0, s36
	ds_read_b128 v[178:181], v157 offset:49152
	ds_read_b128 v[182:185], v157 offset:50176
	ds_read_b128 v[186:189], v157 offset:51200
	ds_read_b128 v[206:209], v157 offset:52224
	ds_read_b128 v[210:213], v157 offset:53248
	ds_read_b128 v[214:217], v157 offset:54272
	ds_read_b128 v[218:221], v157 offset:55296
	ds_read_b128 v[222:225], v157 offset:56320
	global_load_lds_dwordx4 v[152:153], off
	s_add_i32 m0, s36, 0x2000
	v_lshl_add_u64 v[152:153], s[34:35], 0, v[130:131]
	s_add_u32 s34, s34, s38
	s_addc_u32 s35, s35, s33
	s_add_i32 s36, s74, s40
	global_load_lds_dwordx4 v[152:153], off
	v_lshl_add_u64 v[152:153], s[34:35], 0, v[0:1]
	s_mov_b32 m0, s36
	s_nop 0
	global_load_lds_dwordx4 v[152:153], off
	v_lshl_add_u64 v[152:153], s[34:35], 0, v[130:131]
	s_add_i32 m0, s36, 0x2000
	s_nop 0
	global_load_lds_dwordx4 v[152:153], off
	v_lshl_add_u64 v[152:153], s[28:29], 0, v[0:1]
	s_mov_b32 m0, s53
	s_nop 0
	global_load_lds_dwordx4 v[152:153], off
	v_lshl_add_u64 v[152:153], s[28:29], 0, v[130:131]
	s_mov_b32 m0, s54
	s_nop 0
	global_load_lds_dwordx4 v[152:153], off
	s_waitcnt vmcnt(8)
	s_waitcnt lgkmcnt(0)
	s_barrier
	s_setprio 1
	v_mfma_f32_16x16x32_bf16 v[62:65], v[132:135], v[178:181], v[62:65]
	v_mfma_f32_16x16x32_bf16 v[58:61], v[140:143], v[178:181], v[58:61]
	v_mfma_f32_16x16x32_bf16 v[54:57], v[132:135], v[186:189], v[54:57]
	v_mfma_f32_16x16x32_bf16 v[50:53], v[140:143], v[186:189], v[50:53]
	v_mfma_f32_16x16x32_bf16 v[46:49], v[132:135], v[210:213], v[46:49]
	v_mfma_f32_16x16x32_bf16 v[34:37], v[140:143], v[210:213], v[34:37]
	v_mfma_f32_16x16x32_bf16 v[18:21], v[132:135], v[218:221], v[18:21]
	v_mfma_f32_16x16x32_bf16 v[14:17], v[140:143], v[218:221], v[14:17]
	v_mfma_f32_16x16x32_bf16 v[62:65], v[136:139], v[182:185], v[62:65]
	v_mfma_f32_16x16x32_bf16 v[58:61], v[144:147], v[182:185], v[58:61]
	v_mfma_f32_16x16x32_bf16 v[54:57], v[136:139], v[206:209], v[54:57]
	v_mfma_f32_16x16x32_bf16 v[50:53], v[144:147], v[206:209], v[50:53]
	v_mfma_f32_16x16x32_bf16 v[46:49], v[136:139], v[214:217], v[46:49]
	v_mfma_f32_16x16x32_bf16 v[34:37], v[144:147], v[214:217], v[34:37]
	v_mfma_f32_16x16x32_bf16 v[18:21], v[136:139], v[222:225], v[18:21]
	v_mfma_f32_16x16x32_bf16 v[14:17], v[144:147], v[222:225], v[14:17]
	s_setprio 0
	s_setprio 1
	v_mfma_f32_16x16x32_bf16 v[42:45], v[148:151], v[178:181], v[42:45]
	v_mfma_f32_16x16x32_bf16 v[38:41], v[170:173], v[178:181], v[38:41]
	v_mfma_f32_16x16x32_bf16 v[30:33], v[148:151], v[186:189], v[30:33]
	v_mfma_f32_16x16x32_bf16 v[26:29], v[170:173], v[186:189], v[26:29]
	v_mfma_f32_16x16x32_bf16 v[22:25], v[148:151], v[210:213], v[22:25]
	v_mfma_f32_16x16x32_bf16 v[10:13], v[170:173], v[210:213], v[10:13]
	v_mfma_f32_16x16x32_bf16 v[6:9], v[148:151], v[218:221], v[6:9]
	v_mfma_f32_16x16x32_bf16 v[2:5], v[170:173], v[218:221], v[2:5]
	v_mfma_f32_16x16x32_bf16 v[42:45], v[158:161], v[182:185], v[42:45]
	v_mfma_f32_16x16x32_bf16 v[38:41], v[174:177], v[182:185], v[38:41]
	v_mfma_f32_16x16x32_bf16 v[30:33], v[158:161], v[206:209], v[30:33]
	v_mfma_f32_16x16x32_bf16 v[26:29], v[174:177], v[206:209], v[26:29]
	v_mfma_f32_16x16x32_bf16 v[22:25], v[158:161], v[214:217], v[22:25]
	v_mfma_f32_16x16x32_bf16 v[10:13], v[174:177], v[214:217], v[10:13]
	v_mfma_f32_16x16x32_bf16 v[6:9], v[158:161], v[222:225], v[6:9]
	v_mfma_f32_16x16x32_bf16 v[2:5], v[174:177], v[222:225], v[2:5]
	s_setprio 0
	s_barrier
	s_cmp_ge_u32 s30, s49
	s_mov_b64 s[28:29], s[30:31]
	s_cbranch_scc0 .LBB0_583
	s_and_b64 vcc, exec, s[18:19]
	s_cbranch_vccz .LBB0_586
	s_barrier

; #define PG8_STAGE(bufoff, gbase, voff) do { _Pragma("unroll") for (int _i = 0; _i < 2; ++_i) \
;         __builtin_amdgcn_global_load_lds((const unsigned*)((const char*)(gbase) + (voff)[_i]), (LAS unsigned*)(lds + (bufoff) + ldsw + _i * 8192), 16, 0, 0); } while (0)
; #define PG8_LDA(dst, b, h) do { _Pragma("unroll") for (int m = 0; m < 4; ++m) _Pragma("unroll") for (int k = 0; k < 2; ++k) dst[m][k] = *(const LAS bf16x8*)(lds + PG8_SA(b, h) + aoff + m * 2048 + k * 1024); } while (0)
; #define PG8_LDB(dst, b, h) do { _Pragma("unroll") for (int n = 0; n < 2; ++n) _Pragma("unroll") for (int k = 0; k < 2; ++k) dst[n][k] = *(const LAS bf16x8*)(lds + PG8_SB(b, h) + boff + n * 2048 + k * 1024); } while (0)
; #define PG8_MMA(ai, bj, At, Bt) do { __builtin_amdgcn_s_setprio(1); _Pragma("unroll") for (int m = 0; m < 4; ++m) _Pragma("unroll") for (int n = 0; n < 2; ++n) _Pragma("unroll") for (int k = 0; k < 2; ++k) \
;         acc[ai][bj][m][n] = __builtin_amdgcn_mfma_f32_16x16x32_bf16(Bt[n][k], At[m][k], acc[ai][bj][m][n], 0, 0, 0); __builtin_amdgcn_s_setprio(0); } while (0)
; #define PG8_WAIT_V(n) asm volatile("s_waitcnt vmcnt(" #n ")" ::: "memory")
; #define PG8_WAIT_L(n) asm volatile("s_waitcnt lgkmcnt(" #n ")" ::: "memory")
; #define PG8_BAR __builtin_amdgcn_s_barrier()
; #define PG8_SCHED __builtin_amdgcn_sched_barrier(0)
; template <class Epi, bool ALIGN_EPI = PG8_ALIGN, bool SP2 = PG8_SP2>
; __device__ __forceinline__ void gemm_phase(LAS unsigned char* lds, const Gemm g, const StaticOrder& S, const Epi& E) {
;     ...
;             const bool last = (t == nt - 2);
;             const char* a1 = cA + (size_t)(t + 1) * kstepA;
;             const char* a2 = last ? nA : cA + (size_t)(t + 2) * kstepA; const char* b2 = last ? nB : cB + (size_t)(t + 2) * kstepB;
;             const char* a3 = a2 + kstepA; const char* b3 = b2 + kstepB;
;             if constexpr (SP2) {
;             PG8_LDB(B0, 0, 0); PG8_LDB(B1, 0, 1); PG8_SCHED; PG8_LDA(At, 0, 0); PG8_STAGE(PG8_SA(1, 1), a1 + hstepA, voffA);
;             PG8_WAIT_V(8); PG8_WAIT_L(0); PG8_BAR; PG8_MMA(0, 0, At, B0); PG8_MMA(0, 1, At, B1); PG8_BAR; PG8_SCHED;
;             PG8_LDA(At, 0, 1); PG8_STAGE(PG8_SB(0, 0), b2, voffB); PG8_STAGE(PG8_SB(0, 1), b2 + hstepB, voffB); PG8_STAGE(PG8_SA(0, 0), a2, voffA);
;             PG8_WAIT_V(8); PG8_WAIT_L(0); PG8_BAR; PG8_MMA(1, 0, At, B0); PG8_MMA(1, 1, At, B1); PG8_BAR; PG8_SCHED;
.Lfirst_iter_u583:
	s_add_u32 s74, s28, 1
	s_addc_u32 s75, s29, 0
	s_add_u32 s30, s28, 2
	s_addc_u32 s31, s29, 0
	s_lshl_b64 s[34:35], s[30:31], s56
	s_add_u32 s29, s26, s34
	s_addc_u32 s36, s27, s35
	s_add_u32 s34, s24, s34
	s_addc_u32 s35, s25, s35
	s_cmp_eq_u32 s66, s28
	s_cselect_b32 s37, s21, s36
	s_cselect_b32 s36, s20, s29
	s_cselect_b32 s34, s22, s34
	s_cselect_b32 s35, s23, s35
	s_add_u32 s28, s36, s52
	s_addc_u32 s29, s37, 0
	s_add_i32 s73, 0, 0x10000
	s_add_i32 s76, 0, 0x14000
	v_add_u32_e32 v144, s73, v155
	v_add_u32_e32 v152, s76, v155
	ds_read_b128 v[132:135], v144
	ds_read_b128 v[136:139], v144 offset:1024
	ds_read_b128 v[140:143], v144 offset:2048
	ds_read_b128 v[144:147], v144 offset:3072
	ds_read_b128 v[148:151], v152
	ds_read_b128 v[158:161], v152 offset:1024
	ds_read_b128 v[170:173], v152 offset:2048
	ds_read_b128 v[174:177], v152 offset:3072
	s_lshl_b64 s[74:75], s[74:75], s56
	s_add_u32 s74, s71, s74
	s_addc_u32 s75, s72, s75
	v_lshl_add_u64 v[152:153], s[74:75], 0, v[0:1]
	s_add_i32 m0, s41, 0xc000
	ds_read_b128 v[178:181], v157
	ds_read_b128 v[182:185], v157 offset:1024
	ds_read_b128 v[186:189], v157 offset:2048
	ds_read_b128 v[206:209], v157 offset:3072
	ds_read_b128 v[210:213], v157 offset:4096
	ds_read_b128 v[214:217], v157 offset:5120
	ds_read_b128 v[218:221], v157 offset:6144
	ds_read_b128 v[222:225], v157 offset:7168
	global_load_lds_dwordx4 v[152:153], off
	v_lshl_add_u64 v[152:153], s[74:75], 0, v[130:131]
	s_add_i32 m0, s41, 0xe000
	s_nop 0
	global_load_lds_dwordx4 v[152:153], off
	s_waitcnt vmcnt(8)
	s_waitcnt lgkmcnt(0)
	s_barrier
	s_setprio 1
	v_mfma_f32_16x16x32_bf16 v[126:129], v[132:135], v[178:181], 0
	v_mfma_f32_16x16x32_bf16 v[122:125], v[140:143], v[178:181], 0
	v_mfma_f32_16x16x32_bf16 v[118:121], v[132:135], v[186:189], 0
	v_mfma_f32_16x16x32_bf16 v[114:117], v[140:143], v[186:189], 0
	v_mfma_f32_16x16x32_bf16 v[110:113], v[132:135], v[210:213], 0
	v_mfma_f32_16x16x32_bf16 v[90:93], v[140:143], v[210:213], 0
	v_mfma_f32_16x16x32_bf16 v[86:89], v[132:135], v[218:221], 0
	v_mfma_f32_16x16x32_bf16 v[78:81], v[140:143], v[218:221], 0
	v_mfma_f32_16x16x32_bf16 v[126:129], v[136:139], v[182:185], v[126:129]
	v_mfma_f32_16x16x32_bf16 v[122:125], v[144:147], v[182:185], v[122:125]
	v_mfma_f32_16x16x32_bf16 v[118:121], v[136:139], v[206:209], v[118:121]
	v_mfma_f32_16x16x32_bf16 v[114:117], v[144:147], v[206:209], v[114:117]
	v_mfma_f32_16x16x32_bf16 v[110:113], v[136:139], v[214:217], v[110:113]
	v_mfma_f32_16x16x32_bf16 v[90:93], v[144:147], v[214:217], v[90:93]
	v_mfma_f32_16x16x32_bf16 v[86:89], v[136:139], v[222:225], v[86:89]
	v_mfma_f32_16x16x32_bf16 v[78:81], v[144:147], v[222:225], v[78:81]
	s_setprio 0
	s_setprio 1
	v_mfma_f32_16x16x32_bf16 v[106:109], v[148:151], v[178:181], 0
	v_mfma_f32_16x16x32_bf16 v[102:105], v[170:173], v[178:181], 0
	v_mfma_f32_16x16x32_bf16 v[98:101], v[148:151], v[186:189], 0
	v_mfma_f32_16x16x32_bf16 v[94:97], v[170:173], v[186:189], 0
	v_mfma_f32_16x16x32_bf16 v[82:85], v[148:151], v[210:213], 0
	v_mfma_f32_16x16x32_bf16 v[74:77], v[170:173], v[210:213], 0
	v_mfma_f32_16x16x32_bf16 v[70:73], v[148:151], v[218:221], 0
	v_mfma_f32_16x16x32_bf16 v[66:69], v[170:173], v[218:221], 0
	v_mfma_f32_16x16x32_bf16 v[106:109], v[158:161], v[182:185], v[106:109]
	v_mfma_f32_16x16x32_bf16 v[102:105], v[174:177], v[182:185], v[102:105]
	v_mfma_f32_16x16x32_bf16 v[98:101], v[158:161], v[206:209], v[98:101]
	v_mfma_f32_16x16x32_bf16 v[94:97], v[174:177], v[206:209], v[94:97]
	v_mfma_f32_16x16x32_bf16 v[82:85], v[158:161], v[214:217], v[82:85]
	v_mfma_f32_16x16x32_bf16 v[74:77], v[174:177], v[214:217], v[74:77]
	v_mfma_f32_16x16x32_bf16 v[70:73], v[158:161], v[222:225], v[70:73]
	v_mfma_f32_16x16x32_bf16 v[66:69], v[174:177], v[222:225], v[66:69]
	s_setprio 0
	s_barrier
	s_add_i32 s73, s73, s40
	v_lshl_add_u64 v[152:153], s[34:35], 0, v[0:1]
	s_mov_b32 m0, s73
	ds_read_b128 v[178:181], v157 offset:16384
	ds_read_b128 v[182:185], v157 offset:17408
	ds_read_b128 v[186:189], v157 offset:18432
	ds_read_b128 v[206:209], v157 offset:19456
	ds_read_b128 v[210:213], v157 offset:20480
	ds_read_b128 v[214:217], v157 offset:21504
	ds_read_b128 v[218:221], v157 offset:22528
	ds_read_b128 v[222:225], v157 offset:23552
	global_load_lds_dwordx4 v[152:153], off
	s_add_i32 m0, s73, 0x2000
	s_add_u32 s74, s34, s38
	v_lshl_add_u64 v[152:153], s[34:35], 0, v[130:131]
	s_addc_u32 s75, s35, s33
	s_add_i32 s73, s76, s40
	global_load_lds_dwordx4 v[152:153], off
	v_lshl_add_u64 v[152:153], s[74:75], 0, v[0:1]
	s_mov_b32 m0, s73
	s_nop 0
	global_load_lds_dwordx4 v[152:153], off
	v_lshl_add_u64 v[152:153], s[74:75], 0, v[130:131]
	s_add_i32 m0, s73, 0x2000
	s_nop 0
	global_load_lds_dwordx4 v[152:153], off
	v_lshl_add_u64 v[152:153], s[36:37], 0, v[0:1]
	s_mov_b32 m0, s41
	s_nop 0
	global_load_lds_dwordx4 v[152:153], off
	v_lshl_add_u64 v[152:153], s[36:37], 0, v[130:131]
	s_mov_b32 m0, s42
	s_nop 0
	global_load_lds_dwordx4 v[152:153], off
	s_waitcnt vmcnt(8)
	s_waitcnt lgkmcnt(0)
	s_barrier
; #define PG8_STAGE(bufoff, gbase, voff) do { _Pragma("unroll") for (int _i = 0; _i < 2; ++_i) \
;         __builtin_amdgcn_global_load_lds((const unsigned*)((const char*)(gbase) + (voff)[_i]), (LAS unsigned*)(lds + (bufoff) + ldsw + _i * 8192), 16, 0, 0); } while (0)
; #define PG8_LDA(dst, b, h) do { _Pragma("unroll") for (int m = 0; m < 4; ++m) _Pragma("unroll") for (int k = 0; k < 2; ++k) dst[m][k] = *(const LAS bf16x8*)(lds + PG8_SA(b, h) + aoff + m * 2048 + k * 1024); } while (0)
; #define PG8_LDB(dst, b, h) do { _Pragma("unroll") for (int n = 0; n < 2; ++n) _Pragma("unroll") for (int k = 0; k < 2; ++k) dst[n][k] = *(const LAS bf16x8*)(lds + PG8_SB(b, h) + boff + n * 2048 + k * 1024); } while (0)
; #define PG8_MMA(ai, bj, At, Bt) do { __builtin_amdgcn_s_setprio(1); _Pragma("unroll") for (int m = 0; m < 4; ++m) _Pragma("unroll") for (int n = 0; n < 2; ++n) _Pragma("unroll") for (int k = 0; k < 2; ++k) \
;         acc[ai][bj][m][n] = __builtin_amdgcn_mfma_f32_16x16x32_bf16(Bt[n][k], At[m][k], acc[ai][bj][m][n], 0, 0, 0); __builtin_amdgcn_s_setprio(0); } while (0)
; #define PG8_WAIT_V(n) asm volatile("s_waitcnt vmcnt(" #n ")" ::: "memory")
; #define PG8_WAIT_L(n) asm volatile("s_waitcnt lgkmcnt(" #n ")" ::: "memory")
; #define PG8_BAR __builtin_amdgcn_s_barrier()
; #define PG8_SCHED __builtin_amdgcn_sched_barrier(0)
; template <class Epi, bool ALIGN_EPI = PG8_ALIGN, bool SP2 = PG8_SP2>
; __device__ __forceinline__ void gemm_phase(LAS unsigned char* lds, const Gemm g, const StaticOrder& S, const Epi& E) {
;     ...
;             PG8_WAIT_V(8); PG8_WAIT_L(0); PG8_BAR; PG8_MMA(1, 0, At, B0); PG8_MMA(1, 1, At, B1); PG8_BAR; PG8_SCHED;
;             PG8_LDB(B0, 1, 0); PG8_LDB(B1, 1, 1); PG8_SCHED; PG8_LDA(At, 1, 0); PG8_STAGE(PG8_SA(0, 1), a2 + hstepA, voffA);
;             PG8_WAIT_V(8); PG8_WAIT_L(0); PG8_BAR; PG8_MMA(0, 0, At, B0); PG8_MMA(0, 1, At, B1); PG8_BAR; PG8_SCHED;
	s_setprio 1
	v_mfma_f32_16x16x32_bf16 v[62:65], v[132:135], v[178:181], 0
	v_mfma_f32_16x16x32_bf16 v[58:61], v[140:143], v[178:181], 0
	v_mfma_f32_16x16x32_bf16 v[54:57], v[132:135], v[186:189], 0
	v_mfma_f32_16x16x32_bf16 v[50:53], v[140:143], v[186:189], 0
	v_mfma_f32_16x16x32_bf16 v[46:49], v[132:135], v[210:213], 0
	v_mfma_f32_16x16x32_bf16 v[34:37], v[140:143], v[210:213], 0
	v_mfma_f32_16x16x32_bf16 v[18:21], v[132:135], v[218:221], 0
	v_mfma_f32_16x16x32_bf16 v[14:17], v[140:143], v[218:221], 0
	v_mfma_f32_16x16x32_bf16 v[62:65], v[136:139], v[182:185], v[62:65]
	v_mfma_f32_16x16x32_bf16 v[58:61], v[144:147], v[182:185], v[58:61]
	v_mfma_f32_16x16x32_bf16 v[54:57], v[136:139], v[206:209], v[54:57]
	v_mfma_f32_16x16x32_bf16 v[50:53], v[144:147], v[206:209], v[50:53]
	v_mfma_f32_16x16x32_bf16 v[46:49], v[136:139], v[214:217], v[46:49]
	v_mfma_f32_16x16x32_bf16 v[34:37], v[144:147], v[214:217], v[34:37]
	v_mfma_f32_16x16x32_bf16 v[18:21], v[136:139], v[222:225], v[18:21]
	v_mfma_f32_16x16x32_bf16 v[14:17], v[144:147], v[222:225], v[14:17]
	s_setprio 0
	s_setprio 1
	v_mfma_f32_16x16x32_bf16 v[42:45], v[148:151], v[178:181], 0
	v_mfma_f32_16x16x32_bf16 v[38:41], v[170:173], v[178:181], 0
	v_mfma_f32_16x16x32_bf16 v[30:33], v[148:151], v[186:189], 0
	v_mfma_f32_16x16x32_bf16 v[26:29], v[170:173], v[186:189], 0
	v_mfma_f32_16x16x32_bf16 v[22:25], v[148:151], v[210:213], 0
	v_mfma_f32_16x16x32_bf16 v[10:13], v[170:173], v[210:213], 0
	v_mfma_f32_16x16x32_bf16 v[6:9], v[148:151], v[218:221], 0
	v_mfma_f32_16x16x32_bf16 v[2:5], v[170:173], v[218:221], 0
	v_mfma_f32_16x16x32_bf16 v[42:45], v[158:161], v[182:185], v[42:45]
	v_mfma_f32_16x16x32_bf16 v[38:41], v[174:177], v[182:185], v[38:41]
	v_mfma_f32_16x16x32_bf16 v[30:33], v[158:161], v[206:209], v[30:33]
	v_mfma_f32_16x16x32_bf16 v[26:29], v[174:177], v[206:209], v[26:29]
	v_mfma_f32_16x16x32_bf16 v[22:25], v[158:161], v[214:217], v[22:25]
	v_mfma_f32_16x16x32_bf16 v[10:13], v[174:177], v[214:217], v[10:13]
	v_mfma_f32_16x16x32_bf16 v[6:9], v[158:161], v[222:225], v[6:9]
	v_mfma_f32_16x16x32_bf16 v[2:5], v[174:177], v[222:225], v[2:5]
	s_setprio 0
	s_barrier
	s_add_i32 s73, 0, 0x18000
	s_add_i32 s74, 0, 0x1c000
	v_add_u32_e32 v144, s73, v155
	v_add_u32_e32 v152, s74, v155
	ds_read_b128 v[132:135], v144
	ds_read_b128 v[136:139], v144 offset:1024
	ds_read_b128 v[140:143], v144 offset:2048
	ds_read_b128 v[144:147], v144 offset:3072
	ds_read_b128 v[148:151], v152
	ds_read_b128 v[158:161], v152 offset:1024
	ds_read_b128 v[170:173], v152 offset:2048
	ds_read_b128 v[174:177], v152 offset:3072
	s_add_u32 s36, s36, s38
	s_addc_u32 s37, s37, s33
	s_mov_b32 m0, s43
	v_lshl_add_u64 v[152:153], s[36:37], 0, v[0:1]
	ds_read_b128 v[178:181], v157 offset:32768
	ds_read_b128 v[182:185], v157 offset:33792
	ds_read_b128 v[186:189], v157 offset:34816
	ds_read_b128 v[206:209], v157 offset:35840
	ds_read_b128 v[210:213], v157 offset:36864
	ds_read_b128 v[214:217], v157 offset:37888
	ds_read_b128 v[218:221], v157 offset:38912
	ds_read_b128 v[222:225], v157 offset:39936
	global_load_lds_dwordx4 v[152:153], off
	v_lshl_add_u64 v[152:153], s[36:37], 0, v[130:131]
	s_mov_b32 m0, s44
	s_nop 0
	global_load_lds_dwordx4 v[152:153], off
	s_waitcnt vmcnt(8)
	s_waitcnt lgkmcnt(0)
	s_barrier
	s_setprio 1
	v_mfma_f32_16x16x32_bf16 v[126:129], v[132:135], v[178:181], v[126:129]
	v_mfma_f32_16x16x32_bf16 v[122:125], v[140:143], v[178:181], v[122:125]
	v_mfma_f32_16x16x32_bf16 v[118:121], v[132:135], v[186:189], v[118:121]
	v_mfma_f32_16x16x32_bf16 v[114:117], v[140:143], v[186:189], v[114:117]
	v_mfma_f32_16x16x32_bf16 v[110:113], v[132:135], v[210:213], v[110:113]
	v_mfma_f32_16x16x32_bf16 v[90:93], v[140:143], v[210:213], v[90:93]
	v_mfma_f32_16x16x32_bf16 v[86:89], v[132:135], v[218:221], v[86:89]
	v_mfma_f32_16x16x32_bf16 v[78:81], v[140:143], v[218:221], v[78:81]
	v_mfma_f32_16x16x32_bf16 v[126:129], v[136:139], v[182:185], v[126:129]
	v_mfma_f32_16x16x32_bf16 v[122:125], v[144:147], v[182:185], v[122:125]
	v_mfma_f32_16x16x32_bf16 v[118:121], v[136:139], v[206:209], v[118:121]
	v_mfma_f32_16x16x32_bf16 v[114:117], v[144:147], v[206:209], v[114:117]
	v_mfma_f32_16x16x32_bf16 v[110:113], v[136:139], v[214:217], v[110:113]
	v_mfma_f32_16x16x32_bf16 v[90:93], v[144:147], v[214:217], v[90:93]
	v_mfma_f32_16x16x32_bf16 v[86:89], v[136:139], v[222:225], v[86:89]
	v_mfma_f32_16x16x32_bf16 v[78:81], v[144:147], v[222:225], v[78:81]
	s_setprio 0
	s_setprio 1
	v_mfma_f32_16x16x32_bf16 v[106:109], v[148:151], v[178:181], v[106:109]
	v_mfma_f32_16x16x32_bf16 v[102:105], v[170:173], v[178:181], v[102:105]
	v_mfma_f32_16x16x32_bf16 v[98:101], v[148:151], v[186:189], v[98:101]
	v_mfma_f32_16x16x32_bf16 v[94:97], v[170:173], v[186:189], v[94:97]
	v_mfma_f32_16x16x32_bf16 v[82:85], v[148:151], v[210:213], v[82:85]
	v_mfma_f32_16x16x32_bf16 v[74:77], v[170:173], v[210:213], v[74:77]
	v_mfma_f32_16x16x32_bf16 v[70:73], v[148:151], v[218:221], v[70:73]
	v_mfma_f32_16x16x32_bf16 v[66:69], v[170:173], v[218:221], v[66:69]
	v_mfma_f32_16x16x32_bf16 v[106:109], v[158:161], v[182:185], v[106:109]
	v_mfma_f32_16x16x32_bf16 v[102:105], v[174:177], v[182:185], v[102:105]
	v_mfma_f32_16x16x32_bf16 v[98:101], v[158:161], v[206:209], v[98:101]
	v_mfma_f32_16x16x32_bf16 v[94:97], v[174:177], v[206:209], v[94:97]
	v_mfma_f32_16x16x32_bf16 v[82:85], v[158:161], v[214:217], v[82:85]
	v_mfma_f32_16x16x32_bf16 v[74:77], v[174:177], v[214:217], v[74:77]
	v_mfma_f32_16x16x32_bf16 v[70:73], v[158:161], v[222:225], v[70:73]
	v_mfma_f32_16x16x32_bf16 v[66:69], v[174:177], v[222:225], v[66:69]
	s_setprio 0
	s_barrier
; #define PG8_STAGE(bufoff, gbase, voff) do { _Pragma("unroll") for (int _i = 0; _i < 2; ++_i) \
;         __builtin_amdgcn_global_load_lds((const unsigned*)((const char*)(gbase) + (voff)[_i]), (LAS unsigned*)(lds + (bufoff) + ldsw + _i * 8192), 16, 0, 0); } while (0)
; #define PG8_LDA(dst, b, h) do { _Pragma("unroll") for (int m = 0; m < 4; ++m) _Pragma("unroll") for (int k = 0; k < 2; ++k) dst[m][k] = *(const LAS bf16x8*)(lds + PG8_SA(b, h) + aoff + m * 2048 + k * 1024); } while (0)
; #define PG8_MMA(ai, bj, At, Bt) do { __builtin_amdgcn_s_setprio(1); _Pragma("unroll") for (int m = 0; m < 4; ++m) _Pragma("unroll") for (int n = 0; n < 2; ++n) _Pragma("unroll") for (int k = 0; k < 2; ++k) \
;         acc[ai][bj][m][n] = __builtin_amdgcn_mfma_f32_16x16x32_bf16(Bt[n][k], At[m][k], acc[ai][bj][m][n], 0, 0, 0); __builtin_amdgcn_s_setprio(0); } while (0)
; #define PG8_WAIT_V(n) asm volatile("s_waitcnt vmcnt(" #n ")" ::: "memory")
; #define PG8_WAIT_L(n) asm volatile("s_waitcnt lgkmcnt(" #n ")" ::: "memory")
; #define PG8_BAR __builtin_amdgcn_s_barrier()
; #define PG8_SCHED __builtin_amdgcn_sched_barrier(0)
; template <class Epi, bool ALIGN_EPI = PG8_ALIGN, bool SP2 = PG8_SP2>
; __device__ __forceinline__ void gemm_phase(LAS unsigned char* lds, const Gemm g, const StaticOrder& S, const Epi& E) {
;     ...
;             PG8_LDA(At, 1, 1); PG8_STAGE(PG8_SB(1, 0), b3, voffB); PG8_STAGE(PG8_SB(1, 1), b3 + hstepB, voffB); PG8_STAGE(PG8_SA(1, 0), a3, voffA);
;             PG8_WAIT_V(8); PG8_WAIT_L(0); PG8_BAR; PG8_MMA(1, 0, At, B0); PG8_MMA(1, 1, At, B1); PG8_BAR; PG8_SCHED;
	s_add_u32 s34, s34, s52
	s_addc_u32 s35, s35, 0
	s_add_i32 s36, s73, s40
	v_lshl_add_u64 v[152:153], s[34:35], 0, v[0:1]
	s_mov_b32 m0, s36
	ds_read_b128 v[178:181], v157 offset:49152
	ds_read_b128 v[182:185], v157 offset:50176
	ds_read_b128 v[186:189], v157 offset:51200
	ds_read_b128 v[206:209], v157 offset:52224
	ds_read_b128 v[210:213], v157 offset:53248
	ds_read_b128 v[214:217], v157 offset:54272
	ds_read_b128 v[218:221], v157 offset:55296
	ds_read_b128 v[222:225], v157 offset:56320
	global_load_lds_dwordx4 v[152:153], off
	s_add_i32 m0, s36, 0x2000
	v_lshl_add_u64 v[152:153], s[34:35], 0, v[130:131]
	s_add_u32 s34, s34, s38
	s_addc_u32 s35, s35, s33
	s_add_i32 s36, s74, s40
	global_load_lds_dwordx4 v[152:153], off
	v_lshl_add_u64 v[152:153], s[34:35], 0, v[0:1]
	s_mov_b32 m0, s36
	s_nop 0
	global_load_lds_dwordx4 v[152:153], off
	v_lshl_add_u64 v[152:153], s[34:35], 0, v[130:131]
	s_add_i32 m0, s36, 0x2000
	s_nop 0
	global_load_lds_dwordx4 v[152:153], off
	v_lshl_add_u64 v[152:153], s[28:29], 0, v[0:1]
	s_mov_b32 m0, s53
	s_nop 0
	global_load_lds_dwordx4 v[152:153], off
	v_lshl_add_u64 v[152:153], s[28:29], 0, v[130:131]
	s_mov_b32 m0, s54
	s_nop 0
	global_load_lds_dwordx4 v[152:153], off
	s_waitcnt vmcnt(8)
	s_waitcnt lgkmcnt(0)
	s_barrier
	s_setprio 1
	v_mfma_f32_16x16x32_bf16 v[62:65], v[132:135], v[178:181], v[62:65]
	v_mfma_f32_16x16x32_bf16 v[58:61], v[140:143], v[178:181], v[58:61]
	v_mfma_f32_16x16x32_bf16 v[54:57], v[132:135], v[186:189], v[54:57]
	v_mfma_f32_16x16x32_bf16 v[50:53], v[140:143], v[186:189], v[50:53]
	v_mfma_f32_16x16x32_bf16 v[46:49], v[132:135], v[210:213], v[46:49]
	v_mfma_f32_16x16x32_bf16 v[34:37], v[140:143], v[210:213], v[34:37]
	v_mfma_f32_16x16x32_bf16 v[18:21], v[132:135], v[218:221], v[18:21]
	v_mfma_f32_16x16x32_bf16 v[14:17], v[140:143], v[218:221], v[14:17]
	v_mfma_f32_16x16x32_bf16 v[62:65], v[136:139], v[182:185], v[62:65]
	v_mfma_f32_16x16x32_bf16 v[58:61], v[144:147], v[182:185], v[58:61]
	v_mfma_f32_16x16x32_bf16 v[54:57], v[136:139], v[206:209], v[54:57]
	v_mfma_f32_16x16x32_bf16 v[50:53], v[144:147], v[206:209], v[50:53]
	v_mfma_f32_16x16x32_bf16 v[46:49], v[136:139], v[214:217], v[46:49]
	v_mfma_f32_16x16x32_bf16 v[34:37], v[144:147], v[214:217], v[34:37]
	v_mfma_f32_16x16x32_bf16 v[18:21], v[136:139], v[222:225], v[18:21]
	v_mfma_f32_16x16x32_bf16 v[14:17], v[144:147], v[222:225], v[14:17]
	s_setprio 0
	s_setprio 1
	v_mfma_f32_16x16x32_bf16 v[42:45], v[148:151], v[178:181], v[42:45]
	v_mfma_f32_16x16x32_bf16 v[38:41], v[170:173], v[178:181], v[38:41]
	v_mfma_f32_16x16x32_bf16 v[30:33], v[148:151], v[186:189], v[30:33]
	v_mfma_f32_16x16x32_bf16 v[26:29], v[170:173], v[186:189], v[26:29]
	v_mfma_f32_16x16x32_bf16 v[22:25], v[148:151], v[210:213], v[22:25]
	v_mfma_f32_16x16x32_bf16 v[10:13], v[170:173], v[210:213], v[10:13]
	v_mfma_f32_16x16x32_bf16 v[6:9], v[148:151], v[218:221], v[6:9]
	v_mfma_f32_16x16x32_bf16 v[2:5], v[170:173], v[218:221], v[2:5]
	v_mfma_f32_16x16x32_bf16 v[42:45], v[158:161], v[182:185], v[42:45]
	v_mfma_f32_16x16x32_bf16 v[38:41], v[174:177], v[182:185], v[38:41]
	v_mfma_f32_16x16x32_bf16 v[30:33], v[158:161], v[206:209], v[30:33]
	v_mfma_f32_16x16x32_bf16 v[26:29], v[174:177], v[206:209], v[26:29]
	v_mfma_f32_16x16x32_bf16 v[22:25], v[158:161], v[214:217], v[22:25]
	v_mfma_f32_16x16x32_bf16 v[10:13], v[174:177], v[214:217], v[10:13]
	v_mfma_f32_16x16x32_bf16 v[6:9], v[158:161], v[222:225], v[6:9]
	v_mfma_f32_16x16x32_bf16 v[2:5], v[174:177], v[222:225], v[2:5]
	s_setprio 0
	s_barrier
	s_cmp_ge_u32 s30, s49
	s_mov_b64 s[28:29], s[30:31]
	s_branch .LBB0_583

; #define PG8_STAGE(bufoff, gbase, voff) do { _Pragma("unroll") for (int _i = 0; _i < 2; ++_i) \
;         __builtin_amdgcn_global_load_lds((const unsigned*)((const char*)(gbase) + (voff)[_i]), (LAS unsigned*)(lds + (bufoff) + ldsw + _i * 8192), 16, 0, 0); } while (0)
; #define PG8_LDA(dst, b, h) do { _Pragma("unroll") for (int m = 0; m < 4; ++m) _Pragma("unroll") for (int k = 0; k < 2; ++k) dst[m][k] = *(const LAS bf16x8*)(lds + PG8_SA(b, h) + aoff + m * 2048 + k * 1024); } while (0)
; #define PG8_LDB(dst, b, h) do { _Pragma("unroll") for (int n = 0; n < 2; ++n) _Pragma("unroll") for (int k = 0; k < 2; ++k) dst[n][k] = *(const LAS bf16x8*)(lds + PG8_SB(b, h) + boff + n * 2048 + k * 1024); } while (0)
; #define PG8_MMA(ai, bj, At, Bt) do { __builtin_amdgcn_s_setprio(1); _Pragma("unroll") for (int m = 0; m < 4; ++m) _Pragma("unroll") for (int n = 0; n < 2; ++n) _Pragma("unroll") for (int k = 0; k < 2; ++k) \
;         acc[ai][bj][m][n] = __builtin_amdgcn_mfma_f32_16x16x32_bf16(Bt[n][k], At[m][k], acc[ai][bj][m][n], 0, 0, 0); __builtin_amdgcn_s_setprio(0); } while (0)
; #define PG8_WAIT_V(n) asm volatile("s_waitcnt vmcnt(" #n ")" ::: "memory")
; #define PG8_WAIT_L(n) asm volatile("s_waitcnt lgkmcnt(" #n ")" ::: "memory")
; #define PG8_BAR __builtin_amdgcn_s_barrier()
; #define PG8_SCHED __builtin_amdgcn_sched_barrier(0)
; template <class Epi, bool ALIGN_EPI = PG8_ALIGN, bool SP2 = PG8_SP2>
; __device__ __forceinline__ void gemm_phase(LAS unsigned char* lds, const Gemm g, const StaticOrder& S, const Epi& E) {
;     ...
;             const bool last = (t == nt - 2);
;             const char* a1 = cA + (size_t)(t + 1) * kstepA;
;             const char* a2 = last ? nA : cA + (size_t)(t + 2) * kstepA; const char* b2 = last ? nB : cB + (size_t)(t + 2) * kstepB;
;             const char* a3 = a2 + kstepA; const char* b3 = b2 + kstepB;
;             if constexpr (SP2) {
;             PG8_LDB(B0, 0, 0); PG8_LDB(B1, 0, 1); PG8_SCHED; PG8_LDA(At, 0, 0); PG8_STAGE(PG8_SA(1, 1), a1 + hstepA, voffA);
;             PG8_WAIT_V(8); PG8_WAIT_L(0); PG8_BAR; PG8_MMA(0, 0, At, B0); PG8_MMA(0, 1, At, B1); PG8_BAR; PG8_SCHED;
;             PG8_LDA(At, 0, 1); PG8_STAGE(PG8_SB(0, 0), b2, voffB); PG8_STAGE(PG8_SB(0, 1), b2 + hstepB, voffB); PG8_STAGE(PG8_SA(0, 0), a2, voffA);
;             PG8_WAIT_V(8); PG8_WAIT_L(0); PG8_BAR; PG8_MMA(1, 0, At, B0); PG8_MMA(1, 1, At, B1); PG8_BAR; PG8_SCHED;
.LBB0_611:
	s_cmp_eq_u32 s47, -2
	s_cbranch_scc1 .Lfirst_iter_u611
	s_add_u32 s22, s20, 0xfffc0080
	s_addc_u32 s23, s21, -1
	s_add_i32 s48, 0, 0x10000
	s_cmp_eq_u32 s47, 12
	s_cselect_b32 s25, s13, s23
	s_cselect_b32 s24, s43, s22
	v_add_u32_e32 v0, s48, v141
	s_cselect_b32 s23, s11, s46
	s_cselect_b32 s22, s44, s45
	s_add_i32 s52, 0, 0x14000
	ds_read_b128 v[144:147], v0
	ds_read_b128 v[148:151], v0 offset:1024
	ds_read_b128 v[152:155], v0 offset:2048
	ds_read_b128 v[156:159], v0 offset:3072
	v_add_u32_e32 v0, s52, v141
	ds_read_b128 v[170:173], v0
	ds_read_b128 v[174:177], v0 offset:1024
	ds_read_b128 v[178:181], v0 offset:2048
	ds_read_b128 v[182:185], v0 offset:3072
	v_lshl_add_u64 v[160:161], s[20:21], 0, v[134:135]
	s_add_i32 m0, s34, 0xc000
	ds_read_b128 v[186:189], v142
	ds_read_b128 v[206:209], v142 offset:1024
	ds_read_b128 v[210:213], v142 offset:2048
	ds_read_b128 v[214:217], v142 offset:3072
	ds_read_b128 v[218:221], v142 offset:4096
	ds_read_b128 v[222:225], v142 offset:5120
	ds_read_b128 v[226:229], v142 offset:6144
	ds_read_b128 v[230:233], v142 offset:7168
	global_load_lds_dwordx4 v[160:161], off
	v_lshl_add_u64 v[160:161], s[20:21], 0, v[136:137]
	s_add_i32 m0, s34, 0xe000
	s_nop 0
	global_load_lds_dwordx4 v[160:161], off
	s_waitcnt vmcnt(8)
	s_waitcnt lgkmcnt(0)
	s_barrier
	s_setprio 1
	v_mfma_f32_16x16x32_bf16 v[126:129], v[144:147], v[186:189], v[126:129]
	v_mfma_f32_16x16x32_bf16 v[118:121], v[152:155], v[186:189], v[118:121]
	v_mfma_f32_16x16x32_bf16 v[110:113], v[144:147], v[210:213], v[110:113]
	v_mfma_f32_16x16x32_bf16 v[102:105], v[152:155], v[210:213], v[102:105]
	v_mfma_f32_16x16x32_bf16 v[94:97], v[144:147], v[218:221], v[94:97]
	v_mfma_f32_16x16x32_bf16 v[86:89], v[152:155], v[218:221], v[86:89]
	v_mfma_f32_16x16x32_bf16 v[78:81], v[144:147], v[226:229], v[78:81]
	v_mfma_f32_16x16x32_bf16 v[70:73], v[152:155], v[226:229], v[70:73]
	v_mfma_f32_16x16x32_bf16 v[126:129], v[148:151], v[206:209], v[126:129]
	v_mfma_f32_16x16x32_bf16 v[118:121], v[156:159], v[206:209], v[118:121]
	v_mfma_f32_16x16x32_bf16 v[110:113], v[148:151], v[214:217], v[110:113]
	v_mfma_f32_16x16x32_bf16 v[102:105], v[156:159], v[214:217], v[102:105]
	v_mfma_f32_16x16x32_bf16 v[94:97], v[148:151], v[222:225], v[94:97]
	v_mfma_f32_16x16x32_bf16 v[86:89], v[156:159], v[222:225], v[86:89]
	v_mfma_f32_16x16x32_bf16 v[78:81], v[148:151], v[230:233], v[78:81]
	v_mfma_f32_16x16x32_bf16 v[70:73], v[156:159], v[230:233], v[70:73]
	s_setprio 0
	s_setprio 1
	v_mfma_f32_16x16x32_bf16 v[122:125], v[170:173], v[186:189], v[122:125]
	v_mfma_f32_16x16x32_bf16 v[114:117], v[178:181], v[186:189], v[114:117]
	v_mfma_f32_16x16x32_bf16 v[106:109], v[170:173], v[210:213], v[106:109]
	v_mfma_f32_16x16x32_bf16 v[98:101], v[178:181], v[210:213], v[98:101]
	v_mfma_f32_16x16x32_bf16 v[90:93], v[170:173], v[218:221], v[90:93]
	v_mfma_f32_16x16x32_bf16 v[82:85], v[178:181], v[218:221], v[82:85]
	v_mfma_f32_16x16x32_bf16 v[74:77], v[170:173], v[226:229], v[74:77]
	v_mfma_f32_16x16x32_bf16 v[66:69], v[178:181], v[226:229], v[66:69]
	v_mfma_f32_16x16x32_bf16 v[122:125], v[174:177], v[206:209], v[122:125]
	v_mfma_f32_16x16x32_bf16 v[114:117], v[182:185], v[206:209], v[114:117]
	v_mfma_f32_16x16x32_bf16 v[106:109], v[174:177], v[214:217], v[106:109]
	v_mfma_f32_16x16x32_bf16 v[98:101], v[182:185], v[214:217], v[98:101]
	v_mfma_f32_16x16x32_bf16 v[90:93], v[174:177], v[222:225], v[90:93]
	v_mfma_f32_16x16x32_bf16 v[82:85], v[182:185], v[222:225], v[82:85]
	v_mfma_f32_16x16x32_bf16 v[74:77], v[174:177], v[230:233], v[74:77]
	v_mfma_f32_16x16x32_bf16 v[66:69], v[182:185], v[230:233], v[66:69]
	s_setprio 0
	s_barrier
	s_add_i32 s48, s48, s33
	v_lshl_add_u64 v[160:161], s[22:23], 0, v[130:131]
	s_mov_b32 m0, s48
	ds_read_b128 v[186:189], v142 offset:16384
	ds_read_b128 v[206:209], v142 offset:17408
	ds_read_b128 v[210:213], v142 offset:18432
	ds_read_b128 v[214:217], v142 offset:19456
	ds_read_b128 v[218:221], v142 offset:20480
	ds_read_b128 v[222:225], v142 offset:21504
	ds_read_b128 v[226:229], v142 offset:22528
	ds_read_b128 v[230:233], v142 offset:23552
	global_load_lds_dwordx4 v[160:161], off
	s_add_i32 m0, s48, 0x2000
	s_add_u32 s48, s22, 0x40000
	v_lshl_add_u64 v[164:165], s[22:23], 0, v[132:133]
	s_addc_u32 s49, s23, 0
	s_add_i32 s52, s52, s33
	global_load_lds_dwordx4 v[164:165], off
	v_lshl_add_u64 v[166:167], s[48:49], 0, v[130:131]
	s_mov_b32 m0, s52
	v_lshl_add_u64 v[194:195], s[24:25], 0, v[132:133]
	global_load_lds_dwordx4 v[166:167], off
	v_lshl_add_u64 v[166:167], s[48:49], 0, v[132:133]
	s_add_i32 m0, s52, 0x2000
	s_nop 0
	global_load_lds_dwordx4 v[166:167], off
	v_lshl_add_u64 v[166:167], s[24:25], 0, v[130:131]
	s_mov_b32 m0, s34
	s_nop 0
	global_load_lds_dwordx4 v[166:167], off
	s_mov_b32 m0, s35
	s_nop 0
	global_load_lds_dwordx4 v[194:195], off
	s_waitcnt vmcnt(8)
	s_waitcnt lgkmcnt(0)
	s_barrier
; #define PG8_STAGE(bufoff, gbase, voff) do { _Pragma("unroll") for (int _i = 0; _i < 2; ++_i) \
;         __builtin_amdgcn_global_load_lds((const unsigned*)((const char*)(gbase) + (voff)[_i]), (LAS unsigned*)(lds + (bufoff) + ldsw + _i * 8192), 16, 0, 0); } while (0)
; #define PG8_LDA(dst, b, h) do { _Pragma("unroll") for (int m = 0; m < 4; ++m) _Pragma("unroll") for (int k = 0; k < 2; ++k) dst[m][k] = *(const LAS bf16x8*)(lds + PG8_SA(b, h) + aoff + m * 2048 + k * 1024); } while (0)
; #define PG8_LDB(dst, b, h) do { _Pragma("unroll") for (int n = 0; n < 2; ++n) _Pragma("unroll") for (int k = 0; k < 2; ++k) dst[n][k] = *(const LAS bf16x8*)(lds + PG8_SB(b, h) + boff + n * 2048 + k * 1024); } while (0)
; #define PG8_MMA(ai, bj, At, Bt) do { __builtin_amdgcn_s_setprio(1); _Pragma("unroll") for (int m = 0; m < 4; ++m) _Pragma("unroll") for (int n = 0; n < 2; ++n) _Pragma("unroll") for (int k = 0; k < 2; ++k) \
;         acc[ai][bj][m][n] = __builtin_amdgcn_mfma_f32_16x16x32_bf16(Bt[n][k], At[m][k], acc[ai][bj][m][n], 0, 0, 0); __builtin_amdgcn_s_setprio(0); } while (0)
; #define PG8_WAIT_V(n) asm volatile("s_waitcnt vmcnt(" #n ")" ::: "memory")
; #define PG8_WAIT_L(n) asm volatile("s_waitcnt lgkmcnt(" #n ")" ::: "memory")
; #define PG8_BAR __builtin_amdgcn_s_barrier()
; #define PG8_SCHED __builtin_amdgcn_sched_barrier(0)
; template <class Epi, bool ALIGN_EPI = PG8_ALIGN, bool SP2 = PG8_SP2>
; __device__ __forceinline__ void gemm_phase(LAS unsigned char* lds, const Gemm g, const StaticOrder& S, const Epi& E) {
;     ...
;             PG8_WAIT_V(8); PG8_WAIT_L(0); PG8_BAR; PG8_MMA(1, 0, At, B0); PG8_MMA(1, 1, At, B1); PG8_BAR; PG8_SCHED;
;             PG8_LDB(B0, 1, 0); PG8_LDB(B1, 1, 1); PG8_SCHED; PG8_LDA(At, 1, 0); PG8_STAGE(PG8_SA(0, 1), a2 + hstepA, voffA);
;             PG8_WAIT_V(8); PG8_WAIT_L(0); PG8_BAR; PG8_MMA(0, 0, At, B0); PG8_MMA(0, 1, At, B1); PG8_BAR; PG8_SCHED;
	s_setprio 1
	v_mfma_f32_16x16x32_bf16 v[62:65], v[144:147], v[186:189], v[62:65]
	v_mfma_f32_16x16x32_bf16 v[54:57], v[152:155], v[186:189], v[54:57]
	v_mfma_f32_16x16x32_bf16 v[46:49], v[144:147], v[210:213], v[46:49]
	v_mfma_f32_16x16x32_bf16 v[38:41], v[152:155], v[210:213], v[38:41]
	v_mfma_f32_16x16x32_bf16 v[30:33], v[144:147], v[218:221], v[30:33]
	v_mfma_f32_16x16x32_bf16 v[22:25], v[152:155], v[218:221], v[22:25]
	v_mfma_f32_16x16x32_bf16 v[14:17], v[144:147], v[226:229], v[14:17]
	v_mfma_f32_16x16x32_bf16 v[6:9], v[152:155], v[226:229], v[6:9]
	v_mfma_f32_16x16x32_bf16 v[62:65], v[148:151], v[206:209], v[62:65]
	v_mfma_f32_16x16x32_bf16 v[54:57], v[156:159], v[206:209], v[54:57]
	v_mfma_f32_16x16x32_bf16 v[46:49], v[148:151], v[214:217], v[46:49]
	v_mfma_f32_16x16x32_bf16 v[38:41], v[156:159], v[214:217], v[38:41]
	v_mfma_f32_16x16x32_bf16 v[30:33], v[148:151], v[222:225], v[30:33]
	v_mfma_f32_16x16x32_bf16 v[22:25], v[156:159], v[222:225], v[22:25]
	v_mfma_f32_16x16x32_bf16 v[14:17], v[148:151], v[230:233], v[14:17]
	v_mfma_f32_16x16x32_bf16 v[6:9], v[156:159], v[230:233], v[6:9]
	s_setprio 0
	s_setprio 1
	v_mfma_f32_16x16x32_bf16 v[58:61], v[170:173], v[186:189], v[58:61]
	v_mfma_f32_16x16x32_bf16 v[50:53], v[178:181], v[186:189], v[50:53]
	v_mfma_f32_16x16x32_bf16 v[42:45], v[170:173], v[210:213], v[42:45]
	v_mfma_f32_16x16x32_bf16 v[34:37], v[178:181], v[210:213], v[34:37]
	v_mfma_f32_16x16x32_bf16 v[26:29], v[170:173], v[218:221], v[26:29]
	v_mfma_f32_16x16x32_bf16 v[18:21], v[178:181], v[218:221], v[18:21]
	v_mfma_f32_16x16x32_bf16 v[10:13], v[170:173], v[226:229], v[10:13]
	v_mfma_f32_16x16x32_bf16 v[2:5], v[178:181], v[226:229], v[2:5]
	v_mfma_f32_16x16x32_bf16 v[58:61], v[174:177], v[206:209], v[58:61]
	v_mfma_f32_16x16x32_bf16 v[50:53], v[182:185], v[206:209], v[50:53]
	v_mfma_f32_16x16x32_bf16 v[42:45], v[174:177], v[214:217], v[42:45]
	v_mfma_f32_16x16x32_bf16 v[34:37], v[182:185], v[214:217], v[34:37]
	v_mfma_f32_16x16x32_bf16 v[26:29], v[174:177], v[222:225], v[26:29]
	v_mfma_f32_16x16x32_bf16 v[18:21], v[182:185], v[222:225], v[18:21]
	v_mfma_f32_16x16x32_bf16 v[10:13], v[174:177], v[230:233], v[10:13]
	v_mfma_f32_16x16x32_bf16 v[2:5], v[182:185], v[230:233], v[2:5]
	s_setprio 0
	s_barrier
	s_add_i32 s48, 0, 0x18000
	v_add_u32_e32 v0, s48, v141
	s_add_i32 s49, 0, 0x1c000
	ds_read_b128 v[144:147], v0
	ds_read_b128 v[148:151], v0 offset:1024
	ds_read_b128 v[152:155], v0 offset:2048
	ds_read_b128 v[156:159], v0 offset:3072
	v_add_u32_e32 v0, s49, v141
	ds_read_b128 v[170:173], v0
	ds_read_b128 v[174:177], v0 offset:1024
	ds_read_b128 v[178:181], v0 offset:2048
	ds_read_b128 v[182:185], v0 offset:3072
	s_add_u32 s24, s24, 0x40000
	s_addc_u32 s25, s25, 0
	s_mov_b32 m0, s36
	v_lshl_add_u64 v[196:197], s[24:25], 0, v[130:131]
	ds_read_b128 v[186:189], v142 offset:32768
	ds_read_b128 v[206:209], v142 offset:33792
	ds_read_b128 v[210:213], v142 offset:34816
	ds_read_b128 v[214:217], v142 offset:35840
	ds_read_b128 v[218:221], v142 offset:36864
	ds_read_b128 v[222:225], v142 offset:37888
	ds_read_b128 v[226:229], v142 offset:38912
	ds_read_b128 v[230:233], v142 offset:39936
	global_load_lds_dwordx4 v[196:197], off
	v_lshl_add_u64 v[196:197], s[24:25], 0, v[132:133]
	s_mov_b32 m0, s37
	s_nop 0
	global_load_lds_dwordx4 v[196:197], off
	s_waitcnt vmcnt(8)
	s_waitcnt lgkmcnt(0)
	s_barrier
	s_setprio 1
	v_mfma_f32_16x16x32_bf16 v[126:129], v[144:147], v[186:189], v[126:129]
	v_mfma_f32_16x16x32_bf16 v[118:121], v[152:155], v[186:189], v[118:121]
	v_mfma_f32_16x16x32_bf16 v[110:113], v[144:147], v[210:213], v[110:113]
	v_mfma_f32_16x16x32_bf16 v[102:105], v[152:155], v[210:213], v[102:105]
	v_mfma_f32_16x16x32_bf16 v[94:97], v[144:147], v[218:221], v[94:97]
	v_mfma_f32_16x16x32_bf16 v[86:89], v[152:155], v[218:221], v[86:89]
	v_mfma_f32_16x16x32_bf16 v[78:81], v[144:147], v[226:229], v[78:81]
	v_mfma_f32_16x16x32_bf16 v[70:73], v[152:155], v[226:229], v[70:73]
	v_mfma_f32_16x16x32_bf16 v[126:129], v[148:151], v[206:209], v[126:129]
	v_mfma_f32_16x16x32_bf16 v[118:121], v[156:159], v[206:209], v[118:121]
	v_mfma_f32_16x16x32_bf16 v[110:113], v[148:151], v[214:217], v[110:113]
	v_mfma_f32_16x16x32_bf16 v[102:105], v[156:159], v[214:217], v[102:105]
	v_mfma_f32_16x16x32_bf16 v[94:97], v[148:151], v[222:225], v[94:97]
	v_mfma_f32_16x16x32_bf16 v[86:89], v[156:159], v[222:225], v[86:89]
	v_mfma_f32_16x16x32_bf16 v[78:81], v[148:151], v[230:233], v[78:81]
	v_mfma_f32_16x16x32_bf16 v[70:73], v[156:159], v[230:233], v[70:73]
	s_setprio 0
	s_setprio 1
	v_mfma_f32_16x16x32_bf16 v[122:125], v[170:173], v[186:189], v[122:125]
	v_mfma_f32_16x16x32_bf16 v[114:117], v[178:181], v[186:189], v[114:117]
	v_mfma_f32_16x16x32_bf16 v[106:109], v[170:173], v[210:213], v[106:109]
	v_mfma_f32_16x16x32_bf16 v[98:101], v[178:181], v[210:213], v[98:101]
	v_mfma_f32_16x16x32_bf16 v[90:93], v[170:173], v[218:221], v[90:93]
	v_mfma_f32_16x16x32_bf16 v[82:85], v[178:181], v[218:221], v[82:85]
	v_mfma_f32_16x16x32_bf16 v[74:77], v[170:173], v[226:229], v[74:77]
	v_mfma_f32_16x16x32_bf16 v[66:69], v[178:181], v[226:229], v[66:69]
	v_mfma_f32_16x16x32_bf16 v[122:125], v[174:177], v[206:209], v[122:125]
	v_mfma_f32_16x16x32_bf16 v[114:117], v[182:185], v[206:209], v[114:117]
	v_mfma_f32_16x16x32_bf16 v[106:109], v[174:177], v[214:217], v[106:109]
	v_mfma_f32_16x16x32_bf16 v[98:101], v[182:185], v[214:217], v[98:101]
	v_mfma_f32_16x16x32_bf16 v[90:93], v[174:177], v[222:225], v[90:93]
	v_mfma_f32_16x16x32_bf16 v[82:85], v[182:185], v[222:225], v[82:85]
	v_mfma_f32_16x16x32_bf16 v[74:77], v[174:177], v[230:233], v[74:77]
	v_mfma_f32_16x16x32_bf16 v[66:69], v[182:185], v[230:233], v[66:69]
	s_setprio 0
	s_barrier
; #define PG8_STAGE(bufoff, gbase, voff) do { _Pragma("unroll") for (int _i = 0; _i < 2; ++_i) \
;         __builtin_amdgcn_global_load_lds((const unsigned*)((const char*)(gbase) + (voff)[_i]), (LAS unsigned*)(lds + (bufoff) + ldsw + _i * 8192), 16, 0, 0); } while (0)
; #define PG8_LDA(dst, b, h) do { _Pragma("unroll") for (int m = 0; m < 4; ++m) _Pragma("unroll") for (int k = 0; k < 2; ++k) dst[m][k] = *(const LAS bf16x8*)(lds + PG8_SA(b, h) + aoff + m * 2048 + k * 1024); } while (0)
; #define PG8_MMA(ai, bj, At, Bt) do { __builtin_amdgcn_s_setprio(1); _Pragma("unroll") for (int m = 0; m < 4; ++m) _Pragma("unroll") for (int n = 0; n < 2; ++n) _Pragma("unroll") for (int k = 0; k < 2; ++k) \
;         acc[ai][bj][m][n] = __builtin_amdgcn_mfma_f32_16x16x32_bf16(Bt[n][k], At[m][k], acc[ai][bj][m][n], 0, 0, 0); __builtin_amdgcn_s_setprio(0); } while (0)
; #define PG8_WAIT_V(n) asm volatile("s_waitcnt vmcnt(" #n ")" ::: "memory")
; #define PG8_WAIT_L(n) asm volatile("s_waitcnt lgkmcnt(" #n ")" ::: "memory")
; #define PG8_BAR __builtin_amdgcn_s_barrier()
; #define PG8_SCHED __builtin_amdgcn_sched_barrier(0)
; template <class Epi, bool ALIGN_EPI = PG8_ALIGN, bool SP2 = PG8_SP2>
; __device__ __forceinline__ void gemm_phase(LAS unsigned char* lds, const Gemm g, const StaticOrder& S, const Epi& E) {
;     ...
;             PG8_LDA(At, 1, 1); PG8_STAGE(PG8_SB(1, 0), b3, voffB); PG8_STAGE(PG8_SB(1, 1), b3 + hstepB, voffB); PG8_STAGE(PG8_SA(1, 0), a3, voffA);
;             PG8_WAIT_V(8); PG8_WAIT_L(0); PG8_BAR; PG8_MMA(1, 0, At, B0); PG8_MMA(1, 1, At, B1); PG8_BAR; PG8_SCHED;
;     ...
;         if constexpr (ALIGN_EPI) { if (wr == 0) PG8_BAR; }
	s_add_i32 s24, s48, s33
	v_lshl_add_u64 v[160:161], v[160:161], 0, s[50:51]
	s_mov_b32 m0, s24
	ds_read_b128 v[186:189], v142 offset:49152
	ds_read_b128 v[206:209], v142 offset:50176
	ds_read_b128 v[210:213], v142 offset:51200
	ds_read_b128 v[214:217], v142 offset:52224
	ds_read_b128 v[218:221], v142 offset:53248
	ds_read_b128 v[222:225], v142 offset:54272
	ds_read_b128 v[226:229], v142 offset:55296
	ds_read_b128 v[230:233], v142 offset:56320
	global_load_lds_dwordx4 v[160:161], off
	s_add_i32 m0, s24, 0x2000
	s_add_u32 s22, s22, 0x40080
	v_lshl_add_u64 v[160:161], v[164:165], 0, s[50:51]
	s_addc_u32 s23, s23, 0
	s_add_i32 s24, s49, s33
	global_load_lds_dwordx4 v[160:161], off
	v_lshl_add_u64 v[160:161], s[22:23], 0, v[130:131]
	s_mov_b32 m0, s24
	s_nop 0
	global_load_lds_dwordx4 v[160:161], off
	v_lshl_add_u64 v[160:161], s[22:23], 0, v[132:133]
	s_add_i32 m0, s24, 0x2000
	s_nop 0
	global_load_lds_dwordx4 v[160:161], off
	v_lshl_add_u64 v[160:161], v[166:167], 0, s[50:51]
	s_mov_b32 m0, s40
	s_nop 0
	global_load_lds_dwordx4 v[160:161], off
	v_lshl_add_u64 v[160:161], v[194:195], 0, s[50:51]
	s_mov_b32 m0, s41
	s_nop 0
	global_load_lds_dwordx4 v[160:161], off
	s_waitcnt vmcnt(8)
	s_waitcnt lgkmcnt(0)
	s_barrier
	s_setprio 1
	v_mfma_f32_16x16x32_bf16 v[62:65], v[144:147], v[186:189], v[62:65]
	v_mfma_f32_16x16x32_bf16 v[54:57], v[152:155], v[186:189], v[54:57]
	v_mfma_f32_16x16x32_bf16 v[46:49], v[144:147], v[210:213], v[46:49]
	v_mfma_f32_16x16x32_bf16 v[38:41], v[152:155], v[210:213], v[38:41]
	v_mfma_f32_16x16x32_bf16 v[30:33], v[144:147], v[218:221], v[30:33]
	v_mfma_f32_16x16x32_bf16 v[22:25], v[152:155], v[218:221], v[22:25]
	v_mfma_f32_16x16x32_bf16 v[14:17], v[144:147], v[226:229], v[14:17]
	v_mfma_f32_16x16x32_bf16 v[6:9], v[152:155], v[226:229], v[6:9]
	v_mfma_f32_16x16x32_bf16 v[62:65], v[148:151], v[206:209], v[62:65]
	v_mfma_f32_16x16x32_bf16 v[54:57], v[156:159], v[206:209], v[54:57]
	v_mfma_f32_16x16x32_bf16 v[46:49], v[148:151], v[214:217], v[46:49]
	v_mfma_f32_16x16x32_bf16 v[38:41], v[156:159], v[214:217], v[38:41]
	v_mfma_f32_16x16x32_bf16 v[30:33], v[148:151], v[222:225], v[30:33]
	v_mfma_f32_16x16x32_bf16 v[22:25], v[156:159], v[222:225], v[22:25]
	v_mfma_f32_16x16x32_bf16 v[14:17], v[148:151], v[230:233], v[14:17]
	v_mfma_f32_16x16x32_bf16 v[6:9], v[156:159], v[230:233], v[6:9]
	s_setprio 0
	s_setprio 1
	v_mfma_f32_16x16x32_bf16 v[58:61], v[170:173], v[186:189], v[58:61]
	v_mfma_f32_16x16x32_bf16 v[50:53], v[178:181], v[186:189], v[50:53]
	v_mfma_f32_16x16x32_bf16 v[42:45], v[170:173], v[210:213], v[42:45]
	v_mfma_f32_16x16x32_bf16 v[34:37], v[178:181], v[210:213], v[34:37]
	v_mfma_f32_16x16x32_bf16 v[26:29], v[170:173], v[218:221], v[26:29]
	v_mfma_f32_16x16x32_bf16 v[18:21], v[178:181], v[218:221], v[18:21]
	v_mfma_f32_16x16x32_bf16 v[10:13], v[170:173], v[226:229], v[10:13]
	v_mfma_f32_16x16x32_bf16 v[2:5], v[178:181], v[226:229], v[2:5]
	v_mfma_f32_16x16x32_bf16 v[58:61], v[174:177], v[206:209], v[58:61]
	v_mfma_f32_16x16x32_bf16 v[50:53], v[182:185], v[206:209], v[50:53]
	v_mfma_f32_16x16x32_bf16 v[42:45], v[174:177], v[214:217], v[42:45]
	v_mfma_f32_16x16x32_bf16 v[34:37], v[182:185], v[214:217], v[34:37]
	v_mfma_f32_16x16x32_bf16 v[26:29], v[174:177], v[222:225], v[26:29]
	v_mfma_f32_16x16x32_bf16 v[18:21], v[182:185], v[222:225], v[18:21]
	v_mfma_f32_16x16x32_bf16 v[10:13], v[174:177], v[230:233], v[10:13]
	v_mfma_f32_16x16x32_bf16 v[2:5], v[182:185], v[230:233], v[2:5]
	s_setprio 0
	s_barrier
	s_add_i32 s47, s47, 2
	s_add_u32 s20, s20, 0x100
	s_addc_u32 s21, s21, 0
	s_add_u32 s45, s45, 0x100
	s_addc_u32 s46, s46, 0
	s_cmp_gt_u32 s47, 13
	s_cbranch_scc0 .LBB0_611
	s_and_b64 vcc, exec, s[8:9]
	s_cbranch_vccz .LBB0_614
	s_barrier

; #define PG8_STAGE(bufoff, gbase, voff) do { _Pragma("unroll") for (int _i = 0; _i < 2; ++_i) \
;         __builtin_amdgcn_global_load_lds((const unsigned*)((const char*)(gbase) + (voff)[_i]), (LAS unsigned*)(lds + (bufoff) + ldsw + _i * 8192), 16, 0, 0); } while (0)
; #define PG8_LDA(dst, b, h) do { _Pragma("unroll") for (int m = 0; m < 4; ++m) _Pragma("unroll") for (int k = 0; k < 2; ++k) dst[m][k] = *(const LAS bf16x8*)(lds + PG8_SA(b, h) + aoff + m * 2048 + k * 1024); } while (0)
; #define PG8_LDB(dst, b, h) do { _Pragma("unroll") for (int n = 0; n < 2; ++n) _Pragma("unroll") for (int k = 0; k < 2; ++k) dst[n][k] = *(const LAS bf16x8*)(lds + PG8_SB(b, h) + boff + n * 2048 + k * 1024); } while (0)
; #define PG8_MMA(ai, bj, At, Bt) do { __builtin_amdgcn_s_setprio(1); _Pragma("unroll") for (int m = 0; m < 4; ++m) _Pragma("unroll") for (int n = 0; n < 2; ++n) _Pragma("unroll") for (int k = 0; k < 2; ++k) \
;         acc[ai][bj][m][n] = __builtin_amdgcn_mfma_f32_16x16x32_bf16(Bt[n][k], At[m][k], acc[ai][bj][m][n], 0, 0, 0); __builtin_amdgcn_s_setprio(0); } while (0)
; #define PG8_WAIT_V(n) asm volatile("s_waitcnt vmcnt(" #n ")" ::: "memory")
; #define PG8_WAIT_L(n) asm volatile("s_waitcnt lgkmcnt(" #n ")" ::: "memory")
; #define PG8_BAR __builtin_amdgcn_s_barrier()
; #define PG8_SCHED __builtin_amdgcn_sched_barrier(0)
; template <class Epi, bool ALIGN_EPI = PG8_ALIGN, bool SP2 = PG8_SP2>
; __device__ __forceinline__ void gemm_phase(LAS unsigned char* lds, const Gemm g, const StaticOrder& S, const Epi& E) {
;     ...
;             const bool last = (t == nt - 2);
;             const char* a1 = cA + (size_t)(t + 1) * kstepA;
;             const char* a2 = last ? nA : cA + (size_t)(t + 2) * kstepA; const char* b2 = last ? nB : cB + (size_t)(t + 2) * kstepB;
;             const char* a3 = a2 + kstepA; const char* b3 = b2 + kstepB;
;             if constexpr (SP2) {
;             PG8_LDB(B0, 0, 0); PG8_LDB(B1, 0, 1); PG8_SCHED; PG8_LDA(At, 0, 0); PG8_STAGE(PG8_SA(1, 1), a1 + hstepA, voffA);
;             PG8_WAIT_V(8); PG8_WAIT_L(0); PG8_BAR; PG8_MMA(0, 0, At, B0); PG8_MMA(0, 1, At, B1); PG8_BAR; PG8_SCHED;
;             PG8_LDA(At, 0, 1); PG8_STAGE(PG8_SB(0, 0), b2, voffB); PG8_STAGE(PG8_SB(0, 1), b2 + hstepB, voffB); PG8_STAGE(PG8_SA(0, 0), a2, voffA);
;             PG8_WAIT_V(8); PG8_WAIT_L(0); PG8_BAR; PG8_MMA(1, 0, At, B0); PG8_MMA(1, 1, At, B1); PG8_BAR; PG8_SCHED;
.Lfirst_iter_u611:
	s_add_u32 s22, s20, 0xfffc0080
	s_addc_u32 s23, s21, -1
	s_add_i32 s48, 0, 0x10000
	s_cmp_eq_u32 s47, 12
	s_cselect_b32 s25, s13, s23
	s_cselect_b32 s24, s43, s22
	v_add_u32_e32 v0, s48, v141
	s_cselect_b32 s23, s11, s46
	s_cselect_b32 s22, s44, s45
	s_add_i32 s52, 0, 0x14000
	ds_read_b128 v[144:147], v0
	ds_read_b128 v[148:151], v0 offset:1024
	ds_read_b128 v[152:155], v0 offset:2048
	ds_read_b128 v[156:159], v0 offset:3072
	v_add_u32_e32 v0, s52, v141
	ds_read_b128 v[170:173], v0
	ds_read_b128 v[174:177], v0 offset:1024
	ds_read_b128 v[178:181], v0 offset:2048
	ds_read_b128 v[182:185], v0 offset:3072
	v_lshl_add_u64 v[160:161], s[20:21], 0, v[134:135]
	s_add_i32 m0, s34, 0xc000
	ds_read_b128 v[186:189], v142
	ds_read_b128 v[206:209], v142 offset:1024
	ds_read_b128 v[210:213], v142 offset:2048
	ds_read_b128 v[214:217], v142 offset:3072
	ds_read_b128 v[218:221], v142 offset:4096
	ds_read_b128 v[222:225], v142 offset:5120
	ds_read_b128 v[226:229], v142 offset:6144
	ds_read_b128 v[230:233], v142 offset:7168
	global_load_lds_dwordx4 v[160:161], off
	v_lshl_add_u64 v[160:161], s[20:21], 0, v[136:137]
	s_add_i32 m0, s34, 0xe000
	s_nop 0
	global_load_lds_dwordx4 v[160:161], off
	s_waitcnt vmcnt(8)
	s_waitcnt lgkmcnt(0)
	s_barrier
	s_setprio 1
	v_mfma_f32_16x16x32_bf16 v[126:129], v[144:147], v[186:189], 0
	v_mfma_f32_16x16x32_bf16 v[118:121], v[152:155], v[186:189], 0
	v_mfma_f32_16x16x32_bf16 v[110:113], v[144:147], v[210:213], 0
	v_mfma_f32_16x16x32_bf16 v[102:105], v[152:155], v[210:213], 0
	v_mfma_f32_16x16x32_bf16 v[94:97], v[144:147], v[218:221], 0
	v_mfma_f32_16x16x32_bf16 v[86:89], v[152:155], v[218:221], 0
	v_mfma_f32_16x16x32_bf16 v[78:81], v[144:147], v[226:229], 0
	v_mfma_f32_16x16x32_bf16 v[70:73], v[152:155], v[226:229], 0
	v_mfma_f32_16x16x32_bf16 v[126:129], v[148:151], v[206:209], v[126:129]
	v_mfma_f32_16x16x32_bf16 v[118:121], v[156:159], v[206:209], v[118:121]
	v_mfma_f32_16x16x32_bf16 v[110:113], v[148:151], v[214:217], v[110:113]
	v_mfma_f32_16x16x32_bf16 v[102:105], v[156:159], v[214:217], v[102:105]
	v_mfma_f32_16x16x32_bf16 v[94:97], v[148:151], v[222:225], v[94:97]
	v_mfma_f32_16x16x32_bf16 v[86:89], v[156:159], v[222:225], v[86:89]
	v_mfma_f32_16x16x32_bf16 v[78:81], v[148:151], v[230:233], v[78:81]
	v_mfma_f32_16x16x32_bf16 v[70:73], v[156:159], v[230:233], v[70:73]
	s_setprio 0
	s_setprio 1
	v_mfma_f32_16x16x32_bf16 v[122:125], v[170:173], v[186:189], 0
	v_mfma_f32_16x16x32_bf16 v[114:117], v[178:181], v[186:189], 0
	v_mfma_f32_16x16x32_bf16 v[106:109], v[170:173], v[210:213], 0
	v_mfma_f32_16x16x32_bf16 v[98:101], v[178:181], v[210:213], 0
	v_mfma_f32_16x16x32_bf16 v[90:93], v[170:173], v[218:221], 0
	v_mfma_f32_16x16x32_bf16 v[82:85], v[178:181], v[218:221], 0
	v_mfma_f32_16x16x32_bf16 v[74:77], v[170:173], v[226:229], 0
	v_mfma_f32_16x16x32_bf16 v[66:69], v[178:181], v[226:229], 0
	v_mfma_f32_16x16x32_bf16 v[122:125], v[174:177], v[206:209], v[122:125]
	v_mfma_f32_16x16x32_bf16 v[114:117], v[182:185], v[206:209], v[114:117]
	v_mfma_f32_16x16x32_bf16 v[106:109], v[174:177], v[214:217], v[106:109]
	v_mfma_f32_16x16x32_bf16 v[98:101], v[182:185], v[214:217], v[98:101]
	v_mfma_f32_16x16x32_bf16 v[90:93], v[174:177], v[222:225], v[90:93]
	v_mfma_f32_16x16x32_bf16 v[82:85], v[182:185], v[222:225], v[82:85]
	v_mfma_f32_16x16x32_bf16 v[74:77], v[174:177], v[230:233], v[74:77]
	v_mfma_f32_16x16x32_bf16 v[66:69], v[182:185], v[230:233], v[66:69]
	s_setprio 0
	s_barrier
	s_add_i32 s48, s48, s33
	v_lshl_add_u64 v[160:161], s[22:23], 0, v[130:131]
	s_mov_b32 m0, s48
	ds_read_b128 v[186:189], v142 offset:16384
	ds_read_b128 v[206:209], v142 offset:17408
	ds_read_b128 v[210:213], v142 offset:18432
	ds_read_b128 v[214:217], v142 offset:19456
	ds_read_b128 v[218:221], v142 offset:20480
	ds_read_b128 v[222:225], v142 offset:21504
	ds_read_b128 v[226:229], v142 offset:22528
	ds_read_b128 v[230:233], v142 offset:23552
	global_load_lds_dwordx4 v[160:161], off
	s_add_i32 m0, s48, 0x2000
	s_add_u32 s48, s22, 0x40000
	v_lshl_add_u64 v[164:165], s[22:23], 0, v[132:133]
	s_addc_u32 s49, s23, 0
	s_add_i32 s52, s52, s33
	global_load_lds_dwordx4 v[164:165], off
	v_lshl_add_u64 v[166:167], s[48:49], 0, v[130:131]
	s_mov_b32 m0, s52
	v_lshl_add_u64 v[194:195], s[24:25], 0, v[132:133]
	global_load_lds_dwordx4 v[166:167], off
	v_lshl_add_u64 v[166:167], s[48:49], 0, v[132:133]
	s_add_i32 m0, s52, 0x2000
	s_nop 0
	global_load_lds_dwordx4 v[166:167], off
	v_lshl_add_u64 v[166:167], s[24:25], 0, v[130:131]
	s_mov_b32 m0, s34
	s_nop 0
	global_load_lds_dwordx4 v[166:167], off
	s_mov_b32 m0, s35
	s_nop 0
	global_load_lds_dwordx4 v[194:195], off
	s_waitcnt vmcnt(8)
	s_waitcnt lgkmcnt(0)
	s_barrier
; #define PG8_STAGE(bufoff, gbase, voff) do { _Pragma("unroll") for (int _i = 0; _i < 2; ++_i) \
;         __builtin_amdgcn_global_load_lds((const unsigned*)((const char*)(gbase) + (voff)[_i]), (LAS unsigned*)(lds + (bufoff) + ldsw + _i * 8192), 16, 0, 0); } while (0)
; #define PG8_LDA(dst, b, h) do { _Pragma("unroll") for (int m = 0; m < 4; ++m) _Pragma("unroll") for (int k = 0; k < 2; ++k) dst[m][k] = *(const LAS bf16x8*)(lds + PG8_SA(b, h) + aoff + m * 2048 + k * 1024); } while (0)
; #define PG8_LDB(dst, b, h) do { _Pragma("unroll") for (int n = 0; n < 2; ++n) _Pragma("unroll") for (int k = 0; k < 2; ++k) dst[n][k] = *(const LAS bf16x8*)(lds + PG8_SB(b, h) + boff + n * 2048 + k * 1024); } while (0)
; #define PG8_MMA(ai, bj, At, Bt) do { __builtin_amdgcn_s_setprio(1); _Pragma("unroll") for (int m = 0; m < 4; ++m) _Pragma("unroll") for (int n = 0; n < 2; ++n) _Pragma("unroll") for (int k = 0; k < 2; ++k) \
;         acc[ai][bj][m][n] = __builtin_amdgcn_mfma_f32_16x16x32_bf16(Bt[n][k], At[m][k], acc[ai][bj][m][n], 0, 0, 0); __builtin_amdgcn_s_setprio(0); } while (0)
; #define PG8_WAIT_V(n) asm volatile("s_waitcnt vmcnt(" #n ")" ::: "memory")
; #define PG8_WAIT_L(n) asm volatile("s_waitcnt lgkmcnt(" #n ")" ::: "memory")
; #define PG8_BAR __builtin_amdgcn_s_barrier()
; #define PG8_SCHED __builtin_amdgcn_sched_barrier(0)
; template <class Epi, bool ALIGN_EPI = PG8_ALIGN, bool SP2 = PG8_SP2>
; __device__ __forceinline__ void gemm_phase(LAS unsigned char* lds, const Gemm g, const StaticOrder& S, const Epi& E) {
;     ...
;             PG8_WAIT_V(8); PG8_WAIT_L(0); PG8_BAR; PG8_MMA(1, 0, At, B0); PG8_MMA(1, 1, At, B1); PG8_BAR; PG8_SCHED;
;             PG8_LDB(B0, 1, 0); PG8_LDB(B1, 1, 1); PG8_SCHED; PG8_LDA(At, 1, 0); PG8_STAGE(PG8_SA(0, 1), a2 + hstepA, voffA);
;             PG8_WAIT_V(8); PG8_WAIT_L(0); PG8_BAR; PG8_MMA(0, 0, At, B0); PG8_MMA(0, 1, At, B1); PG8_BAR; PG8_SCHED;
	s_setprio 1
	v_mfma_f32_16x16x32_bf16 v[62:65], v[144:147], v[186:189], 0
	v_mfma_f32_16x16x32_bf16 v[54:57], v[152:155], v[186:189], 0
	v_mfma_f32_16x16x32_bf16 v[46:49], v[144:147], v[210:213], 0
	v_mfma_f32_16x16x32_bf16 v[38:41], v[152:155], v[210:213], 0
	v_mfma_f32_16x16x32_bf16 v[30:33], v[144:147], v[218:221], 0
	v_mfma_f32_16x16x32_bf16 v[22:25], v[152:155], v[218:221], 0
	v_mfma_f32_16x16x32_bf16 v[14:17], v[144:147], v[226:229], 0
	v_mfma_f32_16x16x32_bf16 v[6:9], v[152:155], v[226:229], 0
	v_mfma_f32_16x16x32_bf16 v[62:65], v[148:151], v[206:209], v[62:65]
	v_mfma_f32_16x16x32_bf16 v[54:57], v[156:159], v[206:209], v[54:57]
	v_mfma_f32_16x16x32_bf16 v[46:49], v[148:151], v[214:217], v[46:49]
	v_mfma_f32_16x16x32_bf16 v[38:41], v[156:159], v[214:217], v[38:41]
	v_mfma_f32_16x16x32_bf16 v[30:33], v[148:151], v[222:225], v[30:33]
	v_mfma_f32_16x16x32_bf16 v[22:25], v[156:159], v[222:225], v[22:25]
	v_mfma_f32_16x16x32_bf16 v[14:17], v[148:151], v[230:233], v[14:17]
	v_mfma_f32_16x16x32_bf16 v[6:9], v[156:159], v[230:233], v[6:9]
	s_setprio 0
	s_setprio 1
	v_mfma_f32_16x16x32_bf16 v[58:61], v[170:173], v[186:189], 0
	v_mfma_f32_16x16x32_bf16 v[50:53], v[178:181], v[186:189], 0
	v_mfma_f32_16x16x32_bf16 v[42:45], v[170:173], v[210:213], 0
	v_mfma_f32_16x16x32_bf16 v[34:37], v[178:181], v[210:213], 0
	v_mfma_f32_16x16x32_bf16 v[26:29], v[170:173], v[218:221], 0
	v_mfma_f32_16x16x32_bf16 v[18:21], v[178:181], v[218:221], 0
	v_mfma_f32_16x16x32_bf16 v[10:13], v[170:173], v[226:229], 0
	v_mfma_f32_16x16x32_bf16 v[2:5], v[178:181], v[226:229], 0
	v_mfma_f32_16x16x32_bf16 v[58:61], v[174:177], v[206:209], v[58:61]
	v_mfma_f32_16x16x32_bf16 v[50:53], v[182:185], v[206:209], v[50:53]
	v_mfma_f32_16x16x32_bf16 v[42:45], v[174:177], v[214:217], v[42:45]
	v_mfma_f32_16x16x32_bf16 v[34:37], v[182:185], v[214:217], v[34:37]
	v_mfma_f32_16x16x32_bf16 v[26:29], v[174:177], v[222:225], v[26:29]
	v_mfma_f32_16x16x32_bf16 v[18:21], v[182:185], v[222:225], v[18:21]
	v_mfma_f32_16x16x32_bf16 v[10:13], v[174:177], v[230:233], v[10:13]
	v_mfma_f32_16x16x32_bf16 v[2:5], v[182:185], v[230:233], v[2:5]
	s_setprio 0
	s_barrier
	s_add_i32 s48, 0, 0x18000
	v_add_u32_e32 v0, s48, v141
	s_add_i32 s49, 0, 0x1c000
	ds_read_b128 v[144:147], v0
	ds_read_b128 v[148:151], v0 offset:1024
	ds_read_b128 v[152:155], v0 offset:2048
	ds_read_b128 v[156:159], v0 offset:3072
	v_add_u32_e32 v0, s49, v141
	ds_read_b128 v[170:173], v0
	ds_read_b128 v[174:177], v0 offset:1024
	ds_read_b128 v[178:181], v0 offset:2048
	ds_read_b128 v[182:185], v0 offset:3072
	s_add_u32 s24, s24, 0x40000
	s_addc_u32 s25, s25, 0
	s_mov_b32 m0, s36
	v_lshl_add_u64 v[196:197], s[24:25], 0, v[130:131]
	ds_read_b128 v[186:189], v142 offset:32768
	ds_read_b128 v[206:209], v142 offset:33792
	ds_read_b128 v[210:213], v142 offset:34816
	ds_read_b128 v[214:217], v142 offset:35840
	ds_read_b128 v[218:221], v142 offset:36864
	ds_read_b128 v[222:225], v142 offset:37888
	ds_read_b128 v[226:229], v142 offset:38912
	ds_read_b128 v[230:233], v142 offset:39936
	global_load_lds_dwordx4 v[196:197], off
	v_lshl_add_u64 v[196:197], s[24:25], 0, v[132:133]
	s_mov_b32 m0, s37
	s_nop 0
	global_load_lds_dwordx4 v[196:197], off
	s_waitcnt vmcnt(8)
	s_waitcnt lgkmcnt(0)
	s_barrier
	s_setprio 1
	v_mfma_f32_16x16x32_bf16 v[126:129], v[144:147], v[186:189], v[126:129]
	v_mfma_f32_16x16x32_bf16 v[118:121], v[152:155], v[186:189], v[118:121]
	v_mfma_f32_16x16x32_bf16 v[110:113], v[144:147], v[210:213], v[110:113]
	v_mfma_f32_16x16x32_bf16 v[102:105], v[152:155], v[210:213], v[102:105]
	v_mfma_f32_16x16x32_bf16 v[94:97], v[144:147], v[218:221], v[94:97]
	v_mfma_f32_16x16x32_bf16 v[86:89], v[152:155], v[218:221], v[86:89]
	v_mfma_f32_16x16x32_bf16 v[78:81], v[144:147], v[226:229], v[78:81]
	v_mfma_f32_16x16x32_bf16 v[70:73], v[152:155], v[226:229], v[70:73]
	v_mfma_f32_16x16x32_bf16 v[126:129], v[148:151], v[206:209], v[126:129]
	v_mfma_f32_16x16x32_bf16 v[118:121], v[156:159], v[206:209], v[118:121]
	v_mfma_f32_16x16x32_bf16 v[110:113], v[148:151], v[214:217], v[110:113]
	v_mfma_f32_16x16x32_bf16 v[102:105], v[156:159], v[214:217], v[102:105]
	v_mfma_f32_16x16x32_bf16 v[94:97], v[148:151], v[222:225], v[94:97]
	v_mfma_f32_16x16x32_bf16 v[86:89], v[156:159], v[222:225], v[86:89]
	v_mfma_f32_16x16x32_bf16 v[78:81], v[148:151], v[230:233], v[78:81]
	v_mfma_f32_16x16x32_bf16 v[70:73], v[156:159], v[230:233], v[70:73]
	s_setprio 0
	s_setprio 1
	v_mfma_f32_16x16x32_bf16 v[122:125], v[170:173], v[186:189], v[122:125]
	v_mfma_f32_16x16x32_bf16 v[114:117], v[178:181], v[186:189], v[114:117]
	v_mfma_f32_16x16x32_bf16 v[106:109], v[170:173], v[210:213], v[106:109]
	v_mfma_f32_16x16x32_bf16 v[98:101], v[178:181], v[210:213], v[98:101]
	v_mfma_f32_16x16x32_bf16 v[90:93], v[170:173], v[218:221], v[90:93]
	v_mfma_f32_16x16x32_bf16 v[82:85], v[178:181], v[218:221], v[82:85]
	v_mfma_f32_16x16x32_bf16 v[74:77], v[170:173], v[226:229], v[74:77]
	v_mfma_f32_16x16x32_bf16 v[66:69], v[178:181], v[226:229], v[66:69]
	v_mfma_f32_16x16x32_bf16 v[122:125], v[174:177], v[206:209], v[122:125]
	v_mfma_f32_16x16x32_bf16 v[114:117], v[182:185], v[206:209], v[114:117]
	v_mfma_f32_16x16x32_bf16 v[106:109], v[174:177], v[214:217], v[106:109]
	v_mfma_f32_16x16x32_bf16 v[98:101], v[182:185], v[214:217], v[98:101]
	v_mfma_f32_16x16x32_bf16 v[90:93], v[174:177], v[222:225], v[90:93]
	v_mfma_f32_16x16x32_bf16 v[82:85], v[182:185], v[222:225], v[82:85]
	v_mfma_f32_16x16x32_bf16 v[74:77], v[174:177], v[230:233], v[74:77]
	v_mfma_f32_16x16x32_bf16 v[66:69], v[182:185], v[230:233], v[66:69]
	s_setprio 0
	s_barrier
; #define PG8_STAGE(bufoff, gbase, voff) do { _Pragma("unroll") for (int _i = 0; _i < 2; ++_i) \
;         __builtin_amdgcn_global_load_lds((const unsigned*)((const char*)(gbase) + (voff)[_i]), (LAS unsigned*)(lds + (bufoff) + ldsw + _i * 8192), 16, 0, 0); } while (0)
; #define PG8_LDA(dst, b, h) do { _Pragma("unroll") for (int m = 0; m < 4; ++m) _Pragma("unroll") for (int k = 0; k < 2; ++k) dst[m][k] = *(const LAS bf16x8*)(lds + PG8_SA(b, h) + aoff + m * 2048 + k * 1024); } while (0)
; #define PG8_MMA(ai, bj, At, Bt) do { __builtin_amdgcn_s_setprio(1); _Pragma("unroll") for (int m = 0; m < 4; ++m) _Pragma("unroll") for (int n = 0; n < 2; ++n) _Pragma("unroll") for (int k = 0; k < 2; ++k) \
;         acc[ai][bj][m][n] = __builtin_amdgcn_mfma_f32_16x16x32_bf16(Bt[n][k], At[m][k], acc[ai][bj][m][n], 0, 0, 0); __builtin_amdgcn_s_setprio(0); } while (0)
; #define PG8_WAIT_V(n) asm volatile("s_waitcnt vmcnt(" #n ")" ::: "memory")
; #define PG8_WAIT_L(n) asm volatile("s_waitcnt lgkmcnt(" #n ")" ::: "memory")
; #define PG8_BAR __builtin_amdgcn_s_barrier()
; #define PG8_SCHED __builtin_amdgcn_sched_barrier(0)
; template <class Epi, bool ALIGN_EPI = PG8_ALIGN, bool SP2 = PG8_SP2>
; __device__ __forceinline__ void gemm_phase(LAS unsigned char* lds, const Gemm g, const StaticOrder& S, const Epi& E) {
;     ...
;             PG8_LDA(At, 1, 1); PG8_STAGE(PG8_SB(1, 0), b3, voffB); PG8_STAGE(PG8_SB(1, 1), b3 + hstepB, voffB); PG8_STAGE(PG8_SA(1, 0), a3, voffA);
;             PG8_WAIT_V(8); PG8_WAIT_L(0); PG8_BAR; PG8_MMA(1, 0, At, B0); PG8_MMA(1, 1, At, B1); PG8_BAR; PG8_SCHED;
	s_add_i32 s24, s48, s33
	v_lshl_add_u64 v[160:161], v[160:161], 0, s[50:51]
	s_mov_b32 m0, s24
	ds_read_b128 v[186:189], v142 offset:49152
	ds_read_b128 v[206:209], v142 offset:50176
	ds_read_b128 v[210:213], v142 offset:51200
	ds_read_b128 v[214:217], v142 offset:52224
	ds_read_b128 v[218:221], v142 offset:53248
	ds_read_b128 v[222:225], v142 offset:54272
	ds_read_b128 v[226:229], v142 offset:55296
	ds_read_b128 v[230:233], v142 offset:56320
	global_load_lds_dwordx4 v[160:161], off
	s_add_i32 m0, s24, 0x2000
	s_add_u32 s22, s22, 0x40080
	v_lshl_add_u64 v[160:161], v[164:165], 0, s[50:51]
	s_addc_u32 s23, s23, 0
	s_add_i32 s24, s49, s33
	global_load_lds_dwordx4 v[160:161], off
	v_lshl_add_u64 v[160:161], s[22:23], 0, v[130:131]
	s_mov_b32 m0, s24
	s_nop 0
	global_load_lds_dwordx4 v[160:161], off
	v_lshl_add_u64 v[160:161], s[22:23], 0, v[132:133]
	s_add_i32 m0, s24, 0x2000
	s_nop 0
	global_load_lds_dwordx4 v[160:161], off
	v_lshl_add_u64 v[160:161], v[166:167], 0, s[50:51]
	s_mov_b32 m0, s40
	s_nop 0
	global_load_lds_dwordx4 v[160:161], off
	v_lshl_add_u64 v[160:161], v[194:195], 0, s[50:51]
	s_mov_b32 m0, s41
	s_nop 0
	global_load_lds_dwordx4 v[160:161], off
	s_waitcnt vmcnt(8)
	s_waitcnt lgkmcnt(0)
	s_barrier
	s_setprio 1
	v_mfma_f32_16x16x32_bf16 v[62:65], v[144:147], v[186:189], v[62:65]
	v_mfma_f32_16x16x32_bf16 v[54:57], v[152:155], v[186:189], v[54:57]
	v_mfma_f32_16x16x32_bf16 v[46:49], v[144:147], v[210:213], v[46:49]
	v_mfma_f32_16x16x32_bf16 v[38:41], v[152:155], v[210:213], v[38:41]
	v_mfma_f32_16x16x32_bf16 v[30:33], v[144:147], v[218:221], v[30:33]
	v_mfma_f32_16x16x32_bf16 v[22:25], v[152:155], v[218:221], v[22:25]
	v_mfma_f32_16x16x32_bf16 v[14:17], v[144:147], v[226:229], v[14:17]
	v_mfma_f32_16x16x32_bf16 v[6:9], v[152:155], v[226:229], v[6:9]
	v_mfma_f32_16x16x32_bf16 v[62:65], v[148:151], v[206:209], v[62:65]
	v_mfma_f32_16x16x32_bf16 v[54:57], v[156:159], v[206:209], v[54:57]
	v_mfma_f32_16x16x32_bf16 v[46:49], v[148:151], v[214:217], v[46:49]
	v_mfma_f32_16x16x32_bf16 v[38:41], v[156:159], v[214:217], v[38:41]
	v_mfma_f32_16x16x32_bf16 v[30:33], v[148:151], v[222:225], v[30:33]
	v_mfma_f32_16x16x32_bf16 v[22:25], v[156:159], v[222:225], v[22:25]
	v_mfma_f32_16x16x32_bf16 v[14:17], v[148:151], v[230:233], v[14:17]
	v_mfma_f32_16x16x32_bf16 v[6:9], v[156:159], v[230:233], v[6:9]
	s_setprio 0
	s_setprio 1
	v_mfma_f32_16x16x32_bf16 v[58:61], v[170:173], v[186:189], v[58:61]
	v_mfma_f32_16x16x32_bf16 v[50:53], v[178:181], v[186:189], v[50:53]
	v_mfma_f32_16x16x32_bf16 v[42:45], v[170:173], v[210:213], v[42:45]
	v_mfma_f32_16x16x32_bf16 v[34:37], v[178:181], v[210:213], v[34:37]
	v_mfma_f32_16x16x32_bf16 v[26:29], v[170:173], v[218:221], v[26:29]
	v_mfma_f32_16x16x32_bf16 v[18:21], v[178:181], v[218:221], v[18:21]
	v_mfma_f32_16x16x32_bf16 v[10:13], v[170:173], v[226:229], v[10:13]
	v_mfma_f32_16x16x32_bf16 v[2:5], v[178:181], v[226:229], v[2:5]
	v_mfma_f32_16x16x32_bf16 v[58:61], v[174:177], v[206:209], v[58:61]
	v_mfma_f32_16x16x32_bf16 v[50:53], v[182:185], v[206:209], v[50:53]
	v_mfma_f32_16x16x32_bf16 v[42:45], v[174:177], v[214:217], v[42:45]
	v_mfma_f32_16x16x32_bf16 v[34:37], v[182:185], v[214:217], v[34:37]
	v_mfma_f32_16x16x32_bf16 v[26:29], v[174:177], v[222:225], v[26:29]
	v_mfma_f32_16x16x32_bf16 v[18:21], v[182:185], v[222:225], v[18:21]
	v_mfma_f32_16x16x32_bf16 v[10:13], v[174:177], v[230:233], v[10:13]
	v_mfma_f32_16x16x32_bf16 v[2:5], v[182:185], v[230:233], v[2:5]
	s_setprio 0
	s_barrier
	s_add_i32 s47, s47, 2
	s_add_u32 s20, s20, 0x100
	s_addc_u32 s21, s21, 0
	s_add_u32 s45, s45, 0x100
	s_addc_u32 s46, s46, 0
	s_cmp_gt_u32 s47, 13
	s_branch .LBB0_611
